# weight conversion tiles: load loops flattened (16/32 loads in flight per thread, counted vmcnt), attention DMA issue interleaved in QK
# speedup vs baseline: 1.1372x; 1.0168x over previous
.LBB0_39:
	s_lshl_b32 s59, s31, 3
	s_lshl_b32 s35, s30, 3
	v_mov_b32_e32 v65, v25
	v_or_b32_e32 v64, s59, v6
	s_add_i32 s64, s59, 16
	v_or_b32_e32 v66, s35, v5
	s_add_i32 s61, s35, 16
	s_add_i32 s66, s59, 32
	v_mov_b32_e32 v69, v1
	v_add_lshl_u32 v68, v64, s2, 10
	v_mov_b32_e32 v71, v27
	v_or_b32_e32 v70, s64, v6
	v_mov_b32_e32 v72, v8
	v_mov_b32_e32 v73, v69
	s_add_i32 s65, s35, 32
	s_add_i32 s35, s35, 48
	s_add_i32 s59, s59, 48
	v_mov_b32_e32 v75, v73
	v_add_lshl_u32 v74, v66, s3, 10
	v_mov_b32_e32 v72, v64
	v_or_b32_e32 v73, s61, v5
	v_or_b32_e32 v64, s66, v6
	v_lshl_add_u64 v[76:77], v[68:69], 2, v[2:3]
	v_mov_b32_e32 v79, v69
	v_add_lshl_u32 v78, v70, s2, 10
	v_mov_b32_e32 v68, v10
	v_mov_b32_e32 v69, v79
	v_mov_b32_e32 v80, v70
	v_or_b32_e32 v81, s65, v5
	v_or_b32_e32 v65, s35, v5
	v_or_b32_e32 v67, s59, v6
	v_lshl_add_u64 v[70:71], v[74:75], 2, v[2:3]
	v_mov_b32_e32 v75, v69
	v_add_lshl_u32 v74, v73, s3, 10
	v_lshl_add_u64 v[68:69], v[78:79], 2, v[2:3]
	v_mov_b32_e32 v83, v79
	v_add_lshl_u32 v82, v64, s2, 10
	v_mov_b32_e32 v78, v12
	v_mov_b32_e32 v79, v83
	v_mov_b32_e32 v84, v18
	v_mov_b32_e32 v85, v83
	v_mov_b32_e32 v87, v79
	v_add_lshl_u32 v86, v81, s3, 10
	v_mov_b32_e32 v79, v85
	v_add_lshl_u32 v78, v65, s3, 10
	v_lshl_add_u64 v[84:85], v[74:75], 2, v[2:3]
	global_load_dword v74, v[76:77], off
	global_load_dword v75, v[70:71], off
	global_load_dword v88, v[68:69], off
	global_load_dword v89, v[84:85], off
	v_lshl_add_u64 v[90:91], v[82:83], 2, v[2:3]
	v_mov_b32_e32 v71, v83
	v_add_lshl_u32 v70, v67, s2, 10
	v_lshl_add_u64 v[82:83], v[86:87], 2, v[2:3]
	v_lshl_add_u64 v[86:87], v[78:79], 2, v[2:3]
	v_lshl_add_u64 v[78:79], v[70:71], 2, v[2:3]
	v_mov_b32_e32 v85, v71
	global_load_dword v84, v[90:91], off
	global_load_dword v70, v[82:83], off
	global_load_dword v71, v[78:79], off
	global_load_dword v92, v[86:87], off
	s_add_i32 s31, s31, 8
	s_add_i32 s30, s30, 8
	s_add_i32 s34, s34, -8
	v_mad_u64_u32 v[94:95], s[64:65], v72, s41, v[4:5]
	s_cmp_lg_u32 s34, 0
	v_mad_u64_u32 v[90:91], s[64:65], v66, s41, v[4:5]
	v_mad_u64_u32 v[78:79], s[64:65], v80, s41, v[4:5]
	v_mad_u64_u32 v[82:83], s[64:65], v73, s41, v[4:5]
	v_mad_u64_u32 v[86:87], s[64:65], v64, s41, v[4:5]
	v_mad_u64_u32 v[76:77], s[64:65], v81, s41, v[4:5]
	v_mad_u64_u32 v[68:69], s[64:65], v67, s41, v[4:5]
	v_mad_u64_u32 v[72:73], s[64:65], v65, s41, v[4:5]
	s_lshl_b32 s59, s31, 3
	s_lshl_b32 s35, s30, 3
	v_mov_b32_e32 v81, v69
	v_or_b32_e32 v80, s59, v6
	s_add_i32 s64, s59, 16
	v_or_b32_e32 v69, s35, v5
	s_add_i32 s61, s35, 16
	s_add_i32 s66, s59, 32
	v_mov_b32_e32 v97, v85
	v_add_lshl_u32 v96, v80, s2, 10
	v_mov_b32_e32 v99, v73
	v_or_b32_e32 v98, s64, v6
	v_mov_b32_e32 v100, v94
	v_mov_b32_e32 v101, v97
	s_add_i32 s65, s35, 32
	s_add_i32 s35, s35, 48
	s_add_i32 s59, s59, 48
	v_mov_b32_e32 v103, v101
	v_add_lshl_u32 v102, v69, s3, 10
	v_mov_b32_e32 v100, v80
	v_or_b32_e32 v101, s61, v5
	v_or_b32_e32 v66, s66, v6
	v_lshl_add_u64 v[80:81], v[96:97], 2, v[2:3]
	v_mov_b32_e32 v105, v97
	v_add_lshl_u32 v104, v98, s2, 10
	v_mov_b32_e32 v96, v90
	v_mov_b32_e32 v97, v105
	v_mov_b32_e32 v106, v98
	v_or_b32_e32 v107, s65, v5
	v_or_b32_e32 v64, s35, v5
	v_or_b32_e32 v65, s59, v6
	v_lshl_add_u64 v[98:99], v[102:103], 2, v[2:3]
	v_mov_b32_e32 v103, v97
	v_add_lshl_u32 v102, v101, s3, 10
	v_lshl_add_u64 v[96:97], v[104:105], 2, v[2:3]
	v_mov_b32_e32 v109, v105
	v_add_lshl_u32 v108, v66, s2, 10
	v_mov_b32_e32 v104, v78
	v_mov_b32_e32 v105, v109
	v_mov_b32_e32 v110, v82
	v_mov_b32_e32 v111, v109
	v_mov_b32_e32 v113, v105
	v_add_lshl_u32 v112, v107, s3, 10
	v_mov_b32_e32 v105, v111
	v_add_lshl_u32 v104, v64, s3, 10
	v_lshl_add_u64 v[110:111], v[102:103], 2, v[2:3]
	global_load_dword v67, v[80:81], off
	global_load_dword v73, v[98:99], off
	global_load_dword v77, v[96:97], off
	global_load_dword v79, v[110:111], off
	v_lshl_add_u64 v[102:103], v[108:109], 2, v[2:3]
	v_mov_b32_e32 v99, v109
	v_add_lshl_u32 v98, v65, s2, 10
	v_lshl_add_u64 v[108:109], v[112:113], 2, v[2:3]
	v_lshl_add_u64 v[112:113], v[104:105], 2, v[2:3]
	v_lshl_add_u64 v[104:105], v[98:99], 2, v[2:3]
	v_mov_b32_e32 v111, v99
	global_load_dword v110, v[102:103], off
	global_load_dword v83, v[108:109], off
	global_load_dword v85, v[104:105], off
	global_load_dword v87, v[112:113], off
	s_add_i32 s31, s31, 8
	s_add_i32 s30, s30, 8
	s_add_i32 s34, s34, -8
	v_mad_u64_u32 v[98:99], s[64:65], v100, s41, v[4:5]
	s_cmp_lg_u32 s34, 0
	v_mad_u64_u32 v[102:103], s[64:65], v69, s41, v[4:5]
	v_mad_u64_u32 v[104:105], s[64:65], v106, s41, v[4:5]
	v_mad_u64_u32 v[108:109], s[64:65], v101, s41, v[4:5]
	v_mad_u64_u32 v[112:113], s[64:65], v66, s41, v[4:5]
	v_mad_u64_u32 v[80:81], s[64:65], v107, s41, v[4:5]
	v_mad_u64_u32 v[96:97], s[64:65], v65, s41, v[4:5]
	v_mad_u64_u32 v[100:101], s[64:65], v64, s41, v[4:5]
	s_waitcnt vmcnt(15)
	ds_write_b32 v94, v74
	s_waitcnt vmcnt(14)
	ds_write_b32 v90, v75
	s_waitcnt vmcnt(13)
	ds_write_b32 v78, v88
	s_waitcnt vmcnt(12)
	ds_write_b32 v82, v89
	s_waitcnt vmcnt(11)
	ds_write_b32 v86, v84
	s_waitcnt vmcnt(10)
	ds_write_b32 v76, v70
	s_waitcnt vmcnt(9)
	ds_write_b32 v68, v71
	s_waitcnt vmcnt(8)
	ds_write_b32 v72, v92
	s_waitcnt vmcnt(7)
	ds_write_b32 v98, v67
	s_waitcnt vmcnt(6)
	ds_write_b32 v102, v73
	s_waitcnt vmcnt(5)
	ds_write_b32 v104, v77
	s_waitcnt vmcnt(4)
	ds_write_b32 v108, v79
	s_waitcnt vmcnt(3)
	ds_write_b32 v112, v110
	s_waitcnt vmcnt(2)
	ds_write_b32 v80, v83
	s_waitcnt vmcnt(1)
	ds_write_b32 v96, v85
	s_waitcnt vmcnt(0)
	ds_write_b32 v100, v87
	v_mov_b32_e32 v0, v110
	v_mov_b32_e32 v1, v111
	v_mov_b32_e32 v8, v98
	v_mov_b32_e32 v9, v99
	v_mov_b32_e32 v10, v102
	v_mov_b32_e32 v11, v103
	v_mov_b32_e32 v12, v104
	v_mov_b32_e32 v13, v105
	v_mov_b32_e32 v17, v69
	v_mov_b32_e32 v18, v108
	v_mov_b32_e32 v19, v109
	v_mov_b32_e32 v20, v112
	v_mov_b32_e32 v21, v113
	v_mov_b32_e32 v22, v80
	v_mov_b32_e32 v23, v81
	v_mov_b32_e32 v24, v96
	v_mov_b32_e32 v25, v97
	v_mov_b32_e32 v26, v100
	v_mov_b32_e32 v27, v101
	v_mov_b32_e32 v28, v66
	v_mov_b32_e32 v29, v64
	v_mov_b32_e32 v30, v65
	v_mov_b32_e32 v31, v67
	v_mov_b32_e32 v32, v73
	v_mov_b32_e32 v33, v77
	v_mov_b32_e32 v34, v79
	v_mov_b32_e32 v35, v83
	v_mov_b32_e32 v36, v85
	v_mov_b32_e32 v37, v87
	v_lshlrev_b32_sdwa v0, v14, v7 dst_sel:DWORD dst_unused:UNUSED_PAD src0_sel:DWORD src1_sel:BYTE_0
	v_and_b32_e32 v0, 0x7e, v0
	v_lshrrev_b32_sdwa v8, v15, v7 dst_sel:DWORD dst_unused:UNUSED_PAD src0_sel:DWORD src1_sel:BYTE_0
	v_or_b32_e32 v6, s2, v0
	v_mul_u32_u24_e32 v0, 0x84, v0
	v_lshlrev_b32_e32 v2, 2, v8
	v_add3_u32 v12, s36, v0, v2
	s_waitcnt lgkmcnt(0)
	s_barrier
	ds_read2_b32 v[2:3], v12 offset0:33 offset1:37
	ds_read2_b32 v[4:5], v12 offset1:4
	v_lshlrev_b32_e32 v0, 1, v6
	v_lshl_add_u64 v[6:7], s[4:5], 0, v[0:1]
	v_or_b32_e32 v0, s20, v8
	v_lshlrev_b64 v[10:11], 11, v[0:1]
	s_waitcnt lgkmcnt(0)
	v_cvt_pk_bf16_f32 v2, v4, v2
	v_lshl_add_u64 v[10:11], v[6:7], 0, v[10:11]
	ds_read2_b32 v[8:9], v12 offset0:8 offset1:12
	global_store_dword v[10:11], v2, off
	v_or_b32_e32 v10, 4, v0
	v_mov_b32_e32 v11, v1
	v_cvt_pk_bf16_f32 v13, v5, v3
	ds_read2_b32 v[4:5], v12 offset0:41 offset1:45
	v_lshlrev_b64 v[2:3], 11, v[10:11]
	v_lshl_add_u64 v[2:3], v[6:7], 0, v[2:3]
	global_store_dword v[2:3], v13, off
	v_or_b32_e32 v2, 8, v0
	v_mov_b32_e32 v3, v1
	v_lshlrev_b64 v[2:3], 11, v[2:3]
	s_waitcnt lgkmcnt(0)
	v_cvt_pk_bf16_f32 v4, v8, v4
	v_lshl_add_u64 v[2:3], v[6:7], 0, v[2:3]
	global_store_dword v[2:3], v4, off
	v_or_b32_e32 v2, 12, v0
	v_mov_b32_e32 v3, v1
	v_cvt_pk_bf16_f32 v10, v9, v5
	ds_read2_b32 v[4:5], v12 offset0:16 offset1:20
	ds_read2_b32 v[8:9], v12 offset0:49 offset1:53
	v_lshlrev_b64 v[2:3], 11, v[2:3]
	v_lshl_add_u64 v[2:3], v[6:7], 0, v[2:3]
	global_store_dword v[2:3], v10, off
	v_or_b32_e32 v2, 16, v0
	v_mov_b32_e32 v3, v1
	v_lshlrev_b64 v[2:3], 11, v[2:3]
	s_waitcnt lgkmcnt(0)
	v_cvt_pk_bf16_f32 v4, v4, v8
	v_lshl_add_u64 v[2:3], v[6:7], 0, v[2:3]
	global_store_dword v[2:3], v4, off
	v_or_b32_e32 v2, 20, v0
	v_mov_b32_e32 v3, v1
	v_cvt_pk_bf16_f32 v10, v5, v9
	ds_read2_b32 v[4:5], v12 offset0:57 offset1:61
	ds_read2_b32 v[8:9], v12 offset0:24 offset1:28
	v_lshlrev_b64 v[2:3], 11, v[2:3]
	v_lshl_add_u64 v[2:3], v[6:7], 0, v[2:3]
	global_store_dword v[2:3], v10, off
	v_or_b32_e32 v2, 24, v0
	v_mov_b32_e32 v3, v1
	v_lshlrev_b64 v[2:3], 11, v[2:3]
	s_waitcnt lgkmcnt(0)
	v_cvt_pk_bf16_f32 v4, v8, v4
	v_lshl_add_u64 v[2:3], v[6:7], 0, v[2:3]
	v_or_b32_e32 v0, 28, v0
	global_store_dword v[2:3], v4, off
	v_lshlrev_b64 v[2:3], 11, v[0:1]
	v_cvt_pk_bf16_f32 v4, v9, v5
	v_lshl_add_u64 v[2:3], v[6:7], 0, v[2:3]
	global_store_dword v[2:3], v4, off
	s_barrier
	s_mov_b64 s[2:3], 0

.LBB0_43:
	s_lshl_b32 s61, s31, 3
	s_lshl_b32 s59, s30, 3
	v_mov_b32_e32 v65, v25
	v_or_b32_e32 v64, s61, v6
	s_add_i32 s65, s61, 16
	v_or_b32_e32 v66, s59, v5
	s_add_i32 s64, s59, 16
	s_add_i32 s67, s61, 32
	v_mov_b32_e32 v69, v1
	v_add_lshl_u32 v68, v64, s3, 10
	v_mov_b32_e32 v71, v27
	v_or_b32_e32 v70, s65, v6
	v_mov_b32_e32 v72, v8
	v_mov_b32_e32 v73, v69
	s_add_i32 s66, s59, 32
	s_add_i32 s59, s59, 48
	s_add_i32 s61, s61, 48
	v_mov_b32_e32 v75, v73
	v_add_lshl_u32 v74, v66, s34, 10
	v_mov_b32_e32 v72, v64
	v_or_b32_e32 v73, s64, v5
	v_or_b32_e32 v64, s67, v6
	v_lshl_add_u64 v[76:77], v[68:69], 2, v[2:3]
	v_mov_b32_e32 v79, v69
	v_add_lshl_u32 v78, v70, s3, 10
	v_mov_b32_e32 v68, v10
	v_mov_b32_e32 v69, v79
	v_mov_b32_e32 v80, v70
	v_or_b32_e32 v81, s66, v5
	v_or_b32_e32 v65, s59, v5
	v_or_b32_e32 v67, s61, v6
	v_lshl_add_u64 v[70:71], v[74:75], 2, v[2:3]
	v_mov_b32_e32 v75, v69
	v_add_lshl_u32 v74, v73, s34, 10
	v_lshl_add_u64 v[68:69], v[78:79], 2, v[2:3]
	v_mov_b32_e32 v83, v79
	v_add_lshl_u32 v82, v64, s3, 10
	v_mov_b32_e32 v78, v12
	v_mov_b32_e32 v79, v83
	v_mov_b32_e32 v84, v18
	v_mov_b32_e32 v85, v83
	v_mov_b32_e32 v87, v79
	v_add_lshl_u32 v86, v81, s34, 10
	v_mov_b32_e32 v79, v85
	v_add_lshl_u32 v78, v65, s34, 10
	v_lshl_add_u64 v[84:85], v[74:75], 2, v[2:3]
	global_load_dword v74, v[76:77], off
	global_load_dword v75, v[70:71], off
	global_load_dword v88, v[68:69], off
	global_load_dword v89, v[84:85], off
	v_lshl_add_u64 v[90:91], v[82:83], 2, v[2:3]
	v_mov_b32_e32 v71, v83
	v_add_lshl_u32 v70, v67, s3, 10
	v_lshl_add_u64 v[82:83], v[86:87], 2, v[2:3]
	v_lshl_add_u64 v[86:87], v[78:79], 2, v[2:3]
	v_lshl_add_u64 v[78:79], v[70:71], 2, v[2:3]
	v_mov_b32_e32 v85, v71
	global_load_dword v84, v[90:91], off
	global_load_dword v70, v[82:83], off
	global_load_dword v71, v[78:79], off
	global_load_dword v92, v[86:87], off
	s_add_i32 s31, s31, 8
	s_add_i32 s30, s30, 8
	s_add_i32 s35, s35, -8
	v_mad_u64_u32 v[94:95], s[64:65], v72, s41, v[4:5]
	s_cmp_lg_u32 s35, 0
	v_mad_u64_u32 v[90:91], s[64:65], v66, s41, v[4:5]
	v_mad_u64_u32 v[78:79], s[64:65], v80, s41, v[4:5]
	v_mad_u64_u32 v[82:83], s[64:65], v73, s41, v[4:5]
	v_mad_u64_u32 v[86:87], s[64:65], v64, s41, v[4:5]
	v_mad_u64_u32 v[76:77], s[64:65], v81, s41, v[4:5]
	v_mad_u64_u32 v[68:69], s[64:65], v67, s41, v[4:5]
	v_mad_u64_u32 v[72:73], s[64:65], v65, s41, v[4:5]
	s_lshl_b32 s61, s31, 3
	s_lshl_b32 s59, s30, 3
	v_mov_b32_e32 v81, v69
	v_or_b32_e32 v80, s61, v6
	s_add_i32 s65, s61, 16
	v_or_b32_e32 v69, s59, v5
	s_add_i32 s64, s59, 16
	s_add_i32 s67, s61, 32
	v_mov_b32_e32 v97, v85
	v_add_lshl_u32 v96, v80, s3, 10
	v_mov_b32_e32 v99, v73
	v_or_b32_e32 v98, s65, v6
	v_mov_b32_e32 v100, v94
	v_mov_b32_e32 v101, v97
	s_add_i32 s66, s59, 32
	s_add_i32 s59, s59, 48
	s_add_i32 s61, s61, 48
	v_mov_b32_e32 v103, v101
	v_add_lshl_u32 v102, v69, s34, 10
	v_mov_b32_e32 v100, v80
	v_or_b32_e32 v101, s64, v5
	v_or_b32_e32 v66, s67, v6
	v_lshl_add_u64 v[80:81], v[96:97], 2, v[2:3]
	v_mov_b32_e32 v105, v97
	v_add_lshl_u32 v104, v98, s3, 10
	v_mov_b32_e32 v96, v90
	v_mov_b32_e32 v97, v105
	v_mov_b32_e32 v106, v98
	v_or_b32_e32 v107, s66, v5
	v_or_b32_e32 v64, s59, v5
	v_or_b32_e32 v65, s61, v6
	v_lshl_add_u64 v[98:99], v[102:103], 2, v[2:3]
	v_mov_b32_e32 v103, v97
	v_add_lshl_u32 v102, v101, s34, 10
	v_lshl_add_u64 v[96:97], v[104:105], 2, v[2:3]
	v_mov_b32_e32 v109, v105
	v_add_lshl_u32 v108, v66, s3, 10
	v_mov_b32_e32 v104, v78
	v_mov_b32_e32 v105, v109
	v_mov_b32_e32 v110, v82
	v_mov_b32_e32 v111, v109
	v_mov_b32_e32 v113, v105
	v_add_lshl_u32 v112, v107, s34, 10
	v_mov_b32_e32 v105, v111
	v_add_lshl_u32 v104, v64, s34, 10
	v_lshl_add_u64 v[110:111], v[102:103], 2, v[2:3]
	global_load_dword v67, v[80:81], off
	global_load_dword v73, v[98:99], off
	global_load_dword v77, v[96:97], off
	global_load_dword v79, v[110:111], off
	v_lshl_add_u64 v[102:103], v[108:109], 2, v[2:3]
	v_mov_b32_e32 v99, v109
	v_add_lshl_u32 v98, v65, s3, 10
	v_lshl_add_u64 v[108:109], v[112:113], 2, v[2:3]
	v_lshl_add_u64 v[112:113], v[104:105], 2, v[2:3]
	v_lshl_add_u64 v[104:105], v[98:99], 2, v[2:3]
	v_mov_b32_e32 v111, v99
	global_load_dword v110, v[102:103], off
	global_load_dword v83, v[108:109], off
	global_load_dword v85, v[104:105], off
	global_load_dword v87, v[112:113], off
	s_add_i32 s31, s31, 8
	s_add_i32 s30, s30, 8
	s_add_i32 s35, s35, -8
	v_mad_u64_u32 v[98:99], s[64:65], v100, s41, v[4:5]
	s_cmp_lg_u32 s35, 0
	v_mad_u64_u32 v[102:103], s[64:65], v69, s41, v[4:5]
	v_mad_u64_u32 v[104:105], s[64:65], v106, s41, v[4:5]
	v_mad_u64_u32 v[108:109], s[64:65], v101, s41, v[4:5]
	v_mad_u64_u32 v[112:113], s[64:65], v66, s41, v[4:5]
	v_mad_u64_u32 v[80:81], s[64:65], v107, s41, v[4:5]
	v_mad_u64_u32 v[96:97], s[64:65], v65, s41, v[4:5]
	v_mad_u64_u32 v[100:101], s[64:65], v64, s41, v[4:5]
	s_waitcnt vmcnt(15)
	ds_write_b32 v94, v74
	s_waitcnt vmcnt(14)
	ds_write_b32 v90, v75
	s_waitcnt vmcnt(13)
	ds_write_b32 v78, v88
	s_waitcnt vmcnt(12)
	ds_write_b32 v82, v89
	s_waitcnt vmcnt(11)
	ds_write_b32 v86, v84
	s_waitcnt vmcnt(10)
	ds_write_b32 v76, v70
	s_waitcnt vmcnt(9)
	ds_write_b32 v68, v71
	s_waitcnt vmcnt(8)
	ds_write_b32 v72, v92
	s_waitcnt vmcnt(7)
	ds_write_b32 v98, v67
	s_waitcnt vmcnt(6)
	ds_write_b32 v102, v73
	s_waitcnt vmcnt(5)
	ds_write_b32 v104, v77
	s_waitcnt vmcnt(4)
	ds_write_b32 v108, v79
	s_waitcnt vmcnt(3)
	ds_write_b32 v112, v110
	s_waitcnt vmcnt(2)
	ds_write_b32 v80, v83
	s_waitcnt vmcnt(1)
	ds_write_b32 v96, v85
	s_waitcnt vmcnt(0)
	ds_write_b32 v100, v87
	v_mov_b32_e32 v0, v110
	v_mov_b32_e32 v1, v111
	v_mov_b32_e32 v8, v98
	v_mov_b32_e32 v9, v99
	v_mov_b32_e32 v10, v102
	v_mov_b32_e32 v11, v103
	v_mov_b32_e32 v12, v104
	v_mov_b32_e32 v13, v105
	v_mov_b32_e32 v17, v69
	v_mov_b32_e32 v18, v108
	v_mov_b32_e32 v19, v109
	v_mov_b32_e32 v20, v112
	v_mov_b32_e32 v21, v113
	v_mov_b32_e32 v22, v80
	v_mov_b32_e32 v23, v81
	v_mov_b32_e32 v24, v96
	v_mov_b32_e32 v25, v97
	v_mov_b32_e32 v26, v100
	v_mov_b32_e32 v27, v101
	v_mov_b32_e32 v28, v66
	v_mov_b32_e32 v29, v64
	v_mov_b32_e32 v30, v65
	v_mov_b32_e32 v31, v67
	v_mov_b32_e32 v32, v73
	v_mov_b32_e32 v33, v77
	v_mov_b32_e32 v34, v79
	v_mov_b32_e32 v35, v83
	v_mov_b32_e32 v36, v85
	v_mov_b32_e32 v37, v87
	v_lshlrev_b32_sdwa v0, v14, v7 dst_sel:DWORD dst_unused:UNUSED_PAD src0_sel:DWORD src1_sel:BYTE_0
	v_and_b32_e32 v0, 0x7e, v0
	v_lshrrev_b32_sdwa v2, v15, v7 dst_sel:DWORD dst_unused:UNUSED_PAD src0_sel:DWORD src1_sel:BYTE_0
	v_or_b32_e32 v12, s2, v2
	v_or_b32_e32 v6, s3, v0
	v_mul_u32_u24_e32 v0, 0x84, v0
	v_lshlrev_b32_e32 v2, 2, v2
	v_add3_u32 v17, s36, v0, v2
	s_waitcnt lgkmcnt(0)
	s_barrier
	ds_read2_b32 v[2:3], v17 offset0:33 offset1:37
	ds_read2_b32 v[4:5], v17 offset1:4
	s_lshl_b64 s[30:31], s[20:21], 20
	s_add_u32 s30, s1, s30
	s_addc_u32 s31, s33, s31
	v_lshlrev_b32_e32 v0, 1, v6
	v_lshl_add_u64 v[6:7], s[30:31], 0, v[0:1]
	ds_read2_b32 v[8:9], v17 offset0:8 offset1:12
	ds_read2_b32 v[10:11], v17 offset0:41 offset1:45
	v_lshlrev_b32_e32 v0, 10, v12
	s_waitcnt lgkmcnt(2)
	v_cvt_pk_bf16_f32 v2, v4, v2
	v_lshl_add_u64 v[6:7], v[6:7], 0, v[0:1]
	global_store_dword v[6:7], v2, off
	ds_read2_b32 v[12:13], v17 offset0:16 offset1:20
	ds_read2_b32 v[18:19], v17 offset0:49 offset1:53
	ds_read2_b32 v[20:21], v17 offset0:24 offset1:28
	ds_read2_b32 v[22:23], v17 offset0:57 offset1:61
	v_add_co_u32_e32 v24, vcc, s43, v6
	s_waitcnt lgkmcnt(4)
	v_cvt_pk_bf16_f32 v0, v8, v10
	v_addc_co_u32_e32 v25, vcc, 0, v7, vcc
	global_store_dword v[24:25], v0, off offset:-4096
	s_waitcnt lgkmcnt(2)
	v_cvt_pk_bf16_f32 v0, v12, v18
	global_store_dword v[24:25], v0, off
	v_add_co_u32_e32 v24, vcc, s52, v6
	s_waitcnt lgkmcnt(0)
	v_cvt_pk_bf16_f32 v0, v20, v22
	v_addc_co_u32_e32 v25, vcc, 0, v7, vcc
	global_store_dword v[24:25], v0, off offset:-4096
	v_cvt_pk_bf16_f32 v0, v5, v3
	v_add_co_u32_e32 v2, vcc, s53, v6
	global_store_dword v[24:25], v0, off
	v_cvt_pk_bf16_f32 v0, v9, v11
	v_addc_co_u32_e32 v3, vcc, 0, v7, vcc
	global_store_dword v[2:3], v0, off
	v_add_co_u32_e32 v2, vcc, 0x6000, v6
	v_cvt_pk_bf16_f32 v0, v13, v19
	s_nop 0
	v_addc_co_u32_e32 v3, vcc, 0, v7, vcc
	global_store_dword v[2:3], v0, off
	v_add_co_u32_e32 v2, vcc, 0x7000, v6
	v_cvt_pk_bf16_f32 v0, v21, v23
	s_nop 0
	v_addc_co_u32_e32 v3, vcc, 0, v7, vcc
	global_store_dword v[2:3], v0, off
	s_barrier

.LBB0_46:
	s_andn2_b64 vcc, exec, s[2:3]
	s_cbranch_vccnz .LBB0_58
	s_bfe_u32 s20, s38, 0x1a0005
	v_mov_b32_e32 v17, v198
	s_lshl_b64 s[2:3], s[20:21], 7
	s_bfe_u32 s20, s39, 0x10007
	v_mov_b32_e32 v5, v1
	v_bfe_u32 v10, v17, 5, 3
	v_lshlrev_b32_e32 v2, 2, v17
	v_lshl_or_b32 v8, s20, 7, v10
	v_mul_u32_u24_e32 v0, 0x84, v10
	v_and_b32_e32 v12, 0x7c, v2
	v_lshlrev_b32_e32 v6, 12, v8
	v_add3_u32 v18, v0, v12, s36
	v_or_b32_e32 v0, 0x18000, v6
	v_lshl_add_u64 v[2:3], s[2:3], 0, v[0:1]
	v_lshlrev_b32_e32 v0, 2, v10
	v_lshlrev_b32_e32 v10, 12, v10
	v_or_b32_e32 v4, 0x10000, v6
	v_or_b32_e32 v6, 0x8000, v6
	v_mov_b32_e32 v7, v1
	v_lshl_or_b32 v10, s20, 19, v10
	v_mov_b32_e32 v11, v1
	v_readlane_b32 s44, v240, 2
	v_lshl_add_u64 v[4:5], s[2:3], 0, v[4:5]
	v_lshl_add_u64 v[6:7], s[2:3], 0, v[6:7]
	v_lshl_add_u64 v[10:11], s[2:3], 0, v[10:11]
	v_or_b32_e32 v2, v2, v12
	v_readlane_b32 s48, v240, 6
	v_readlane_b32 s49, v240, 7
	v_readlane_b32 s50, v240, 8
	v_readlane_b32 s51, v240, 9
	v_or_b32_e32 v4, v4, v12
	v_or_b32_e32 v6, v6, v12
	v_or_b32_e32 v10, v10, v12
	v_lshl_add_u64 v[2:3], s[50:51], 0, v[2:3]
	v_lshl_or_b32 v0, s20, 9, v0
	v_lshl_add_u64 v[4:5], s[50:51], 0, v[4:5]
	v_lshl_add_u64 v[6:7], s[50:51], 0, v[6:7]
	v_lshlrev_b32_e32 v8, 2, v8
	v_mov_b32_e32 v9, v1
	v_lshl_add_u64 v[10:11], s[50:51], 0, v[10:11]
	s_mov_b64 s[30:31], 0
	s_mov_b64 s[34:35], s[48:49]
	v_readlane_b32 s45, v240, 3
	v_readlane_b32 s46, v240, 4
	v_readlane_b32 s47, v240, 5
	s_andn2_b64 vcc, exec, s[6:7]
	s_cbranch_vccnz .LBB0_49
	v_lshl_add_u64 v[64:65], v[10:11], 0, s[30:31]
	v_mov_b32_e32 v67, v65
	global_load_dword v66, v[64:65], off
	v_cndmask_b32_e64 v64, 0, 1, s[6:7]
	v_cmp_ne_u32_e64 s[2:3], 1, v64
	s_andn2_b64 vcc, exec, s[6:7]
	v_lshl_add_u64 v[68:69], s[34:35], 0, v[8:9]
	global_load_dword v65, v[68:69], off
	v_lshl_add_u64 v[70:71], v[6:7], 0, s[30:31]
	global_load_dword v64, v[70:71], off
	s_and_b64 vcc, exec, s[2:3]
	v_lshl_add_u64 v[68:69], s[34:35], 0, v[0:1]
	v_mov_b32_e32 v73, v71
	global_load_dword v72, v[68:69], off offset:32
	v_lshl_add_u64 v[70:71], v[4:5], 0, s[30:31]
	v_mov_b32_e32 v75, v71
	global_load_dword v74, v[70:71], off
	s_and_b64 vcc, exec, s[2:3]
	global_load_dword v67, v[68:69], off offset:64
	v_lshl_add_u64 v[70:71], v[2:3], 0, s[30:31]
	global_load_dword v73, v[70:71], off
	s_and_b64 vcc, exec, s[2:3]
	v_mov_b32_e32 v77, v69
	global_load_dword v76, v[68:69], off offset:96
	s_add_u32 s30, s30, 0x20000
	s_addc_u32 s31, s31, 0
	s_add_u32 s34, s34, 0x80
	s_addc_u32 s35, s35, 0
	s_cmp_lg_u32 s30, 0x80000
	v_add_u32_e32 v68, 0x1080, v18
	v_lshl_add_u64 v[78:79], v[10:11], 0, s[30:31]
	v_mov_b32_e32 v81, v79
	global_load_dword v80, v[78:79], off
	v_cndmask_b32_e64 v69, 0, 1, s[6:7]
	v_cmp_ne_u32_e64 s[2:3], 1, v69
	s_andn2_b64 vcc, exec, s[6:7]
	v_lshl_add_u64 v[78:79], s[34:35], 0, v[8:9]
	global_load_dword v75, v[78:79], off
	v_lshl_add_u64 v[82:83], v[6:7], 0, s[30:31]
	global_load_dword v69, v[82:83], off
	s_and_b64 vcc, exec, s[2:3]
	v_lshl_add_u64 v[78:79], s[34:35], 0, v[0:1]
	v_mov_b32_e32 v85, v83
	global_load_dword v84, v[78:79], off offset:32
	v_lshl_add_u64 v[82:83], v[4:5], 0, s[30:31]
	v_mov_b32_e32 v87, v83
	global_load_dword v86, v[82:83], off
	s_and_b64 vcc, exec, s[2:3]
	global_load_dword v77, v[78:79], off offset:64
	v_lshl_add_u64 v[82:83], v[2:3], 0, s[30:31]
	global_load_dword v70, v[82:83], off
	s_and_b64 vcc, exec, s[2:3]
	v_mov_b32_e32 v89, v79
	global_load_dword v88, v[78:79], off offset:96
	s_add_u32 s30, s30, 0x20000
	s_addc_u32 s31, s31, 0
	s_add_u32 s34, s34, 0x80
	s_addc_u32 s35, s35, 0
	s_cmp_lg_u32 s30, 0x80000
	v_add_u32_e32 v71, 0x1080, v68
	v_lshl_add_u64 v[78:79], v[10:11], 0, s[30:31]
	v_mov_b32_e32 v91, v79
	global_load_dword v90, v[78:79], off
	v_cndmask_b32_e64 v78, 0, 1, s[6:7]
	v_cmp_ne_u32_e64 s[2:3], 1, v78
	s_andn2_b64 vcc, exec, s[6:7]
	v_lshl_add_u64 v[92:93], s[34:35], 0, v[8:9]
	global_load_dword v79, v[92:93], off
	v_lshl_add_u64 v[94:95], v[6:7], 0, s[30:31]
	global_load_dword v78, v[94:95], off
	s_and_b64 vcc, exec, s[2:3]
	v_lshl_add_u64 v[92:93], s[34:35], 0, v[0:1]
	v_mov_b32_e32 v97, v95
	global_load_dword v96, v[92:93], off offset:32
	v_lshl_add_u64 v[94:95], v[4:5], 0, s[30:31]
	v_mov_b32_e32 v99, v95
	global_load_dword v98, v[94:95], off
	s_and_b64 vcc, exec, s[2:3]
	global_load_dword v81, v[92:93], off offset:64
	v_lshl_add_u64 v[94:95], v[2:3], 0, s[30:31]
	global_load_dword v82, v[94:95], off
	s_and_b64 vcc, exec, s[2:3]
	v_mov_b32_e32 v101, v93
	global_load_dword v100, v[92:93], off offset:96
	s_add_u32 s30, s30, 0x20000
	s_addc_u32 s31, s31, 0
	s_add_u32 s34, s34, 0x80
	s_addc_u32 s35, s35, 0
	s_cmp_lg_u32 s30, 0x80000
	v_add_u32_e32 v83, 0x1080, v71
	v_lshl_add_u64 v[92:93], v[10:11], 0, s[30:31]
	v_mov_b32_e32 v103, v93
	global_load_dword v102, v[92:93], off
	v_cndmask_b32_e64 v85, 0, 1, s[6:7]
	v_cmp_ne_u32_e64 s[2:3], 1, v85
	s_andn2_b64 vcc, exec, s[6:7]
	v_lshl_add_u64 v[92:93], s[34:35], 0, v[8:9]
	global_load_dword v87, v[92:93], off
	v_lshl_add_u64 v[104:105], v[6:7], 0, s[30:31]
	global_load_dword v85, v[104:105], off
	s_and_b64 vcc, exec, s[2:3]
	v_lshl_add_u64 v[92:93], s[34:35], 0, v[0:1]
	v_mov_b32_e32 v107, v105
	global_load_dword v106, v[92:93], off offset:32
	v_lshl_add_u64 v[104:105], v[4:5], 0, s[30:31]
	v_mov_b32_e32 v109, v105
	global_load_dword v108, v[104:105], off
	s_and_b64 vcc, exec, s[2:3]
	global_load_dword v89, v[92:93], off offset:64
	v_lshl_add_u64 v[104:105], v[2:3], 0, s[30:31]
	global_load_dword v91, v[104:105], off
	s_and_b64 vcc, exec, s[2:3]
	v_mov_b32_e32 v95, v93
	global_load_dword v94, v[92:93], off offset:96
	s_add_u32 s30, s30, 0x20000
	s_addc_u32 s31, s31, 0
	s_add_u32 s34, s34, 0x80
	s_addc_u32 s35, s35, 0
	s_cmp_lg_u32 s30, 0x80000
	v_add_u32_e32 v92, 0x1080, v83
	s_waitcnt vmcnt(30)
	v_mul_f32_e32 v66, v66, v65
	ds_write_b32 v18, v66
	s_waitcnt vmcnt(28)
	v_mul_f32_e32 v64, v64, v72
	ds_write_b32 v18, v64 offset:1056
	s_waitcnt vmcnt(26)
	v_mul_f32_e32 v74, v74, v67
	ds_write_b32 v18, v74 offset:2112
	s_waitcnt vmcnt(24)
	v_mul_f32_e32 v73, v73, v76
	ds_write_b32 v18, v73 offset:3168
	s_waitcnt vmcnt(22)
	v_mul_f32_e32 v80, v80, v75
	ds_write_b32 v68, v80
	s_waitcnt vmcnt(20)
	v_mul_f32_e32 v69, v69, v84
	ds_write_b32 v68, v69 offset:1056
	s_waitcnt vmcnt(18)
	v_mul_f32_e32 v86, v86, v77
	ds_write_b32 v68, v86 offset:2112
	s_waitcnt vmcnt(16)
	v_mul_f32_e32 v70, v70, v88
	ds_write_b32 v68, v70 offset:3168
	s_waitcnt vmcnt(14)
	v_mul_f32_e32 v90, v90, v79
	ds_write_b32 v71, v90
	s_waitcnt vmcnt(12)
	v_mul_f32_e32 v78, v78, v96
	ds_write_b32 v71, v78 offset:1056
	s_waitcnt vmcnt(10)
	v_mul_f32_e32 v98, v98, v81
	ds_write_b32 v71, v98 offset:2112
	s_waitcnt vmcnt(8)
	v_mul_f32_e32 v82, v82, v100
	ds_write_b32 v71, v82 offset:3168
	s_waitcnt vmcnt(6)
	v_mul_f32_e32 v102, v102, v87
	ds_write_b32 v83, v102
	s_waitcnt vmcnt(4)
	v_mul_f32_e32 v85, v85, v106
	ds_write_b32 v83, v85 offset:1056
	s_waitcnt vmcnt(2)
	v_mul_f32_e32 v108, v108, v89
	ds_write_b32 v83, v108 offset:2112
	s_waitcnt vmcnt(0)
	v_mul_f32_e32 v91, v91, v94
	ds_write_b32 v83, v91 offset:3168
	v_mov_b32_e32 v12, v94
	v_mov_b32_e32 v13, v95
	v_mov_b32_e32 v18, v92
	v_mov_b32_e32 v19, v91
	v_mov_b32_e32 v20, v108
	v_mov_b32_e32 v21, v109
	v_mov_b32_e32 v22, v104
	v_mov_b32_e32 v23, v105
	s_branch .LBB0_57

.LBB0_64:
	s_mul_i32 s2, s59, 6
	s_sub_i32 s2, s30, s2
	s_and_b32 s2, s2, 0xff
	v_readlane_b32 s44, v240, 2
	s_lshl_b32 s34, s2, 7
	s_lshl_b64 s[2:3], s[20:21], 2
	v_readlane_b32 s46, v240, 4
	v_readlane_b32 s47, v240, 5
	s_add_u32 s30, s46, s2
	s_addc_u32 s31, s47, s3
	s_cmpk_gt_u32 s35, 0x59
	s_mov_b64 s[2:3], -1
	s_mul_i32 s20, s59, 48
	v_readlane_b32 s45, v240, 3
	v_readlane_b32 s48, v240, 6
	v_readlane_b32 s49, v240, 7
	v_readlane_b32 s50, v240, 8
	v_readlane_b32 s51, v240, 9
	s_cbranch_scc0 .LBB0_76
	v_mov_b32_e32 v6, v198
	s_mul_hi_u32 s2, s35, 0x2aaaaaab
	v_bfe_u32 v4, v6, 5, 3
	v_lshlrev_b32_e32 v0, 2, v6
	v_and_b32_e32 v0, 0x7c, v0
	v_mul_u32_u24_e32 v5, 0x84, v4
	v_lshl_add_u64 v[2:3], s[30:31], 0, v[0:1]
	v_add3_u32 v7, v5, v0, s36
	v_lshl_or_b32 v0, s35, 7, v4
	s_mulk_i32 s2, 0x300
	v_subrev_u32_e32 v8, s2, v0
	v_add_lshl_u32 v0, v4, s34, 2
	v_lshl_add_u64 v[4:5], s[22:23], 0, v[0:1]
	s_mov_b32 s59, 0
	s_andn2_b64 vcc, exec, s[10:11]
	s_cbranch_vccnz .LBB0_67
	v_mov_b32_e32 v65, v1
	v_add_u32_e32 v64, s59, v8
	v_mad_u64_u32 v[66:67], s[2:3], v64, s55, v[2:3]
	global_load_dword v68, v[66:67], off
	v_mov_b32_e32 v71, v67
	v_cndmask_b32_e64 v70, 0, 1, s[10:11]
	v_cmp_ne_u32_e64 s[2:3], 1, v70
	s_andn2_b64 vcc, exec, s[10:11]
	v_readlane_b32 s44, v240, 2
	v_readlane_b32 s45, v240, 3
	v_readlane_b32 s46, v240, 4
	v_readlane_b32 s47, v240, 5
	v_lshl_add_u64 v[66:67], v[64:65], 2, s[44:45]
	v_mov_b32_e32 v71, v67
	global_load_dword v70, v[66:67], off
	v_readlane_b32 s48, v240, 6
	v_readlane_b32 s49, v240, 7
	v_readlane_b32 s50, v240, 8
	v_readlane_b32 s51, v240, 9
	v_mov_b32_e32 v67, v71
	v_add_u32_e32 v66, 8, v64
	v_mad_u64_u32 v[72:73], s[64:65], v66, s55, v[2:3]
	v_mov_b32_e32 v67, v73
	global_load_dword v66, v[72:73], off
	s_and_b64 vcc, exec, s[2:3]
	global_load_dword v69, v[4:5], off offset:-32
	v_add_u32_e32 v71, 16, v64
	v_mad_u64_u32 v[72:73], s[64:65], v71, s55, v[2:3]
	global_load_dword v74, v[72:73], off
	s_and_b64 vcc, exec, s[2:3]
	v_mov_b32_e32 v77, v67
	global_load_dword v76, v[4:5], off
	v_mov_b32_e32 v79, v65
	v_add_u32_e32 v78, 24, v64
	v_mad_u64_u32 v[64:65], s[64:65], v78, s55, v[2:3]
	v_mov_b32_e32 v81, v79
	global_load_dword v80, v[64:65], off
	s_and_b64 vcc, exec, s[2:3]
	global_load_dword v67, v[4:5], off offset:32
	s_add_i32 s59, s59, 32
	v_add_u32_e32 v71, 0x1080, v7
	s_cmpk_lg_i32 s59, 0x80
	v_lshl_add_u64 v[78:79], v[4:5], 0, s[24:25]
	v_mov_b32_e32 v83, v81
	v_add_u32_e32 v82, s59, v8
	v_mad_u64_u32 v[84:85], s[2:3], v82, s55, v[2:3]
	global_load_dword v64, v[84:85], off
	v_mov_b32_e32 v87, v85
	v_cndmask_b32_e64 v86, 0, 1, s[10:11]
	v_cmp_ne_u32_e64 s[2:3], 1, v86
	s_andn2_b64 vcc, exec, s[10:11]
	v_readlane_b32 s44, v240, 2
	v_readlane_b32 s45, v240, 3
	v_readlane_b32 s46, v240, 4
	v_readlane_b32 s47, v240, 5
	v_lshl_add_u64 v[84:85], v[82:83], 2, s[44:45]
	v_mov_b32_e32 v87, v85
	global_load_dword v86, v[84:85], off
	v_readlane_b32 s48, v240, 6
	v_readlane_b32 s49, v240, 7
	v_readlane_b32 s50, v240, 8
	v_readlane_b32 s51, v240, 9
	v_mov_b32_e32 v85, v87
	v_add_u32_e32 v84, 8, v82
	v_mad_u64_u32 v[88:89], s[64:65], v84, s55, v[2:3]
	v_mov_b32_e32 v85, v89
	global_load_dword v84, v[88:89], off
	s_and_b64 vcc, exec, s[2:3]
	global_load_dword v65, v[78:79], off offset:-32
	v_add_u32_e32 v75, 16, v82
	v_mad_u64_u32 v[88:89], s[64:65], v75, s55, v[2:3]
	global_load_dword v72, v[88:89], off
	s_and_b64 vcc, exec, s[2:3]
	v_mov_b32_e32 v91, v85
	global_load_dword v90, v[78:79], off
	v_mov_b32_e32 v93, v83
	v_add_u32_e32 v92, 24, v82
	v_mad_u64_u32 v[82:83], s[64:65], v92, s55, v[2:3]
	v_mov_b32_e32 v95, v93
	global_load_dword v94, v[82:83], off
	s_and_b64 vcc, exec, s[2:3]
	global_load_dword v73, v[78:79], off offset:32
	s_add_i32 s59, s59, 32
	v_add_u32_e32 v75, 0x1080, v71
	s_cmpk_lg_i32 s59, 0x80
	v_lshl_add_u64 v[92:93], v[78:79], 0, s[24:25]
	v_mov_b32_e32 v79, v95
	v_add_u32_e32 v78, s59, v8
	v_mad_u64_u32 v[96:97], s[2:3], v78, s55, v[2:3]
	global_load_dword v77, v[96:97], off
	v_mov_b32_e32 v83, v97
	v_cndmask_b32_e64 v82, 0, 1, s[10:11]
	v_cmp_ne_u32_e64 s[2:3], 1, v82
	s_andn2_b64 vcc, exec, s[10:11]
	v_readlane_b32 s44, v240, 2
	v_readlane_b32 s45, v240, 3
	v_readlane_b32 s46, v240, 4
	v_readlane_b32 s47, v240, 5
	v_lshl_add_u64 v[96:97], v[78:79], 2, s[44:45]
	v_mov_b32_e32 v83, v97
	global_load_dword v82, v[96:97], off
	v_readlane_b32 s48, v240, 6
	v_readlane_b32 s49, v240, 7
	v_readlane_b32 s50, v240, 8
	v_readlane_b32 s51, v240, 9
	v_mov_b32_e32 v97, v83
	v_add_u32_e32 v96, 8, v78
	v_mad_u64_u32 v[98:99], s[64:65], v96, s55, v[2:3]
	v_mov_b32_e32 v97, v99
	global_load_dword v96, v[98:99], off
	s_and_b64 vcc, exec, s[2:3]
	global_load_dword v81, v[92:93], off offset:-32
	v_add_u32_e32 v83, 16, v78
	v_mad_u64_u32 v[98:99], s[64:65], v83, s55, v[2:3]
	global_load_dword v85, v[98:99], off
	s_and_b64 vcc, exec, s[2:3]
	v_mov_b32_e32 v89, v97
	global_load_dword v88, v[92:93], off
	v_mov_b32_e32 v101, v79
	v_add_u32_e32 v100, 24, v78
	v_mad_u64_u32 v[78:79], s[64:65], v100, s55, v[2:3]
	v_mov_b32_e32 v103, v101
	global_load_dword v102, v[78:79], off
	s_and_b64 vcc, exec, s[2:3]
	global_load_dword v83, v[92:93], off offset:32
	s_add_i32 s59, s59, 32
	v_add_u32_e32 v87, 0x1080, v75
	s_cmpk_lg_i32 s59, 0x80
	v_lshl_add_u64 v[100:101], v[92:93], 0, s[24:25]
	v_mov_b32_e32 v93, v103
	v_add_u32_e32 v92, s59, v8
	v_mad_u64_u32 v[104:105], s[2:3], v92, s55, v[2:3]
	global_load_dword v78, v[104:105], off
	v_mov_b32_e32 v107, v105
	v_cndmask_b32_e64 v106, 0, 1, s[10:11]
	v_cmp_ne_u32_e64 s[2:3], 1, v106
	s_andn2_b64 vcc, exec, s[10:11]
	v_readlane_b32 s44, v240, 2
	v_readlane_b32 s45, v240, 3
	v_readlane_b32 s46, v240, 4
	v_readlane_b32 s47, v240, 5
	v_lshl_add_u64 v[104:105], v[92:93], 2, s[44:45]
	v_mov_b32_e32 v107, v105
	global_load_dword v106, v[104:105], off
	v_readlane_b32 s48, v240, 6
	v_readlane_b32 s49, v240, 7
	v_readlane_b32 s50, v240, 8
	v_readlane_b32 s51, v240, 9
	v_mov_b32_e32 v105, v107
	v_add_u32_e32 v104, 8, v92
	v_mad_u64_u32 v[108:109], s[64:65], v104, s55, v[2:3]
	v_mov_b32_e32 v105, v109
	global_load_dword v104, v[108:109], off
	s_and_b64 vcc, exec, s[2:3]
	global_load_dword v79, v[100:101], off offset:-32
	v_add_u32_e32 v89, 16, v92
	v_mad_u64_u32 v[108:109], s[64:65], v89, s55, v[2:3]
	global_load_dword v91, v[108:109], off
	s_and_b64 vcc, exec, s[2:3]
	v_mov_b32_e32 v99, v105
	global_load_dword v98, v[100:101], off
	v_mov_b32_e32 v111, v93
	v_add_u32_e32 v110, 24, v92
	v_mad_u64_u32 v[92:93], s[64:65], v110, s55, v[2:3]
	v_mov_b32_e32 v113, v111
	global_load_dword v112, v[92:93], off
	s_and_b64 vcc, exec, s[2:3]
	global_load_dword v89, v[100:101], off offset:32
	s_add_i32 s59, s59, 32
	v_add_u32_e32 v95, 0x1080, v87
	s_cmpk_lg_i32 s59, 0x80
	v_lshl_add_u64 v[110:111], v[100:101], 0, s[24:25]
	s_waitcnt vmcnt(30)
	v_mul_f32_e32 v68, v68, v70
	v_mul_f32_e32 v68, 0x3e16c740, v68
	ds_write_b32 v7, v68
	s_waitcnt vmcnt(28)
	v_mul_f32_e32 v66, v66, v69
	v_mul_f32_e32 v66, 0x3e16c740, v66
	ds_write_b32 v7, v66 offset:1056
	s_waitcnt vmcnt(26)
	v_mul_f32_e32 v74, v74, v76
	v_mul_f32_e32 v74, 0x3e16c740, v74
	ds_write_b32 v7, v74 offset:2112
	s_waitcnt vmcnt(24)
	v_mul_f32_e32 v80, v80, v67
	v_mul_f32_e32 v80, 0x3e16c740, v80
	ds_write_b32 v7, v80 offset:3168
	s_waitcnt vmcnt(22)
	v_mul_f32_e32 v64, v64, v86
	v_mul_f32_e32 v64, 0x3e16c740, v64
	ds_write_b32 v71, v64
	s_waitcnt vmcnt(20)
	v_mul_f32_e32 v84, v84, v65
	v_mul_f32_e32 v84, 0x3e16c740, v84
	ds_write_b32 v71, v84 offset:1056
	s_waitcnt vmcnt(18)
	v_mul_f32_e32 v72, v72, v90
	v_mul_f32_e32 v72, 0x3e16c740, v72
	ds_write_b32 v71, v72 offset:2112
	s_waitcnt vmcnt(16)
	v_mul_f32_e32 v94, v94, v73
	v_mul_f32_e32 v94, 0x3e16c740, v94
	ds_write_b32 v71, v94 offset:3168
	s_waitcnt vmcnt(14)
	v_mul_f32_e32 v77, v77, v82
	v_mul_f32_e32 v77, 0x3e16c740, v77
	ds_write_b32 v75, v77
	s_waitcnt vmcnt(12)
	v_mul_f32_e32 v96, v96, v81
	v_mul_f32_e32 v96, 0x3e16c740, v96
	ds_write_b32 v75, v96 offset:1056
	s_waitcnt vmcnt(10)
	v_mul_f32_e32 v85, v85, v88
	v_mul_f32_e32 v85, 0x3e16c740, v85
	ds_write_b32 v75, v85 offset:2112
	s_waitcnt vmcnt(8)
	v_mul_f32_e32 v102, v102, v83
	v_mul_f32_e32 v102, 0x3e16c740, v102
	ds_write_b32 v75, v102 offset:3168
	s_waitcnt vmcnt(6)
	v_mul_f32_e32 v78, v78, v106
	v_mul_f32_e32 v78, 0x3e16c740, v78
	ds_write_b32 v87, v78
	s_waitcnt vmcnt(4)
	v_mul_f32_e32 v104, v104, v79
	v_mul_f32_e32 v104, 0x3e16c740, v104
	ds_write_b32 v87, v104 offset:1056
	s_waitcnt vmcnt(2)
	v_mul_f32_e32 v91, v91, v98
	v_mul_f32_e32 v91, 0x3e16c740, v91
	ds_write_b32 v87, v91 offset:2112
	s_waitcnt vmcnt(0)
	v_mul_f32_e32 v112, v112, v89
	v_mul_f32_e32 v112, 0x3e16c740, v112
	ds_write_b32 v87, v112 offset:3168
	v_mov_b32_e32 v0, v112
	v_mov_b32_e32 v1, v113
	v_mov_b32_e32 v4, v110
	v_mov_b32_e32 v5, v111
	v_mov_b32_e32 v7, v95
	v_mov_b32_e32 v9, v89
	v_mov_b32_e32 v10, v92
	v_mov_b32_e32 v11, v93
	v_mov_b32_e32 v12, v108
	v_mov_b32_e32 v13, v109
	s_branch .LBB0_75

.LBB0_76:
	s_and_b64 vcc, exec, s[2:3]
	s_cbranch_vccz .LBB0_88
	v_mov_b32_e32 v6, v198
	s_mul_hi_u32 s2, s35, 0x2aaaaaab
	v_bfe_u32 v4, v6, 5, 3
	v_lshlrev_b32_e32 v0, 2, v6
	v_and_b32_e32 v0, 0x7c, v0
	v_mul_u32_u24_e32 v5, 0x84, v4
	v_lshl_add_u64 v[2:3], s[30:31], 0, v[0:1]
	v_add3_u32 v7, v5, v0, s36
	v_lshl_or_b32 v0, s35, 7, v4
	s_mulk_i32 s2, 0x300
	v_subrev_u32_e32 v8, s2, v0
	v_add_lshl_u32 v0, v4, s34, 2
	v_lshl_add_u64 v[4:5], s[22:23], 0, v[0:1]
	s_mov_b32 s30, 0
	s_andn2_b64 vcc, exec, s[10:11]
	s_cbranch_vccnz .LBB0_79
	v_mov_b32_e32 v65, v1
	v_add_u32_e32 v64, s30, v8
	v_mad_u64_u32 v[66:67], s[2:3], v64, s55, v[2:3]
	global_load_dword v68, v[66:67], off
	v_mov_b32_e32 v71, v67
	v_cndmask_b32_e64 v70, 0, 1, s[10:11]
	v_cmp_ne_u32_e64 s[2:3], 1, v70
	s_andn2_b64 vcc, exec, s[10:11]
	v_readlane_b32 s44, v240, 2
	v_readlane_b32 s45, v240, 3
	v_readlane_b32 s46, v240, 4
	v_readlane_b32 s47, v240, 5
	v_lshl_add_u64 v[66:67], v[64:65], 2, s[44:45]
	v_mov_b32_e32 v71, v67
	global_load_dword v70, v[66:67], off
	v_readlane_b32 s48, v240, 6
	v_readlane_b32 s49, v240, 7
	v_readlane_b32 s50, v240, 8
	v_readlane_b32 s51, v240, 9
	v_mov_b32_e32 v67, v71
	v_add_u32_e32 v66, 8, v64
	v_mad_u64_u32 v[72:73], s[64:65], v66, s55, v[2:3]
	v_mov_b32_e32 v67, v73
	global_load_dword v66, v[72:73], off
	s_and_b64 vcc, exec, s[2:3]
	global_load_dword v69, v[4:5], off offset:-32
	v_add_u32_e32 v71, 16, v64
	v_mad_u64_u32 v[72:73], s[64:65], v71, s55, v[2:3]
	global_load_dword v74, v[72:73], off
	s_and_b64 vcc, exec, s[2:3]
	v_mov_b32_e32 v77, v67
	global_load_dword v76, v[4:5], off
	v_mov_b32_e32 v79, v65
	v_add_u32_e32 v78, 24, v64
	v_mad_u64_u32 v[64:65], s[64:65], v78, s55, v[2:3]
	v_mov_b32_e32 v81, v79
	global_load_dword v80, v[64:65], off
	s_and_b64 vcc, exec, s[2:3]
	global_load_dword v67, v[4:5], off offset:32
	s_add_i32 s30, s30, 32
	v_add_u32_e32 v71, 0x1080, v7
	s_cmpk_lg_i32 s30, 0x80
	v_lshl_add_u64 v[78:79], v[4:5], 0, s[24:25]
	v_mov_b32_e32 v83, v81
	v_add_u32_e32 v82, s30, v8
	v_mad_u64_u32 v[84:85], s[2:3], v82, s55, v[2:3]
	global_load_dword v64, v[84:85], off
	v_mov_b32_e32 v87, v85
	v_cndmask_b32_e64 v86, 0, 1, s[10:11]
	v_cmp_ne_u32_e64 s[2:3], 1, v86
	s_andn2_b64 vcc, exec, s[10:11]
	v_readlane_b32 s44, v240, 2
	v_readlane_b32 s45, v240, 3
	v_readlane_b32 s46, v240, 4
	v_readlane_b32 s47, v240, 5
	v_lshl_add_u64 v[84:85], v[82:83], 2, s[44:45]
	v_mov_b32_e32 v87, v85
	global_load_dword v86, v[84:85], off
	v_readlane_b32 s48, v240, 6
	v_readlane_b32 s49, v240, 7
	v_readlane_b32 s50, v240, 8
	v_readlane_b32 s51, v240, 9
	v_mov_b32_e32 v85, v87
	v_add_u32_e32 v84, 8, v82
	v_mad_u64_u32 v[88:89], s[64:65], v84, s55, v[2:3]
	v_mov_b32_e32 v85, v89
	global_load_dword v84, v[88:89], off
	s_and_b64 vcc, exec, s[2:3]
	global_load_dword v65, v[78:79], off offset:-32
	v_add_u32_e32 v75, 16, v82
	v_mad_u64_u32 v[88:89], s[64:65], v75, s55, v[2:3]
	global_load_dword v72, v[88:89], off
	s_and_b64 vcc, exec, s[2:3]
	v_mov_b32_e32 v91, v85
	global_load_dword v90, v[78:79], off
	v_mov_b32_e32 v93, v83
	v_add_u32_e32 v92, 24, v82
	v_mad_u64_u32 v[82:83], s[64:65], v92, s55, v[2:3]
	v_mov_b32_e32 v95, v93
	global_load_dword v94, v[82:83], off
	s_and_b64 vcc, exec, s[2:3]
	global_load_dword v73, v[78:79], off offset:32
	s_add_i32 s30, s30, 32
	v_add_u32_e32 v75, 0x1080, v71
	s_cmpk_lg_i32 s30, 0x80
	v_lshl_add_u64 v[92:93], v[78:79], 0, s[24:25]
	v_mov_b32_e32 v79, v95
	v_add_u32_e32 v78, s30, v8
	v_mad_u64_u32 v[96:97], s[2:3], v78, s55, v[2:3]
	global_load_dword v77, v[96:97], off
	v_mov_b32_e32 v83, v97
	v_cndmask_b32_e64 v82, 0, 1, s[10:11]
	v_cmp_ne_u32_e64 s[2:3], 1, v82
	s_andn2_b64 vcc, exec, s[10:11]
	v_readlane_b32 s44, v240, 2
	v_readlane_b32 s45, v240, 3
	v_readlane_b32 s46, v240, 4
	v_readlane_b32 s47, v240, 5
	v_lshl_add_u64 v[96:97], v[78:79], 2, s[44:45]
	v_mov_b32_e32 v83, v97
	global_load_dword v82, v[96:97], off
	v_readlane_b32 s48, v240, 6
	v_readlane_b32 s49, v240, 7
	v_readlane_b32 s50, v240, 8
	v_readlane_b32 s51, v240, 9
	v_mov_b32_e32 v97, v83
	v_add_u32_e32 v96, 8, v78
	v_mad_u64_u32 v[98:99], s[64:65], v96, s55, v[2:3]
	v_mov_b32_e32 v97, v99
	global_load_dword v96, v[98:99], off
	s_and_b64 vcc, exec, s[2:3]
	global_load_dword v81, v[92:93], off offset:-32
	v_add_u32_e32 v83, 16, v78
	v_mad_u64_u32 v[98:99], s[64:65], v83, s55, v[2:3]
	global_load_dword v85, v[98:99], off
	s_and_b64 vcc, exec, s[2:3]
	v_mov_b32_e32 v89, v97
	global_load_dword v88, v[92:93], off
	v_mov_b32_e32 v101, v79
	v_add_u32_e32 v100, 24, v78
	v_mad_u64_u32 v[78:79], s[64:65], v100, s55, v[2:3]
	v_mov_b32_e32 v103, v101
	global_load_dword v102, v[78:79], off
	s_and_b64 vcc, exec, s[2:3]
	global_load_dword v83, v[92:93], off offset:32
	s_add_i32 s30, s30, 32
	v_add_u32_e32 v87, 0x1080, v75
	s_cmpk_lg_i32 s30, 0x80
	v_lshl_add_u64 v[100:101], v[92:93], 0, s[24:25]
	v_mov_b32_e32 v93, v103
	v_add_u32_e32 v92, s30, v8
	v_mad_u64_u32 v[104:105], s[2:3], v92, s55, v[2:3]
	global_load_dword v78, v[104:105], off
	v_mov_b32_e32 v107, v105
	v_cndmask_b32_e64 v106, 0, 1, s[10:11]
	v_cmp_ne_u32_e64 s[2:3], 1, v106
	s_andn2_b64 vcc, exec, s[10:11]
	v_readlane_b32 s44, v240, 2
	v_readlane_b32 s45, v240, 3
	v_readlane_b32 s46, v240, 4
	v_readlane_b32 s47, v240, 5
	v_lshl_add_u64 v[104:105], v[92:93], 2, s[44:45]
	v_mov_b32_e32 v107, v105
	global_load_dword v106, v[104:105], off
	v_readlane_b32 s48, v240, 6
	v_readlane_b32 s49, v240, 7
	v_readlane_b32 s50, v240, 8
	v_readlane_b32 s51, v240, 9
	v_mov_b32_e32 v105, v107
	v_add_u32_e32 v104, 8, v92
	v_mad_u64_u32 v[108:109], s[64:65], v104, s55, v[2:3]
	v_mov_b32_e32 v105, v109
	global_load_dword v104, v[108:109], off
	s_and_b64 vcc, exec, s[2:3]
	global_load_dword v79, v[100:101], off offset:-32
	v_add_u32_e32 v89, 16, v92
	v_mad_u64_u32 v[108:109], s[64:65], v89, s55, v[2:3]
	global_load_dword v91, v[108:109], off
	s_and_b64 vcc, exec, s[2:3]
	v_mov_b32_e32 v99, v105
	global_load_dword v98, v[100:101], off
	v_mov_b32_e32 v111, v93
	v_add_u32_e32 v110, 24, v92
	v_mad_u64_u32 v[92:93], s[64:65], v110, s55, v[2:3]
	v_mov_b32_e32 v113, v111
	global_load_dword v112, v[92:93], off
	s_and_b64 vcc, exec, s[2:3]
	global_load_dword v89, v[100:101], off offset:32
	s_add_i32 s30, s30, 32
	v_add_u32_e32 v95, 0x1080, v87
	s_cmpk_lg_i32 s30, 0x80
	v_lshl_add_u64 v[110:111], v[100:101], 0, s[24:25]
	s_waitcnt vmcnt(30)
	v_mul_f32_e32 v68, v68, v70
	v_mul_f32_e32 v68, 0x3e16c740, v68
	ds_write_b32 v7, v68
	s_waitcnt vmcnt(28)
	v_mul_f32_e32 v66, v66, v69
	v_mul_f32_e32 v66, 0x3e16c740, v66
	ds_write_b32 v7, v66 offset:1056
	s_waitcnt vmcnt(26)
	v_mul_f32_e32 v74, v74, v76
	v_mul_f32_e32 v74, 0x3e16c740, v74
	ds_write_b32 v7, v74 offset:2112
	s_waitcnt vmcnt(24)
	v_mul_f32_e32 v80, v80, v67
	v_mul_f32_e32 v80, 0x3e16c740, v80
	ds_write_b32 v7, v80 offset:3168
	s_waitcnt vmcnt(22)
	v_mul_f32_e32 v64, v64, v86
	v_mul_f32_e32 v64, 0x3e16c740, v64
	ds_write_b32 v71, v64
	s_waitcnt vmcnt(20)
	v_mul_f32_e32 v84, v84, v65
	v_mul_f32_e32 v84, 0x3e16c740, v84
	ds_write_b32 v71, v84 offset:1056
	s_waitcnt vmcnt(18)
	v_mul_f32_e32 v72, v72, v90
	v_mul_f32_e32 v72, 0x3e16c740, v72
	ds_write_b32 v71, v72 offset:2112
	s_waitcnt vmcnt(16)
	v_mul_f32_e32 v94, v94, v73
	v_mul_f32_e32 v94, 0x3e16c740, v94
	ds_write_b32 v71, v94 offset:3168
	s_waitcnt vmcnt(14)
	v_mul_f32_e32 v77, v77, v82
	v_mul_f32_e32 v77, 0x3e16c740, v77
	ds_write_b32 v75, v77
	s_waitcnt vmcnt(12)
	v_mul_f32_e32 v96, v96, v81
	v_mul_f32_e32 v96, 0x3e16c740, v96
	ds_write_b32 v75, v96 offset:1056
	s_waitcnt vmcnt(10)
	v_mul_f32_e32 v85, v85, v88
	v_mul_f32_e32 v85, 0x3e16c740, v85
	ds_write_b32 v75, v85 offset:2112
	s_waitcnt vmcnt(8)
	v_mul_f32_e32 v102, v102, v83
	v_mul_f32_e32 v102, 0x3e16c740, v102
	ds_write_b32 v75, v102 offset:3168
	s_waitcnt vmcnt(6)
	v_mul_f32_e32 v78, v78, v106
	v_mul_f32_e32 v78, 0x3e16c740, v78
	ds_write_b32 v87, v78
	s_waitcnt vmcnt(4)
	v_mul_f32_e32 v104, v104, v79
	v_mul_f32_e32 v104, 0x3e16c740, v104
	ds_write_b32 v87, v104 offset:1056
	s_waitcnt vmcnt(2)
	v_mul_f32_e32 v91, v91, v98
	v_mul_f32_e32 v91, 0x3e16c740, v91
	ds_write_b32 v87, v91 offset:2112
	s_waitcnt vmcnt(0)
	v_mul_f32_e32 v112, v112, v89
	v_mul_f32_e32 v112, 0x3e16c740, v112
	ds_write_b32 v87, v112 offset:3168
	v_mov_b32_e32 v0, v112
	v_mov_b32_e32 v1, v113
	v_mov_b32_e32 v4, v110
	v_mov_b32_e32 v5, v111
	v_mov_b32_e32 v7, v95
	v_mov_b32_e32 v9, v89
	v_mov_b32_e32 v10, v92
	v_mov_b32_e32 v11, v93
	v_mov_b32_e32 v12, v108
	v_mov_b32_e32 v13, v109
	s_branch .LBB0_87

.LBB0_91:
	s_lshl_b32 s59, s31, 3
	s_lshl_b32 s35, s30, 3
	v_mov_b32_e32 v65, v25
	v_or_b32_e32 v64, s59, v6
	s_add_i32 s64, s59, 16
	v_or_b32_e32 v66, s35, v5
	s_add_i32 s61, s35, 16
	s_add_i32 s65, s35, 32
	s_add_i32 s66, s59, 32
	s_add_i32 s35, s35, 48
	v_mov_b32_e32 v69, v1
	v_add_u32_e32 v68, s2, v64
	v_mov_b32_e32 v71, v27
	v_or_b32_e32 v70, s64, v6
	s_add_i32 s59, s59, 48
	v_mov_b32_e32 v73, v9
	v_add_u32_e32 v72, s3, v66
	v_mov_b32_e32 v74, v64
	v_or_b32_e32 v75, s61, v5
	v_mov_b32_e32 v64, v70
	v_or_b32_e32 v65, s65, v5
	v_or_b32_e32 v67, s66, v6
	v_or_b32_e32 v70, s35, v5
	v_mov_b32_e32 v77, v69
	v_mul_lo_u32 v76, v68, s56
	v_mov_b32_e32 v69, v13
	v_add_u32_e32 v68, s2, v64
	v_mov_b32_e32 v78, v72
	v_mov_b32_e32 v79, v77
	v_or_b32_e32 v71, s59, v6
	v_mov_b32_e32 v73, v79
	v_mul_lo_u32 v72, v78, s56
	v_mov_b32_e32 v79, v11
	v_add_u32_e32 v78, s3, v75
	v_add_u32_e32 v80, s2, v67
	v_mov_b32_e32 v83, v19
	v_add_u32_e32 v82, s3, v65
	v_mov_b32_e32 v85, v23
	v_add_u32_e32 v84, s3, v70
	v_lshl_add_u64 v[86:87], v[76:77], 2, v[2:3]
	v_mov_b32_e32 v89, v77
	v_mul_lo_u32 v88, v68, s56
	v_mov_b32_e32 v76, v78
	v_mov_b32_e32 v77, v89
	v_add_u32_e32 v78, s2, v71
	v_lshl_add_u64 v[90:91], v[72:73], 2, v[2:3]
	v_mov_b32_e32 v73, v77
	v_mul_lo_u32 v72, v76, s56
	v_mov_b32_e32 v77, v69
	v_mul_lo_u32 v76, v82, s56
	v_mov_b32_e32 v69, v83
	v_mul_lo_u32 v68, v84, s56
	v_lshl_add_u64 v[82:83], v[88:89], 2, v[2:3]
	v_mov_b32_e32 v85, v89
	v_mul_lo_u32 v84, v80, s56
	v_mov_b32_e32 v88, v76
	v_mov_b32_e32 v89, v85
	v_mov_b32_e32 v76, v68
	v_mov_b32_e32 v77, v85
	v_lshl_add_u64 v[68:69], v[72:73], 2, v[2:3]
	global_load_dword v72, v[86:87], off
	global_load_dword v73, v[90:91], off
	global_load_dword v79, v[82:83], off
	global_load_dword v80, v[68:69], off
	v_lshl_add_u64 v[92:93], v[84:85], 2, v[2:3]
	v_mov_b32_e32 v91, v85
	v_mul_lo_u32 v90, v78, s56
	v_lshl_add_u64 v[84:85], v[88:89], 2, v[2:3]
	v_lshl_add_u64 v[88:89], v[76:77], 2, v[2:3]
	v_lshl_add_u64 v[76:77], v[90:91], 2, v[2:3]
	v_mov_b32_e32 v69, v91
	global_load_dword v68, v[92:93], off
	global_load_dword v81, v[84:85], off
	global_load_dword v78, v[76:77], off
	global_load_dword v90, v[88:89], off
	s_add_i32 s31, s31, 8
	s_add_i32 s30, s30, 8
	s_add_i32 s34, s34, -8
	v_mad_u64_u32 v[94:95], s[64:65], v74, s41, v[4:5]
	s_cmp_lg_u32 s34, 0
	v_mad_u64_u32 v[92:93], s[64:65], v66, s41, v[4:5]
	v_mad_u64_u32 v[76:77], s[64:65], v64, s41, v[4:5]
	v_mad_u64_u32 v[84:85], s[64:65], v75, s41, v[4:5]
	v_mad_u64_u32 v[88:89], s[64:65], v67, s41, v[4:5]
	v_mad_u64_u32 v[86:87], s[64:65], v65, s41, v[4:5]
	v_mad_u64_u32 v[82:83], s[64:65], v71, s41, v[4:5]
	v_mad_u64_u32 v[74:75], s[64:65], v70, s41, v[4:5]
	s_lshl_b32 s59, s31, 3
	s_lshl_b32 s35, s30, 3
	v_mov_b32_e32 v65, v83
	v_or_b32_e32 v64, s59, v6
	s_add_i32 s64, s59, 16
	v_or_b32_e32 v83, s35, v5
	s_add_i32 s61, s35, 16
	s_add_i32 s65, s35, 32
	s_add_i32 s66, s59, 32
	s_add_i32 s35, s35, 48
	v_mov_b32_e32 v97, v69
	v_add_u32_e32 v96, s2, v64
	v_mov_b32_e32 v99, v75
	v_or_b32_e32 v98, s64, v6
	s_add_i32 s59, s59, 48
	v_mov_b32_e32 v101, v95
	v_add_u32_e32 v100, s3, v83
	v_mov_b32_e32 v102, v64
	v_or_b32_e32 v103, s61, v5
	v_mov_b32_e32 v64, v98
	v_or_b32_e32 v65, s65, v5
	v_or_b32_e32 v66, s66, v6
	v_or_b32_e32 v67, s35, v5
	v_mov_b32_e32 v99, v97
	v_mul_lo_u32 v98, v96, s56
	v_mov_b32_e32 v97, v77
	v_add_u32_e32 v96, s2, v64
	v_mov_b32_e32 v104, v100
	v_mov_b32_e32 v105, v99
	v_or_b32_e32 v69, s59, v6
	v_mov_b32_e32 v71, v105
	v_mul_lo_u32 v70, v104, s56
	v_mov_b32_e32 v101, v93
	v_add_u32_e32 v100, s3, v103
	v_add_u32_e32 v75, s2, v66
	v_mov_b32_e32 v105, v85
	v_add_u32_e32 v104, s3, v65
	v_mov_b32_e32 v107, v87
	v_add_u32_e32 v106, s3, v67
	v_lshl_add_u64 v[108:109], v[98:99], 2, v[2:3]
	v_mov_b32_e32 v111, v99
	v_mul_lo_u32 v110, v96, s56
	v_mov_b32_e32 v98, v100
	v_mov_b32_e32 v99, v111
	v_add_u32_e32 v77, s2, v69
	v_lshl_add_u64 v[100:101], v[70:71], 2, v[2:3]
	v_mov_b32_e32 v71, v99
	v_mul_lo_u32 v70, v98, s56
	v_mov_b32_e32 v99, v97
	v_mul_lo_u32 v98, v104, s56
	v_mov_b32_e32 v97, v105
	v_mul_lo_u32 v96, v106, s56
	v_lshl_add_u64 v[104:105], v[110:111], 2, v[2:3]
	v_mov_b32_e32 v107, v111
	v_mul_lo_u32 v106, v75, s56
	v_mov_b32_e32 v110, v98
	v_mov_b32_e32 v111, v107
	v_mov_b32_e32 v98, v96
	v_mov_b32_e32 v99, v107
	v_lshl_add_u64 v[96:97], v[70:71], 2, v[2:3]
	global_load_dword v70, v[108:109], off
	global_load_dword v71, v[100:101], off
	global_load_dword v75, v[104:105], off
	global_load_dword v85, v[96:97], off
	v_lshl_add_u64 v[112:113], v[106:107], 2, v[2:3]
	v_mov_b32_e32 v101, v107
	v_mul_lo_u32 v100, v77, s56
	v_lshl_add_u64 v[106:107], v[110:111], 2, v[2:3]
	v_lshl_add_u64 v[110:111], v[98:99], 2, v[2:3]
	v_lshl_add_u64 v[98:99], v[100:101], 2, v[2:3]
	v_mov_b32_e32 v97, v101
	global_load_dword v96, v[112:113], off
	global_load_dword v87, v[106:107], off
	global_load_dword v77, v[98:99], off
	global_load_dword v89, v[110:111], off
	s_add_i32 s31, s31, 8
	s_add_i32 s30, s30, 8
	s_add_i32 s34, s34, -8
	v_mad_u64_u32 v[100:101], s[64:65], v102, s41, v[4:5]
	s_cmp_lg_u32 s34, 0
	v_mad_u64_u32 v[112:113], s[64:65], v83, s41, v[4:5]
	v_mad_u64_u32 v[98:99], s[64:65], v64, s41, v[4:5]
	v_mad_u64_u32 v[106:107], s[64:65], v103, s41, v[4:5]
	v_mad_u64_u32 v[110:111], s[64:65], v66, s41, v[4:5]
	v_mad_u64_u32 v[108:109], s[64:65], v65, s41, v[4:5]
	v_mad_u64_u32 v[104:105], s[64:65], v69, s41, v[4:5]
	v_mad_u64_u32 v[102:103], s[64:65], v67, s41, v[4:5]
	s_waitcnt vmcnt(15)
	ds_write_b32 v94, v72
	s_waitcnt vmcnt(14)
	ds_write_b32 v92, v73
	s_waitcnt vmcnt(13)
	ds_write_b32 v76, v79
	s_waitcnt vmcnt(12)
	ds_write_b32 v84, v80
	s_waitcnt vmcnt(11)
	ds_write_b32 v88, v68
	s_waitcnt vmcnt(10)
	ds_write_b32 v86, v81
	s_waitcnt vmcnt(9)
	ds_write_b32 v82, v78
	s_waitcnt vmcnt(8)
	ds_write_b32 v74, v90
	s_waitcnt vmcnt(7)
	ds_write_b32 v100, v70
	s_waitcnt vmcnt(6)
	ds_write_b32 v112, v71
	s_waitcnt vmcnt(5)
	ds_write_b32 v98, v75
	s_waitcnt vmcnt(4)
	ds_write_b32 v106, v85
	s_waitcnt vmcnt(3)
	ds_write_b32 v110, v96
	s_waitcnt vmcnt(2)
	ds_write_b32 v108, v87
	s_waitcnt vmcnt(1)
	ds_write_b32 v104, v77
	s_waitcnt vmcnt(0)
	ds_write_b32 v102, v89
	v_mov_b32_e32 v0, v96
	v_mov_b32_e32 v1, v97
	v_mov_b32_e32 v8, v100
	v_mov_b32_e32 v9, v101
	v_mov_b32_e32 v10, v112
	v_mov_b32_e32 v11, v113
	v_mov_b32_e32 v12, v98
	v_mov_b32_e32 v13, v99
	v_mov_b32_e32 v17, v83
	v_mov_b32_e32 v18, v106
	v_mov_b32_e32 v19, v107
	v_mov_b32_e32 v20, v110
	v_mov_b32_e32 v21, v111
	v_mov_b32_e32 v22, v108
	v_mov_b32_e32 v23, v109
	v_mov_b32_e32 v24, v104
	v_mov_b32_e32 v25, v105
	v_mov_b32_e32 v26, v102
	v_mov_b32_e32 v27, v103
	v_mov_b32_e32 v28, v66
	v_mov_b32_e32 v29, v67
	v_mov_b32_e32 v30, v69
	v_mov_b32_e32 v31, v70
	v_mov_b32_e32 v32, v87
	v_mov_b32_e32 v33, v71
	v_mov_b32_e32 v34, v75
	v_mov_b32_e32 v35, v85
	v_mov_b32_e32 v36, v77
	v_mov_b32_e32 v37, v89
	v_lshlrev_b32_sdwa v0, v14, v7 dst_sel:DWORD dst_unused:UNUSED_PAD src0_sel:DWORD src1_sel:BYTE_0
	v_and_b32_e32 v0, 0x7e, v0
	v_lshrrev_b32_sdwa v3, v15, v7 dst_sel:DWORD dst_unused:UNUSED_PAD src0_sel:DWORD src1_sel:BYTE_0
	v_or_b32_e32 v2, s20, v3
	v_or_b32_e32 v8, s2, v0
	v_mul_u32_u24_e32 v0, 0x84, v0
	v_lshlrev_b32_e32 v3, 2, v3
	v_add3_u32 v17, s36, v0, v3
	s_waitcnt lgkmcnt(0)
	s_barrier
	ds_read2_b32 v[4:5], v17 offset0:33 offset1:37
	ds_read2_b32 v[6:7], v17 offset1:4
	v_lshlrev_b32_e32 v0, 1, v8
	v_mov_b32_e32 v3, v1
	ds_read2_b32 v[10:11], v17 offset0:8 offset1:12
	ds_read2_b32 v[12:13], v17 offset0:41 offset1:45
	v_lshl_add_u64 v[8:9], s[14:15], 0, v[0:1]
	v_lshlrev_b64 v[18:19], 11, v[2:3]
	s_waitcnt lgkmcnt(2)
	v_cvt_pk_bf16_f32 v0, v6, v4
	v_lshl_add_u64 v[18:19], v[8:9], 0, v[18:19]
	global_store_dword v[18:19], v0, off
	v_or_b32_e32 v0, 4, v2
	v_lshlrev_b64 v[22:23], 11, v[0:1]
	s_waitcnt lgkmcnt(0)
	v_cvt_pk_bf16_f32 v3, v10, v12
	ds_read2_b32 v[18:19], v17 offset0:16 offset1:20
	ds_read2_b32 v[20:21], v17 offset0:49 offset1:53
	v_lshl_add_u64 v[22:23], v[8:9], 0, v[22:23]
	global_store_dword v[22:23], v3, off
	ds_read2_b32 v[22:23], v17 offset0:24 offset1:28
	ds_read2_b32 v[24:25], v17 offset0:57 offset1:61
	v_or_b32_e32 v0, 8, v2
	v_lshlrev_b64 v[26:27], 11, v[0:1]
	s_waitcnt lgkmcnt(2)
	v_cvt_pk_bf16_f32 v3, v18, v20
	v_lshl_add_u64 v[26:27], v[8:9], 0, v[26:27]
	v_or_b32_e32 v0, 12, v2
	global_store_dword v[26:27], v3, off
	v_lshlrev_b64 v[26:27], 11, v[0:1]
	s_waitcnt lgkmcnt(0)
	v_cvt_pk_bf16_f32 v3, v22, v24
	v_lshl_add_u64 v[26:27], v[8:9], 0, v[26:27]
	v_or_b32_e32 v0, 16, v2
	global_store_dword v[26:27], v3, off
	v_cvt_pk_bf16_f32 v3, v7, v5
	v_lshlrev_b64 v[4:5], 11, v[0:1]
	v_lshl_add_u64 v[4:5], v[8:9], 0, v[4:5]
	v_or_b32_e32 v0, 20, v2
	global_store_dword v[4:5], v3, off
	v_lshlrev_b64 v[4:5], 11, v[0:1]
	v_cvt_pk_bf16_f32 v3, v11, v13
	v_lshl_add_u64 v[4:5], v[8:9], 0, v[4:5]
	v_or_b32_e32 v0, 24, v2
	global_store_dword v[4:5], v3, off
	v_lshlrev_b64 v[4:5], 11, v[0:1]
	v_cvt_pk_bf16_f32 v3, v19, v21
	v_lshl_add_u64 v[4:5], v[8:9], 0, v[4:5]
	v_or_b32_e32 v0, 28, v2
	global_store_dword v[4:5], v3, off
	v_lshlrev_b64 v[2:3], 11, v[0:1]
	v_cvt_pk_bf16_f32 v4, v23, v25
	v_lshl_add_u64 v[2:3], v[8:9], 0, v[2:3]
	global_store_dword v[2:3], v4, off
	s_barrier

.LBB0_97:
	s_lshl_b32 s61, s35, 3
	s_lshl_b32 s59, s34, 3
	v_mov_b32_e32 v65, v25
	v_or_b32_e32 v64, s61, v6
	s_add_i32 s65, s61, 16
	v_or_b32_e32 v66, s59, v5
	s_add_i32 s64, s59, 16
	s_add_i32 s66, s59, 32
	s_add_i32 s67, s61, 32
	s_add_i32 s59, s59, 48
	v_mov_b32_e32 v69, v1
	v_add_u32_e32 v68, s2, v64
	v_mov_b32_e32 v71, v27
	v_or_b32_e32 v70, s65, v6
	s_add_i32 s61, s61, 48
	v_mov_b32_e32 v73, v9
	v_add_u32_e32 v72, s3, v66
	v_mov_b32_e32 v74, v64
	v_or_b32_e32 v75, s64, v5
	v_mov_b32_e32 v64, v70
	v_or_b32_e32 v65, s66, v5
	v_or_b32_e32 v67, s67, v6
	v_or_b32_e32 v70, s59, v5
	v_mov_b32_e32 v77, v69
	v_mul_lo_u32 v76, v68, s56
	v_mov_b32_e32 v69, v13
	v_add_u32_e32 v68, s2, v64
	v_mov_b32_e32 v78, v72
	v_mov_b32_e32 v79, v77
	v_or_b32_e32 v71, s61, v6
	v_mov_b32_e32 v73, v79
	v_mul_lo_u32 v72, v78, s56
	v_mov_b32_e32 v79, v11
	v_add_u32_e32 v78, s3, v75
	v_add_u32_e32 v80, s2, v67
	v_mov_b32_e32 v83, v19
	v_add_u32_e32 v82, s3, v65
	v_mov_b32_e32 v85, v23
	v_add_u32_e32 v84, s3, v70
	v_lshl_add_u64 v[86:87], v[76:77], 2, v[2:3]
	v_mov_b32_e32 v89, v77
	v_mul_lo_u32 v88, v68, s56
	v_mov_b32_e32 v76, v78
	v_mov_b32_e32 v77, v89
	v_add_u32_e32 v78, s2, v71
	v_lshl_add_u64 v[90:91], v[72:73], 2, v[2:3]
	v_mov_b32_e32 v73, v77
	v_mul_lo_u32 v72, v76, s56
	v_mov_b32_e32 v77, v69
	v_mul_lo_u32 v76, v82, s56
	v_mov_b32_e32 v69, v83
	v_mul_lo_u32 v68, v84, s56
	v_lshl_add_u64 v[82:83], v[88:89], 2, v[2:3]
	v_mov_b32_e32 v85, v89
	v_mul_lo_u32 v84, v80, s56
	v_mov_b32_e32 v88, v76
	v_mov_b32_e32 v89, v85
	v_mov_b32_e32 v76, v68
	v_mov_b32_e32 v77, v85
	v_lshl_add_u64 v[68:69], v[72:73], 2, v[2:3]
	global_load_dword v72, v[86:87], off
	global_load_dword v73, v[90:91], off
	global_load_dword v79, v[82:83], off
	global_load_dword v80, v[68:69], off
	v_lshl_add_u64 v[92:93], v[84:85], 2, v[2:3]
	v_mov_b32_e32 v91, v85
	v_mul_lo_u32 v90, v78, s56
	v_lshl_add_u64 v[84:85], v[88:89], 2, v[2:3]
	v_lshl_add_u64 v[88:89], v[76:77], 2, v[2:3]
	v_lshl_add_u64 v[76:77], v[90:91], 2, v[2:3]
	v_mov_b32_e32 v69, v91
	global_load_dword v68, v[92:93], off
	global_load_dword v81, v[84:85], off
	global_load_dword v78, v[76:77], off
	global_load_dword v90, v[88:89], off
	s_add_i32 s35, s35, 8
	s_add_i32 s34, s34, 8
	s_add_i32 s58, s58, -8
	v_mad_u64_u32 v[94:95], s[64:65], v74, s41, v[4:5]
	s_cmp_lg_u32 s58, 0
	v_mad_u64_u32 v[92:93], s[64:65], v66, s41, v[4:5]
	v_mad_u64_u32 v[76:77], s[64:65], v64, s41, v[4:5]
	v_mad_u64_u32 v[84:85], s[64:65], v75, s41, v[4:5]
	v_mad_u64_u32 v[88:89], s[64:65], v67, s41, v[4:5]
	v_mad_u64_u32 v[86:87], s[64:65], v65, s41, v[4:5]
	v_mad_u64_u32 v[82:83], s[64:65], v71, s41, v[4:5]
	v_mad_u64_u32 v[74:75], s[64:65], v70, s41, v[4:5]
	s_lshl_b32 s61, s35, 3
	s_lshl_b32 s59, s34, 3
	v_mov_b32_e32 v65, v83
	v_or_b32_e32 v64, s61, v6
	s_add_i32 s65, s61, 16
	v_or_b32_e32 v83, s59, v5
	s_add_i32 s64, s59, 16
	s_add_i32 s66, s59, 32
	s_add_i32 s67, s61, 32
	s_add_i32 s59, s59, 48
	v_mov_b32_e32 v97, v69
	v_add_u32_e32 v96, s2, v64
	v_mov_b32_e32 v99, v75
	v_or_b32_e32 v98, s65, v6
	s_add_i32 s61, s61, 48
	v_mov_b32_e32 v101, v95
	v_add_u32_e32 v100, s3, v83
	v_mov_b32_e32 v102, v64
	v_or_b32_e32 v103, s64, v5
	v_mov_b32_e32 v64, v98
	v_or_b32_e32 v65, s66, v5
	v_or_b32_e32 v66, s67, v6
	v_or_b32_e32 v67, s59, v5
	v_mov_b32_e32 v99, v97
	v_mul_lo_u32 v98, v96, s56
	v_mov_b32_e32 v97, v77
	v_add_u32_e32 v96, s2, v64
	v_mov_b32_e32 v104, v100
	v_mov_b32_e32 v105, v99
	v_or_b32_e32 v69, s61, v6
	v_mov_b32_e32 v71, v105
	v_mul_lo_u32 v70, v104, s56
	v_mov_b32_e32 v101, v93
	v_add_u32_e32 v100, s3, v103
	v_add_u32_e32 v75, s2, v66
	v_mov_b32_e32 v105, v85
	v_add_u32_e32 v104, s3, v65
	v_mov_b32_e32 v107, v87
	v_add_u32_e32 v106, s3, v67
	v_lshl_add_u64 v[108:109], v[98:99], 2, v[2:3]
	v_mov_b32_e32 v111, v99
	v_mul_lo_u32 v110, v96, s56
	v_mov_b32_e32 v98, v100
	v_mov_b32_e32 v99, v111
	v_add_u32_e32 v77, s2, v69
	v_lshl_add_u64 v[100:101], v[70:71], 2, v[2:3]
	v_mov_b32_e32 v71, v99
	v_mul_lo_u32 v70, v98, s56
	v_mov_b32_e32 v99, v97
	v_mul_lo_u32 v98, v104, s56
	v_mov_b32_e32 v97, v105
	v_mul_lo_u32 v96, v106, s56
	v_lshl_add_u64 v[104:105], v[110:111], 2, v[2:3]
	v_mov_b32_e32 v107, v111
	v_mul_lo_u32 v106, v75, s56
	v_mov_b32_e32 v110, v98
	v_mov_b32_e32 v111, v107
	v_mov_b32_e32 v98, v96
	v_mov_b32_e32 v99, v107
	v_lshl_add_u64 v[96:97], v[70:71], 2, v[2:3]
	global_load_dword v70, v[108:109], off
	global_load_dword v71, v[100:101], off
	global_load_dword v75, v[104:105], off
	global_load_dword v85, v[96:97], off
	v_lshl_add_u64 v[112:113], v[106:107], 2, v[2:3]
	v_mov_b32_e32 v101, v107
	v_mul_lo_u32 v100, v77, s56
	v_lshl_add_u64 v[106:107], v[110:111], 2, v[2:3]
	v_lshl_add_u64 v[110:111], v[98:99], 2, v[2:3]
	v_lshl_add_u64 v[98:99], v[100:101], 2, v[2:3]
	v_mov_b32_e32 v97, v101
	global_load_dword v96, v[112:113], off
	global_load_dword v87, v[106:107], off
	global_load_dword v77, v[98:99], off
	global_load_dword v89, v[110:111], off
	s_add_i32 s35, s35, 8
	s_add_i32 s34, s34, 8
	s_add_i32 s58, s58, -8
	v_mad_u64_u32 v[100:101], s[64:65], v102, s41, v[4:5]
	s_cmp_lg_u32 s58, 0
	v_mad_u64_u32 v[112:113], s[64:65], v83, s41, v[4:5]
	v_mad_u64_u32 v[98:99], s[64:65], v64, s41, v[4:5]
	v_mad_u64_u32 v[106:107], s[64:65], v103, s41, v[4:5]
	v_mad_u64_u32 v[110:111], s[64:65], v66, s41, v[4:5]
	v_mad_u64_u32 v[108:109], s[64:65], v65, s41, v[4:5]
	v_mad_u64_u32 v[104:105], s[64:65], v69, s41, v[4:5]
	v_mad_u64_u32 v[102:103], s[64:65], v67, s41, v[4:5]
	s_waitcnt vmcnt(15)
	ds_write_b32 v94, v72
	s_waitcnt vmcnt(14)
	ds_write_b32 v92, v73
	s_waitcnt vmcnt(13)
	ds_write_b32 v76, v79
	s_waitcnt vmcnt(12)
	ds_write_b32 v84, v80
	s_waitcnt vmcnt(11)
	ds_write_b32 v88, v68
	s_waitcnt vmcnt(10)
	ds_write_b32 v86, v81
	s_waitcnt vmcnt(9)
	ds_write_b32 v82, v78
	s_waitcnt vmcnt(8)
	ds_write_b32 v74, v90
	s_waitcnt vmcnt(7)
	ds_write_b32 v100, v70
	s_waitcnt vmcnt(6)
	ds_write_b32 v112, v71
	s_waitcnt vmcnt(5)
	ds_write_b32 v98, v75
	s_waitcnt vmcnt(4)
	ds_write_b32 v106, v85
	s_waitcnt vmcnt(3)
	ds_write_b32 v110, v96
	s_waitcnt vmcnt(2)
	ds_write_b32 v108, v87
	s_waitcnt vmcnt(1)
	ds_write_b32 v104, v77
	s_waitcnt vmcnt(0)
	ds_write_b32 v102, v89
	v_mov_b32_e32 v0, v96
	v_mov_b32_e32 v1, v97
	v_mov_b32_e32 v8, v100
	v_mov_b32_e32 v9, v101
	v_mov_b32_e32 v10, v112
	v_mov_b32_e32 v11, v113
	v_mov_b32_e32 v12, v98
	v_mov_b32_e32 v13, v99
	v_mov_b32_e32 v17, v83
	v_mov_b32_e32 v18, v106
	v_mov_b32_e32 v19, v107
	v_mov_b32_e32 v20, v110
	v_mov_b32_e32 v21, v111
	v_mov_b32_e32 v22, v108
	v_mov_b32_e32 v23, v109
	v_mov_b32_e32 v24, v104
	v_mov_b32_e32 v25, v105
	v_mov_b32_e32 v26, v102
	v_mov_b32_e32 v27, v103
	v_mov_b32_e32 v28, v66
	v_mov_b32_e32 v29, v67
	v_mov_b32_e32 v30, v69
	v_mov_b32_e32 v31, v70
	v_mov_b32_e32 v32, v87
	v_mov_b32_e32 v33, v71
	v_mov_b32_e32 v34, v75
	v_mov_b32_e32 v35, v85
	v_mov_b32_e32 v36, v77
	v_mov_b32_e32 v37, v89
	v_lshlrev_b32_sdwa v0, v14, v7 dst_sel:DWORD dst_unused:UNUSED_PAD src0_sel:DWORD src1_sel:BYTE_0
	v_and_b32_e32 v0, 0x7e, v0
	v_lshrrev_b32_sdwa v3, v15, v7 dst_sel:DWORD dst_unused:UNUSED_PAD src0_sel:DWORD src1_sel:BYTE_0
	v_or_b32_e32 v2, s31, v3
	v_or_b32_e32 v8, s2, v0
	v_mul_u32_u24_e32 v0, 0x84, v0
	v_lshlrev_b32_e32 v3, 2, v3
	v_add3_u32 v17, s36, v0, v3
	s_waitcnt lgkmcnt(0)
	s_barrier
	ds_read2_b32 v[4:5], v17 offset0:33 offset1:37
	ds_read2_b32 v[6:7], v17 offset1:4
	v_lshlrev_b32_e32 v0, 1, v8
	v_ashrrev_i32_e32 v3, 31, v2
	v_lshl_add_u64 v[8:9], s[16:17], 0, v[0:1]
	ds_read2_b32 v[10:11], v17 offset0:8 offset1:12
	v_lshlrev_b64 v[12:13], 11, v[2:3]
	ds_read2_b32 v[18:19], v17 offset0:41 offset1:45
	s_waitcnt lgkmcnt(2)
	v_cvt_pk_bf16_f32 v0, v6, v4
	v_lshl_add_u64 v[12:13], v[8:9], 0, v[12:13]
	global_store_dword v[12:13], v0, off
	v_or_b32_e32 v12, 4, v2
	v_ashrrev_i32_e32 v13, 31, v12
	v_lshlrev_b64 v[12:13], 11, v[12:13]
	ds_read2_b32 v[20:21], v17 offset0:16 offset1:20
	ds_read2_b32 v[22:23], v17 offset0:49 offset1:53
	s_waitcnt lgkmcnt(2)
	v_cvt_pk_bf16_f32 v0, v10, v18
	v_lshl_add_u64 v[12:13], v[8:9], 0, v[12:13]
	global_store_dword v[12:13], v0, off
	v_or_b32_e32 v12, 8, v2
	v_ashrrev_i32_e32 v13, 31, v12
	v_lshlrev_b64 v[12:13], 11, v[12:13]
	ds_read2_b32 v[24:25], v17 offset0:24 offset1:28
	ds_read2_b32 v[26:27], v17 offset0:57 offset1:61
	s_waitcnt lgkmcnt(2)
	v_cvt_pk_bf16_f32 v0, v20, v22
	v_lshl_add_u64 v[12:13], v[8:9], 0, v[12:13]
	global_store_dword v[12:13], v0, off
	v_or_b32_e32 v12, 12, v2
	v_ashrrev_i32_e32 v13, 31, v12
	v_lshlrev_b64 v[12:13], 11, v[12:13]
	s_waitcnt lgkmcnt(0)
	v_cvt_pk_bf16_f32 v0, v24, v26
	v_lshl_add_u64 v[12:13], v[8:9], 0, v[12:13]
	global_store_dword v[12:13], v0, off
	v_or_b32_e32 v12, 16, v2
	v_ashrrev_i32_e32 v13, 31, v12
	v_cvt_pk_bf16_f32 v0, v7, v5
	v_lshlrev_b64 v[4:5], 11, v[12:13]
	v_lshl_add_u64 v[4:5], v[8:9], 0, v[4:5]
	global_store_dword v[4:5], v0, off
	v_or_b32_e32 v4, 20, v2
	v_ashrrev_i32_e32 v5, 31, v4
	v_lshlrev_b64 v[4:5], 11, v[4:5]
	v_cvt_pk_bf16_f32 v0, v11, v19
	v_lshl_add_u64 v[4:5], v[8:9], 0, v[4:5]
	global_store_dword v[4:5], v0, off
	v_or_b32_e32 v4, 24, v2
	v_ashrrev_i32_e32 v5, 31, v4
	v_or_b32_e32 v2, 28, v2
	v_lshlrev_b64 v[4:5], 11, v[4:5]
	v_ashrrev_i32_e32 v3, 31, v2
	v_cvt_pk_bf16_f32 v0, v21, v23
	v_lshl_add_u64 v[4:5], v[8:9], 0, v[4:5]
	v_lshlrev_b64 v[2:3], 11, v[2:3]
	global_store_dword v[4:5], v0, off
	v_cvt_pk_bf16_f32 v0, v25, v27
	v_lshl_add_u64 v[2:3], v[8:9], 0, v[2:3]
	s_mov_b64 s[2:3], 0
	global_store_dword v[2:3], v0, off
	s_barrier

.LBB0_101:
	s_lshl_b32 s35, s30, 3
	s_lshl_b32 s34, s20, 3
	v_mov_b32_e32 v65, v25
	v_or_b32_e32 v64, s35, v6
	s_add_i32 s59, s35, 16
	v_or_b32_e32 v66, s34, v5
	s_add_i32 s58, s34, 16
	s_add_i32 s61, s34, 32
	s_add_i32 s64, s35, 32
	s_add_i32 s34, s34, 48
	v_mov_b32_e32 v69, v1
	v_add_u32_e32 v68, s2, v64
	v_mov_b32_e32 v71, v27
	v_or_b32_e32 v70, s59, v6
	s_add_i32 s35, s35, 48
	v_mov_b32_e32 v73, v9
	v_add_u32_e32 v72, s3, v66
	v_mov_b32_e32 v74, v64
	v_or_b32_e32 v75, s58, v5
	v_mov_b32_e32 v64, v70
	v_or_b32_e32 v65, s61, v5
	v_or_b32_e32 v67, s64, v6
	v_or_b32_e32 v70, s34, v5
	v_mov_b32_e32 v77, v69
	v_mul_lo_u32 v76, v68, s56
	v_mov_b32_e32 v69, v13
	v_add_u32_e32 v68, s2, v64
	v_mov_b32_e32 v78, v72
	v_mov_b32_e32 v79, v77
	v_or_b32_e32 v71, s35, v6
	v_mov_b32_e32 v73, v79
	v_mul_lo_u32 v72, v78, s56
	v_mov_b32_e32 v79, v11
	v_add_u32_e32 v78, s3, v75
	v_add_u32_e32 v80, s2, v67
	v_mov_b32_e32 v83, v19
	v_add_u32_e32 v82, s3, v65
	v_mov_b32_e32 v85, v23
	v_add_u32_e32 v84, s3, v70
	v_lshl_add_u64 v[86:87], v[76:77], 2, v[2:3]
	v_mov_b32_e32 v89, v77
	v_mul_lo_u32 v88, v68, s56
	v_mov_b32_e32 v76, v78
	v_mov_b32_e32 v77, v89
	v_add_u32_e32 v78, s2, v71
	v_lshl_add_u64 v[90:91], v[72:73], 2, v[2:3]
	v_mov_b32_e32 v73, v77
	v_mul_lo_u32 v72, v76, s56
	v_mov_b32_e32 v77, v69
	v_mul_lo_u32 v76, v82, s56
	v_mov_b32_e32 v69, v83
	v_mul_lo_u32 v68, v84, s56
	v_lshl_add_u64 v[82:83], v[88:89], 2, v[2:3]
	v_mov_b32_e32 v85, v89
	v_mul_lo_u32 v84, v80, s56
	v_mov_b32_e32 v88, v76
	v_mov_b32_e32 v89, v85
	v_mov_b32_e32 v76, v68
	v_mov_b32_e32 v77, v85
	v_lshl_add_u64 v[68:69], v[72:73], 2, v[2:3]
	global_load_dword v72, v[86:87], off
	global_load_dword v73, v[90:91], off
	global_load_dword v79, v[82:83], off
	global_load_dword v80, v[68:69], off
	v_lshl_add_u64 v[92:93], v[84:85], 2, v[2:3]
	v_mov_b32_e32 v91, v85
	v_mul_lo_u32 v90, v78, s56
	v_lshl_add_u64 v[84:85], v[88:89], 2, v[2:3]
	v_lshl_add_u64 v[88:89], v[76:77], 2, v[2:3]
	v_lshl_add_u64 v[76:77], v[90:91], 2, v[2:3]
	v_mov_b32_e32 v69, v91
	global_load_dword v68, v[92:93], off
	global_load_dword v81, v[84:85], off
	global_load_dword v78, v[76:77], off
	global_load_dword v90, v[88:89], off
	s_add_i32 s30, s30, 8
	s_add_i32 s20, s20, 8
	s_add_i32 s31, s31, -8
	v_mad_u64_u32 v[94:95], s[34:35], v74, s41, v[4:5]
	s_cmp_lg_u32 s31, 0
	v_mad_u64_u32 v[92:93], s[34:35], v66, s41, v[4:5]
	v_mad_u64_u32 v[76:77], s[34:35], v64, s41, v[4:5]
	v_mad_u64_u32 v[84:85], s[34:35], v75, s41, v[4:5]
	v_mad_u64_u32 v[88:89], s[34:35], v67, s41, v[4:5]
	v_mad_u64_u32 v[86:87], s[34:35], v65, s41, v[4:5]
	v_mad_u64_u32 v[82:83], s[34:35], v71, s41, v[4:5]
	v_mad_u64_u32 v[74:75], s[34:35], v70, s41, v[4:5]
	s_lshl_b32 s35, s30, 3
	s_lshl_b32 s34, s20, 3
	v_mov_b32_e32 v65, v83
	v_or_b32_e32 v64, s35, v6
	s_add_i32 s59, s35, 16
	v_or_b32_e32 v83, s34, v5
	s_add_i32 s58, s34, 16
	s_add_i32 s61, s34, 32
	s_add_i32 s64, s35, 32
	s_add_i32 s34, s34, 48
	v_mov_b32_e32 v97, v69
	v_add_u32_e32 v96, s2, v64
	v_mov_b32_e32 v99, v75
	v_or_b32_e32 v98, s59, v6
	s_add_i32 s35, s35, 48
	v_mov_b32_e32 v101, v95
	v_add_u32_e32 v100, s3, v83
	v_mov_b32_e32 v102, v64
	v_or_b32_e32 v103, s58, v5
	v_mov_b32_e32 v64, v98
	v_or_b32_e32 v65, s61, v5
	v_or_b32_e32 v66, s64, v6
	v_or_b32_e32 v67, s34, v5
	v_mov_b32_e32 v99, v97
	v_mul_lo_u32 v98, v96, s56
	v_mov_b32_e32 v97, v77
	v_add_u32_e32 v96, s2, v64
	v_mov_b32_e32 v104, v100
	v_mov_b32_e32 v105, v99
	v_or_b32_e32 v69, s35, v6
	v_mov_b32_e32 v71, v105
	v_mul_lo_u32 v70, v104, s56
	v_mov_b32_e32 v101, v93
	v_add_u32_e32 v100, s3, v103
	v_add_u32_e32 v75, s2, v66
	v_mov_b32_e32 v105, v85
	v_add_u32_e32 v104, s3, v65
	v_mov_b32_e32 v107, v87
	v_add_u32_e32 v106, s3, v67
	v_lshl_add_u64 v[108:109], v[98:99], 2, v[2:3]
	v_mov_b32_e32 v111, v99
	v_mul_lo_u32 v110, v96, s56
	v_mov_b32_e32 v98, v100
	v_mov_b32_e32 v99, v111
	v_add_u32_e32 v77, s2, v69
	v_lshl_add_u64 v[100:101], v[70:71], 2, v[2:3]
	v_mov_b32_e32 v71, v99
	v_mul_lo_u32 v70, v98, s56
	v_mov_b32_e32 v99, v97
	v_mul_lo_u32 v98, v104, s56
	v_mov_b32_e32 v97, v105
	v_mul_lo_u32 v96, v106, s56
	v_lshl_add_u64 v[104:105], v[110:111], 2, v[2:3]
	v_mov_b32_e32 v107, v111
	v_mul_lo_u32 v106, v75, s56
	v_mov_b32_e32 v110, v98
	v_mov_b32_e32 v111, v107
	v_mov_b32_e32 v98, v96
	v_mov_b32_e32 v99, v107
	v_lshl_add_u64 v[96:97], v[70:71], 2, v[2:3]
	global_load_dword v70, v[108:109], off
	global_load_dword v71, v[100:101], off
	global_load_dword v75, v[104:105], off
	global_load_dword v85, v[96:97], off
	v_lshl_add_u64 v[112:113], v[106:107], 2, v[2:3]
	v_mov_b32_e32 v101, v107
	v_mul_lo_u32 v100, v77, s56
	v_lshl_add_u64 v[106:107], v[110:111], 2, v[2:3]
	v_lshl_add_u64 v[110:111], v[98:99], 2, v[2:3]
	v_lshl_add_u64 v[98:99], v[100:101], 2, v[2:3]
	v_mov_b32_e32 v97, v101
	global_load_dword v96, v[112:113], off
	global_load_dword v87, v[106:107], off
	global_load_dword v77, v[98:99], off
	global_load_dword v89, v[110:111], off
	s_add_i32 s30, s30, 8
	s_add_i32 s20, s20, 8
	s_add_i32 s31, s31, -8
	v_mad_u64_u32 v[100:101], s[34:35], v102, s41, v[4:5]
	s_cmp_lg_u32 s31, 0
	v_mad_u64_u32 v[112:113], s[34:35], v83, s41, v[4:5]
	v_mad_u64_u32 v[98:99], s[34:35], v64, s41, v[4:5]
	v_mad_u64_u32 v[106:107], s[34:35], v103, s41, v[4:5]
	v_mad_u64_u32 v[110:111], s[34:35], v66, s41, v[4:5]
	v_mad_u64_u32 v[108:109], s[34:35], v65, s41, v[4:5]
	v_mad_u64_u32 v[104:105], s[34:35], v69, s41, v[4:5]
	v_mad_u64_u32 v[102:103], s[34:35], v67, s41, v[4:5]
	s_waitcnt vmcnt(15)
	ds_write_b32 v94, v72
	s_waitcnt vmcnt(14)
	ds_write_b32 v92, v73
	s_waitcnt vmcnt(13)
	ds_write_b32 v76, v79
	s_waitcnt vmcnt(12)
	ds_write_b32 v84, v80
	s_waitcnt vmcnt(11)
	ds_write_b32 v88, v68
	s_waitcnt vmcnt(10)
	ds_write_b32 v86, v81
	s_waitcnt vmcnt(9)
	ds_write_b32 v82, v78
	s_waitcnt vmcnt(8)
	ds_write_b32 v74, v90
	s_waitcnt vmcnt(7)
	ds_write_b32 v100, v70
	s_waitcnt vmcnt(6)
	ds_write_b32 v112, v71
	s_waitcnt vmcnt(5)
	ds_write_b32 v98, v75
	s_waitcnt vmcnt(4)
	ds_write_b32 v106, v85
	s_waitcnt vmcnt(3)
	ds_write_b32 v110, v96
	s_waitcnt vmcnt(2)
	ds_write_b32 v108, v87
	s_waitcnt vmcnt(1)
	ds_write_b32 v104, v77
	s_waitcnt vmcnt(0)
	ds_write_b32 v102, v89
	v_mov_b32_e32 v0, v96
	v_mov_b32_e32 v1, v97
	v_mov_b32_e32 v8, v100
	v_mov_b32_e32 v9, v101
	v_mov_b32_e32 v10, v112
	v_mov_b32_e32 v11, v113
	v_mov_b32_e32 v12, v98
	v_mov_b32_e32 v13, v99
	v_mov_b32_e32 v17, v83
	v_mov_b32_e32 v18, v106
	v_mov_b32_e32 v19, v107
	v_mov_b32_e32 v20, v110
	v_mov_b32_e32 v21, v111
	v_mov_b32_e32 v22, v108
	v_mov_b32_e32 v23, v109
	v_mov_b32_e32 v24, v104
	v_mov_b32_e32 v25, v105
	v_mov_b32_e32 v26, v102
	v_mov_b32_e32 v27, v103
	v_mov_b32_e32 v28, v66
	v_mov_b32_e32 v29, v67
	v_mov_b32_e32 v30, v69
	v_mov_b32_e32 v31, v70
	v_mov_b32_e32 v32, v87
	v_mov_b32_e32 v33, v71
	v_mov_b32_e32 v34, v75
	v_mov_b32_e32 v35, v85
	v_mov_b32_e32 v36, v77
	v_mov_b32_e32 v37, v89
	v_lshlrev_b32_sdwa v0, v14, v7 dst_sel:DWORD dst_unused:UNUSED_PAD src0_sel:DWORD src1_sel:BYTE_0
	v_and_b32_e32 v0, 0x7e, v0
	v_lshrrev_b32_sdwa v10, v15, v7 dst_sel:DWORD dst_unused:UNUSED_PAD src0_sel:DWORD src1_sel:BYTE_0
	v_mul_u32_u24_e32 v2, 0x84, v0
	v_lshlrev_b32_e32 v3, 2, v10
	v_add3_u32 v12, s36, v2, v3
	s_waitcnt lgkmcnt(0)
	s_barrier
	ds_read2_b32 v[2:3], v12 offset0:33 offset1:37
	ds_read2_b32 v[4:5], v12 offset1:4
	v_or_b32_e32 v0, s2, v0
	v_lshlrev_b32_e32 v0, 1, v0
	v_lshl_add_u64 v[6:7], s[18:19], 0, v[0:1]
	v_lshlrev_b32_e32 v0, 11, v10
	s_waitcnt lgkmcnt(0)
	v_cvt_pk_bf16_f32 v2, v4, v2
	v_lshl_add_u64 v[10:11], v[6:7], 0, v[0:1]
	ds_read2_b32 v[8:9], v12 offset0:8 offset1:12
	global_store_dword v[10:11], v2, off
	v_cvt_pk_bf16_f32 v10, v5, v3
	ds_read2_b32 v[2:3], v12 offset0:41 offset1:45
	v_or_b32_e32 v4, 0x2000, v0
	v_mov_b32_e32 v5, v1
	v_lshl_add_u64 v[4:5], v[6:7], 0, v[4:5]
	global_store_dword v[4:5], v10, off
	v_or_b32_e32 v4, 0x4000, v0
	v_mov_b32_e32 v5, v1
	s_waitcnt lgkmcnt(0)
	v_cvt_pk_bf16_f32 v2, v8, v2
	v_lshl_add_u64 v[4:5], v[6:7], 0, v[4:5]
	global_store_dword v[4:5], v2, off
	v_cvt_pk_bf16_f32 v10, v9, v3
	ds_read2_b32 v[2:3], v12 offset0:16 offset1:20
	ds_read2_b32 v[4:5], v12 offset0:49 offset1:53
	v_or_b32_e32 v8, 0x6000, v0
	v_mov_b32_e32 v9, v1
	v_lshl_add_u64 v[8:9], v[6:7], 0, v[8:9]
	global_store_dword v[8:9], v10, off
	v_or_b32_e32 v8, 0x8000, v0
	v_mov_b32_e32 v9, v1
	s_waitcnt lgkmcnt(0)
	v_cvt_pk_bf16_f32 v2, v2, v4
	v_lshl_add_u64 v[8:9], v[6:7], 0, v[8:9]
	global_store_dword v[8:9], v2, off
	v_cvt_pk_bf16_f32 v10, v3, v5
	ds_read2_b32 v[2:3], v12 offset0:57 offset1:61
	ds_read2_b32 v[4:5], v12 offset0:24 offset1:28
	v_or_b32_e32 v8, 0xa000, v0
	v_mov_b32_e32 v9, v1
	v_lshl_add_u64 v[8:9], v[6:7], 0, v[8:9]
	global_store_dword v[8:9], v10, off
	v_or_b32_e32 v8, 0xc000, v0
	v_mov_b32_e32 v9, v1
	s_waitcnt lgkmcnt(0)
	v_cvt_pk_bf16_f32 v2, v4, v2
	v_lshl_add_u64 v[8:9], v[6:7], 0, v[8:9]
	v_or_b32_e32 v0, 0xe000, v0
	global_store_dword v[8:9], v2, off
	v_cvt_pk_bf16_f32 v4, v5, v3
	v_lshl_add_u64 v[2:3], v[6:7], 0, v[0:1]
	global_store_dword v[2:3], v4, off
	s_barrier
	s_branch .LBB0_32

.LBB0_633:
.LBB0_634:
	s_and_b32 s12, s18, 1
	s_mul_i32 s19, s12, 0x6000
	s_lshl_b32 s17, s12, 14
	s_add_i32 s17, s17, 0xc000
	s_add_i32 s16, s18, 1
	s_waitcnt vmcnt(0)
	s_barrier
	s_add_i32 s13, s18, 2
	s_cmp_ge_u32 s13, s10
	s_cbranch_scc1 .Lattn_slow_0
	s_xor_b32 s13, s12, 1
	s_mul_i32 s14, s13, 0x6000
	s_add_i32 s14, s14, s11
	s_lshl_b32 s15, s13, 14
	s_add_i32 s15, s15, s11
	s_add_i32 s15, s15, 0xc000
	s_movk_i32 s12, 0x100
	s_mov_b32 s13, 0
	v_add_u32_e32 v10, s19, v152
	v_xor_b32_e32 v154, 32, v10
	ds_read_b128 v[6:9], v10
	ds_read_b128 v[222:225], v154
	ds_read_b128 v[226:229], v10 offset:64
	ds_read_b128 v[230:233], v154 offset:64
	ds_read_b128 v[234:237], v10 offset:128
	ds_read_b128 v[242:245], v154 offset:128
	ds_read_b128 v[246:249], v10 offset:6144
	ds_read_b128 v[250:253], v154 offset:6144
	s_waitcnt lgkmcnt(7)
	v_mfma_f32_32x32x16_bf16 v[80:95], v[6:9], v[120:123], v[174:189]
	ds_read_b128 v[6:9], v10 offset:6208
	s_add_i32 m0, s14, 0x0
	v_lshl_add_u64 v[136:137], v[136:137], 0, v[146:147]
	global_load_lds_dwordx4 v[136:137], off
	s_waitcnt lgkmcnt(7)
	v_mfma_f32_32x32x16_bf16 v[80:95], v[222:225], v[112:115], v[80:95]
	ds_read_b128 v[222:225], v154 offset:6208
	s_waitcnt lgkmcnt(7)
	v_mfma_f32_32x32x16_bf16 v[80:95], v[226:229], v[116:119], v[80:95]
	ds_read_b128 v[226:229], v10 offset:6272
	s_add_i32 m0, s14, 0x2000
	v_lshl_add_u64 v[138:139], v[138:139], 0, v[148:149]
	global_load_lds_dwordx4 v[138:139], off
	s_waitcnt lgkmcnt(7)
	v_mfma_f32_32x32x16_bf16 v[80:95], v[230:233], v[124:127], v[80:95]
	ds_read_b128 v[230:233], v154 offset:6272
	s_waitcnt lgkmcnt(7)
	v_mfma_f32_32x32x16_bf16 v[80:95], v[234:237], v[128:131], v[80:95]
	ds_read_b128 v[234:237], v10 offset:12288
	s_add_i32 m0, s14, 0x4000
	v_lshl_add_u64 v[140:141], v[140:141], 0, v[150:151]
	global_load_lds_dwordx4 v[140:141], off
	s_waitcnt lgkmcnt(7)
	v_mfma_f32_32x32x16_bf16 v[80:95], v[242:245], v[132:135], v[80:95]
	ds_read_b128 v[242:245], v154 offset:12288
	s_waitcnt lgkmcnt(7)
	v_mfma_f32_32x32x16_bf16 v[64:79], v[246:249], v[120:123], v[174:189]
	ds_read_b128 v[246:249], v10 offset:12352
	s_add_i32 m0, s15, 0x0
	v_lshl_add_u64 v[142:143], v[142:143], 0, s[12:13]
	global_load_lds_dwordx4 v[142:143], off
	s_waitcnt lgkmcnt(7)
	v_mfma_f32_32x32x16_bf16 v[64:79], v[250:253], v[112:115], v[64:79]
	ds_read_b128 v[250:253], v154 offset:12352
	s_waitcnt lgkmcnt(7)
	v_mfma_f32_32x32x16_bf16 v[64:79], v[6:9], v[116:119], v[64:79]
	ds_read_b128 v[6:9], v10 offset:12416
	s_add_i32 m0, s15, 0x2000
	v_lshl_add_u64 v[144:145], v[144:145], 0, s[12:13]
	global_load_lds_dwordx4 v[144:145], off
	s_waitcnt lgkmcnt(7)
	v_mfma_f32_32x32x16_bf16 v[64:79], v[222:225], v[124:127], v[64:79]
	ds_read_b128 v[222:225], v154 offset:12416
	s_waitcnt lgkmcnt(7)
	v_mfma_f32_32x32x16_bf16 v[64:79], v[226:229], v[128:131], v[64:79]
	ds_read_b128 v[226:229], v10 offset:18432
	v_max3_f32 v3, v80, v81, v82
	v_max3_f32 v3, v3, v83, v84
	v_max3_f32 v3, v3, v85, v86
	v_max3_f32 v3, v3, v87, v88
	v_max3_f32 v3, v3, v89, v90
	s_waitcnt lgkmcnt(7)
	v_mfma_f32_32x32x16_bf16 v[64:79], v[230:233], v[132:135], v[64:79]
	ds_read_b128 v[230:233], v154 offset:18432
	v_max3_f32 v3, v3, v91, v92
	v_max3_f32 v3, v3, v93, v94
	v_max_f32_e32 v3, v3, v95
	v_exp_f32_e32 v80, v80
	v_exp_f32_e32 v81, v81
	s_waitcnt lgkmcnt(7)
	v_mfma_f32_32x32x16_bf16 v[96:111], v[234:237], v[120:123], v[174:189]
	ds_read_b128 v[234:237], v10 offset:18496
	v_exp_f32_e32 v82, v82
	v_exp_f32_e32 v83, v83
	v_mov_b64_e32 v[12:13], v[80:81]
	v_mov_b64_e32 v[14:15], v[82:83]
	v_exp_f32_e32 v84, v84
	s_waitcnt lgkmcnt(7)
	v_mfma_f32_32x32x16_bf16 v[96:111], v[242:245], v[112:115], v[96:111]
	ds_read_b128 v[242:245], v154 offset:18496
	v_exp_f32_e32 v85, v85
	v_exp_f32_e32 v86, v86
	v_exp_f32_e32 v87, v87
	v_pk_add_f32 v[12:13], v[12:13], v[84:85]
	v_pk_add_f32 v[14:15], v[14:15], v[86:87]
	s_waitcnt lgkmcnt(7)
	v_mfma_f32_32x32x16_bf16 v[96:111], v[246:249], v[116:119], v[96:111]
	ds_read_b128 v[246:249], v10 offset:18560
	v_cvt_pk_bf16_f32 v80, v80, v81
	v_cvt_pk_bf16_f32 v81, v82, v83
	v_cvt_pk_bf16_f32 v82, v84, v85
	v_cvt_pk_bf16_f32 v83, v86, v87
	v_exp_f32_e32 v88, v88
	s_waitcnt lgkmcnt(7)
	v_mfma_f32_32x32x16_bf16 v[96:111], v[250:253], v[124:127], v[96:111]
	ds_read_b128 v[250:253], v154 offset:18560
	v_exp_f32_e32 v89, v89
	v_exp_f32_e32 v90, v90
	v_exp_f32_e32 v91, v91
	v_pk_add_f32 v[12:13], v[12:13], v[88:89]
	v_pk_add_f32 v[14:15], v[14:15], v[90:91]
	s_waitcnt lgkmcnt(7)
	v_mfma_f32_32x32x16_bf16 v[96:111], v[6:9], v[128:131], v[96:111]
	v_add_u32_e32 v155, s17, v153
	v_exp_f32_e32 v92, v92
	v_exp_f32_e32 v93, v93
	v_exp_f32_e32 v94, v94
	v_exp_f32_e32 v95, v95
	v_pk_add_f32 v[12:13], v[12:13], v[92:93]
	s_waitcnt lgkmcnt(6)
	v_mfma_f32_32x32x16_bf16 v[96:111], v[222:225], v[132:135], v[96:111]
	ds_read_b128 v[222:225], v155
	v_pk_add_f32 v[14:15], v[14:15], v[94:95]
	v_cvt_pk_bf16_f32 v84, v88, v89
	v_cvt_pk_bf16_f32 v85, v90, v91
	v_cvt_pk_bf16_f32 v86, v92, v93
	v_cvt_pk_bf16_f32 v87, v94, v95
	s_waitcnt lgkmcnt(6)
	v_mfma_f32_32x32x16_bf16 v[48:63], v[226:229], v[120:123], v[174:189]
	ds_read_b128 v[226:229], v155 offset:8192
	v_max3_f32 v4, v64, v65, v66
	v_max3_f32 v4, v4, v67, v68
	v_max3_f32 v4, v4, v69, v70
	v_max3_f32 v4, v4, v71, v72
	v_max3_f32 v4, v4, v73, v74
	s_waitcnt lgkmcnt(6)
	v_mfma_f32_32x32x16_bf16 v[48:63], v[230:233], v[112:115], v[48:63]
	v_xor_b32_e32 v238, 32, v155
	ds_read_b128 v[230:233], v238
	v_max3_f32 v4, v4, v75, v76
	v_max3_f32 v4, v4, v77, v78
	v_max_f32_e32 v4, v4, v79
	v_exp_f32_e32 v64, v64
	v_exp_f32_e32 v65, v65
	s_waitcnt lgkmcnt(6)
	v_mfma_f32_32x32x16_bf16 v[48:63], v[234:237], v[116:119], v[48:63]
	ds_read_b128 v[234:237], v238 offset:8192
	v_exp_f32_e32 v66, v66
	v_exp_f32_e32 v67, v67
	v_pk_add_f32 v[12:13], v[12:13], v[64:65]
	v_pk_add_f32 v[14:15], v[14:15], v[66:67]
	v_exp_f32_e32 v68, v68
	s_waitcnt lgkmcnt(6)
	v_mfma_f32_32x32x16_bf16 v[48:63], v[242:245], v[124:127], v[48:63]
	v_xor_b32_e32 v239, 64, v155
	ds_read_b128 v[242:245], v239
	v_exp_f32_e32 v69, v69
	v_exp_f32_e32 v70, v70
	v_exp_f32_e32 v71, v71
	v_pk_add_f32 v[12:13], v[12:13], v[68:69]
	v_pk_add_f32 v[14:15], v[14:15], v[70:71]
	s_waitcnt lgkmcnt(6)
	v_mfma_f32_32x32x16_bf16 v[48:63], v[246:249], v[128:131], v[48:63]
	ds_read_b128 v[246:249], v239 offset:8192
	v_cvt_pk_bf16_f32 v64, v64, v65
	v_cvt_pk_bf16_f32 v65, v66, v67
	v_cvt_pk_bf16_f32 v66, v68, v69
	v_cvt_pk_bf16_f32 v67, v70, v71
	v_exp_f32_e32 v72, v72
	s_waitcnt lgkmcnt(6)
	v_mfma_f32_32x32x16_bf16 v[48:63], v[250:253], v[132:135], v[48:63]
	v_xor_b32_e32 v238, 96, v155
	ds_read_b128 v[250:253], v238
	v_exp_f32_e32 v73, v73
	v_exp_f32_e32 v74, v74
	v_exp_f32_e32 v75, v75
	v_pk_add_f32 v[12:13], v[12:13], v[72:73]
	v_pk_add_f32 v[14:15], v[14:15], v[74:75]
	s_waitcnt lgkmcnt(6)
	v_mfma_f32_32x32x16_bf16 v[32:47], v[222:225], v[80:83], v[32:47]
	v_exp_f32_e32 v76, v76
	v_exp_f32_e32 v77, v77
	v_exp_f32_e32 v78, v78
	s_waitcnt lgkmcnt(5)
	v_mfma_f32_32x32x16_bf16 v[16:31], v[226:229], v[80:83], v[16:31]
	ds_read_b128 v[222:225], v238 offset:8192
	v_xor_b32_e32 v239, 128, v155
	ds_read_b128 v[226:229], v239
	v_exp_f32_e32 v79, v79
	v_pk_add_f32 v[12:13], v[12:13], v[76:77]
	v_pk_add_f32 v[14:15], v[14:15], v[78:79]
	s_waitcnt lgkmcnt(6)
	v_mfma_f32_32x32x16_bf16 v[32:47], v[230:233], v[84:87], v[32:47]
	v_cvt_pk_bf16_f32 v68, v72, v73
	v_cvt_pk_bf16_f32 v69, v74, v75
	v_cvt_pk_bf16_f32 v70, v76, v77
	s_waitcnt lgkmcnt(5)
	v_mfma_f32_32x32x16_bf16 v[16:31], v[234:237], v[84:87], v[16:31]
	ds_read_b128 v[230:233], v239 offset:8192
	v_xor_b32_e32 v238, 160, v155
	ds_read_b128 v[234:237], v238
	v_cvt_pk_bf16_f32 v71, v78, v79
	s_waitcnt lgkmcnt(6)
	v_mfma_f32_32x32x16_bf16 v[32:47], v[242:245], v[64:67], v[32:47]
	v_max3_f32 v5, v96, v97, v98
	v_max3_f32 v5, v5, v99, v100
	v_max3_f32 v5, v5, v101, v102
	v_max3_f32 v5, v5, v103, v104
	v_max3_f32 v5, v5, v105, v106
	v_max3_f32 v5, v5, v107, v108
	v_max3_f32 v5, v5, v109, v110
	v_max_f32_e32 v5, v5, v111
	v_exp_f32_e32 v96, v96
	v_exp_f32_e32 v97, v97
	s_waitcnt lgkmcnt(5)
	v_mfma_f32_32x32x16_bf16 v[16:31], v[246:249], v[64:67], v[16:31]
	ds_read_b128 v[242:245], v238 offset:8192
	v_xor_b32_e32 v239, 192, v155
	ds_read_b128 v[246:249], v239
	v_exp_f32_e32 v98, v98
	v_exp_f32_e32 v99, v99
	v_pk_add_f32 v[12:13], v[12:13], v[96:97]
	v_pk_add_f32 v[14:15], v[14:15], v[98:99]
	v_exp_f32_e32 v100, v100
	v_exp_f32_e32 v101, v101
	v_exp_f32_e32 v102, v102
	v_exp_f32_e32 v103, v103
	v_pk_add_f32 v[12:13], v[12:13], v[100:101]
	v_pk_add_f32 v[14:15], v[14:15], v[102:103]
	s_waitcnt lgkmcnt(6)
	v_mfma_f32_32x32x16_bf16 v[32:47], v[250:253], v[68:71], v[32:47]
	v_cvt_pk_bf16_f32 v96, v96, v97
	v_cvt_pk_bf16_f32 v97, v98, v99
	v_cvt_pk_bf16_f32 v98, v100, v101
	v_cvt_pk_bf16_f32 v99, v102, v103
	v_exp_f32_e32 v104, v104
	v_exp_f32_e32 v105, v105
	v_exp_f32_e32 v106, v106
	v_exp_f32_e32 v107, v107
	v_pk_add_f32 v[12:13], v[12:13], v[104:105]
	v_pk_add_f32 v[14:15], v[14:15], v[106:107]
	s_waitcnt lgkmcnt(5)
	v_mfma_f32_32x32x16_bf16 v[16:31], v[222:225], v[68:71], v[16:31]
	ds_read_b128 v[250:253], v239 offset:8192
	v_xor_b32_e32 v238, 224, v155
	ds_read_b128 v[222:225], v238
	v_exp_f32_e32 v108, v108
	v_exp_f32_e32 v109, v109
	v_exp_f32_e32 v110, v110
	v_exp_f32_e32 v111, v111
	v_pk_add_f32 v[12:13], v[12:13], v[108:109]
	v_pk_add_f32 v[14:15], v[14:15], v[110:111]
	v_cvt_pk_bf16_f32 v100, v104, v105
	v_cvt_pk_bf16_f32 v101, v106, v107
	v_cvt_pk_bf16_f32 v102, v108, v109
	v_cvt_pk_bf16_f32 v103, v110, v111
	s_waitcnt lgkmcnt(6)
	v_mfma_f32_32x32x16_bf16 v[32:47], v[226:229], v[96:99], v[32:47]
	v_max3_f32 v2, v48, v49, v50
	v_max3_f32 v2, v2, v51, v52
	v_max3_f32 v2, v2, v53, v54
	v_max3_f32 v2, v2, v55, v56
	v_max3_f32 v2, v2, v57, v58
	v_max3_f32 v2, v2, v59, v60
	v_max3_f32 v2, v2, v61, v62
	v_max_f32_e32 v2, v2, v63
	v_exp_f32_e32 v48, v48
	v_exp_f32_e32 v49, v49
	s_waitcnt lgkmcnt(5)
	v_mfma_f32_32x32x16_bf16 v[16:31], v[230:233], v[96:99], v[16:31]
	ds_read_b128 v[226:229], v238 offset:8192
	v_exp_f32_e32 v50, v50
	v_exp_f32_e32 v51, v51
	v_pk_add_f32 v[12:13], v[12:13], v[48:49]
	v_pk_add_f32 v[14:15], v[14:15], v[50:51]
	v_exp_f32_e32 v52, v52
	v_exp_f32_e32 v53, v53
	v_exp_f32_e32 v54, v54
	v_exp_f32_e32 v55, v55
	v_pk_add_f32 v[12:13], v[12:13], v[52:53]
	v_pk_add_f32 v[14:15], v[14:15], v[54:55]
	s_waitcnt lgkmcnt(5)
	v_mfma_f32_32x32x16_bf16 v[32:47], v[234:237], v[100:103], v[32:47]
	v_cvt_pk_bf16_f32 v48, v48, v49
	v_cvt_pk_bf16_f32 v49, v50, v51
	v_cvt_pk_bf16_f32 v50, v52, v53
	v_cvt_pk_bf16_f32 v51, v54, v55
	v_exp_f32_e32 v56, v56
	v_exp_f32_e32 v57, v57
	v_exp_f32_e32 v58, v58
	v_exp_f32_e32 v59, v59
	v_pk_add_f32 v[12:13], v[12:13], v[56:57]
	v_pk_add_f32 v[14:15], v[14:15], v[58:59]
	s_waitcnt lgkmcnt(4)
	v_mfma_f32_32x32x16_bf16 v[16:31], v[242:245], v[100:103], v[16:31]
	v_exp_f32_e32 v60, v60
	v_exp_f32_e32 v61, v61
	v_exp_f32_e32 v62, v62
	v_exp_f32_e32 v63, v63
	v_pk_add_f32 v[12:13], v[12:13], v[60:61]
	v_pk_add_f32 v[14:15], v[14:15], v[62:63]
	v_cvt_pk_bf16_f32 v52, v56, v57
	v_cvt_pk_bf16_f32 v53, v58, v59
	v_cvt_pk_bf16_f32 v54, v60, v61
	v_cvt_pk_bf16_f32 v55, v62, v63
	s_waitcnt lgkmcnt(3)
	v_mfma_f32_32x32x16_bf16 v[32:47], v[246:249], v[48:51], v[32:47]
	s_waitcnt lgkmcnt(2)
	v_mfma_f32_32x32x16_bf16 v[16:31], v[250:253], v[48:51], v[16:31]
	s_waitcnt lgkmcnt(1)
	v_mfma_f32_32x32x16_bf16 v[32:47], v[222:225], v[52:55], v[32:47]
	s_waitcnt lgkmcnt(0)
	v_mfma_f32_32x32x16_bf16 v[16:31], v[226:229], v[52:55], v[16:31]
	v_add_f32_e32 v12, v12, v13
	v_add_f32_e32 v14, v14, v15
	v_max3_f32 v2, v2, v3, v4
	v_add_f32_e32 v12, v12, v14
	v_max_f32_e32 v2, v2, v5
	v_add_f32_e32 v215, v215, v12
	v_mov_b32_e32 v3, v2
	s_nop 1
	v_permlane32_swap_b32_e32 v2, v3
	v_max_f32_e32 v2, v2, v3
	v_cmp_lt_f32_e32 vcc, 0, v2
	s_cbranch_vccz .Lattn_fnr_0
	s_nop 7
	s_nop 3
	v_max_f32_e32 v2, 0, v2
	v_exp_f32_e64 v4, -v2
	v_add_f32_e32 v0, v0, v2
	s_nop 0
	v_mul_f32_e32 v215, v215, v4
	v_mul_f32_e32 v16, v16, v4
	v_mul_f32_e32 v17, v17, v4
	v_mul_f32_e32 v18, v18, v4
	v_mul_f32_e32 v19, v19, v4
	v_mul_f32_e32 v20, v20, v4
	v_mul_f32_e32 v21, v21, v4
	v_mul_f32_e32 v22, v22, v4
	v_mul_f32_e32 v23, v23, v4
	v_mul_f32_e32 v24, v24, v4
	v_mul_f32_e32 v25, v25, v4
	v_mul_f32_e32 v26, v26, v4
	v_mul_f32_e32 v27, v27, v4
	v_mul_f32_e32 v28, v28, v4
	v_mul_f32_e32 v29, v29, v4
	v_mul_f32_e32 v30, v30, v4
	v_mul_f32_e32 v31, v31, v4
	v_mul_f32_e32 v32, v32, v4
	v_mul_f32_e32 v33, v33, v4
	v_mul_f32_e32 v34, v34, v4
	v_mul_f32_e32 v35, v35, v4
	v_mul_f32_e32 v36, v36, v4
	v_mul_f32_e32 v37, v37, v4
	v_mul_f32_e32 v38, v38, v4
	v_mul_f32_e32 v39, v39, v4
	v_mul_f32_e32 v40, v40, v4
	v_mul_f32_e32 v41, v41, v4
	v_mul_f32_e32 v42, v42, v4
	v_mul_f32_e32 v43, v43, v4
	v_mul_f32_e32 v44, v44, v4
	v_mul_f32_e32 v45, v45, v4
	v_mul_f32_e32 v46, v46, v4
	v_mul_f32_e32 v47, v47, v4
	v_xor_b32_e32 v174, 0x80000000, v0
	v_mov_b32_e32 v175, v174
	v_mov_b32_e32 v176, v174
	v_mov_b32_e32 v177, v174
	v_mov_b32_e32 v178, v174
	v_mov_b32_e32 v179, v174
	v_mov_b32_e32 v180, v174
	v_mov_b32_e32 v181, v174
	v_mov_b32_e32 v182, v174
	v_mov_b32_e32 v183, v174
	v_mov_b32_e32 v184, v174
	v_mov_b32_e32 v185, v174
	v_mov_b32_e32 v186, v174
	v_mov_b32_e32 v187, v174
	v_mov_b32_e32 v188, v174
	v_mov_b32_e32 v189, v174

.Lattn_slow_0:
	s_cmp_ge_u32 s16, s10
	s_cbranch_scc1 .Lattn_nodma_0
	s_xor_b32 s13, s12, 1
	s_mul_i32 s14, s13, 0x6000
	s_add_i32 s14, s14, s11
	s_lshl_b32 s15, s13, 14
	s_add_i32 s15, s15, s11
	s_add_i32 s15, s15, 0xc000
	s_movk_i32 s12, 0x100
	s_mov_b32 s13, 0
	s_add_i32 m0, s14, 0x0
	v_lshl_add_u64 v[136:137], v[136:137], 0, v[146:147]
	global_load_lds_dwordx4 v[136:137], off
	s_add_i32 m0, s14, 0x2000
	v_lshl_add_u64 v[138:139], v[138:139], 0, v[148:149]
	global_load_lds_dwordx4 v[138:139], off
	s_add_i32 m0, s14, 0x4000
	v_lshl_add_u64 v[140:141], v[140:141], 0, v[150:151]
	global_load_lds_dwordx4 v[140:141], off
	s_add_i32 m0, s15, 0x0
	v_lshl_add_u64 v[142:143], v[142:143], 0, s[12:13]
	global_load_lds_dwordx4 v[142:143], off
	s_add_i32 m0, s15, 0x2000
	v_lshl_add_u64 v[144:145], v[144:145], 0, s[12:13]
	global_load_lds_dwordx4 v[144:145], off

.LBB0_805:
	s_lshl_b32 s71, s35, 3
	s_lshl_b32 s37, s34, 3
	v_or_b32_e32 v64, s71, v6
	v_or_b32_e32 v65, s37, v5
	v_mov_b32_e32 v67, v1
	v_add_lshl_u32 v66, v64, s2, 10
	v_mov_b32_e32 v69, v9
	v_add_lshl_u32 v68, v65, s3, 10
	v_lshl_add_u64 v[70:71], v[66:67], 2, v[2:3]
	v_mov_b32_e32 v72, v68
	v_mov_b32_e32 v73, v67
	v_lshl_add_u64 v[68:69], v[72:73], 2, v[2:3]
	v_mov_b32_e32 v73, v67
	global_load_dword v72, v[70:71], off
	global_load_dword v66, v[68:69], off
	v_mad_u64_u32 v[74:75], s[72:73], v64, s64, v[4:5]
	v_mad_u64_u32 v[68:69], s[72:73], v65, s64, v[4:5]
	s_add_i32 s73, s71, 16
	s_add_i32 s72, s37, 16
	v_or_b32_e32 v67, s73, v6
	v_or_b32_e32 v64, s72, v5
	v_mov_b32_e32 v70, v74
	v_mov_b32_e32 v71, v73
	s_add_i32 s35, s35, 8
	s_add_i32 s34, s34, 8
	s_add_i32 s36, s36, -8
	v_mov_b32_e32 v75, v73
	v_add_lshl_u32 v74, v67, s2, 10
	v_mov_b32_e32 v77, v71
	v_add_lshl_u32 v76, v64, s3, 10
	v_lshl_add_u64 v[78:79], v[74:75], 2, v[2:3]
	v_lshl_add_u64 v[80:81], v[76:77], 2, v[2:3]
	v_mov_b32_e32 v77, v75
	global_load_dword v76, v[78:79], off
	global_load_dword v65, v[80:81], off
	v_mad_u64_u32 v[74:75], s[72:73], v67, s64, v[4:5]
	v_mad_u64_u32 v[80:81], s[72:73], v64, s64, v[4:5]
	s_add_i32 s73, s71, 32
	s_add_i32 s72, s37, 32
	v_or_b32_e32 v69, s73, v6
	v_or_b32_e32 v67, s72, v5
	v_mov_b32_e32 v78, v74
	v_mov_b32_e32 v79, v77
	s_add_i32 s71, s71, 48
	s_add_i32 s37, s37, 48
	s_cmp_lg_u32 s36, 0
	v_mov_b32_e32 v75, v77
	v_add_lshl_u32 v74, v69, s2, 10
	v_mov_b32_e32 v83, v79
	v_add_lshl_u32 v82, v67, s3, 10
	v_lshl_add_u64 v[84:85], v[74:75], 2, v[2:3]
	v_lshl_add_u64 v[86:87], v[82:83], 2, v[2:3]
	v_mov_b32_e32 v83, v75
	global_load_dword v82, v[84:85], off
	global_load_dword v64, v[86:87], off
	v_mad_u64_u32 v[74:75], s[72:73], v69, s64, v[4:5]
	v_or_b32_e32 v71, s71, v6
	v_mad_u64_u32 v[86:87], s[72:73], v67, s64, v[4:5]
	v_or_b32_e32 v69, s37, v5
	v_mov_b32_e32 v84, v74
	v_mov_b32_e32 v85, v83
	v_mov_b32_e32 v75, v83
	v_add_lshl_u32 v74, v71, s2, 10
	v_mov_b32_e32 v89, v85
	v_add_lshl_u32 v88, v69, s3, 10
	v_lshl_add_u64 v[90:91], v[74:75], 2, v[2:3]
	v_lshl_add_u64 v[92:93], v[88:89], 2, v[2:3]
	v_mov_b32_e32 v89, v75
	global_load_dword v88, v[90:91], off
	global_load_dword v67, v[92:93], off
	v_mad_u64_u32 v[74:75], s[72:73], v71, s64, v[4:5]
	v_mad_u64_u32 v[92:93], s[72:73], v69, s64, v[4:5]
	s_lshl_b32 s71, s35, 3
	s_lshl_b32 s37, s34, 3
	v_or_b32_e32 v73, s71, v6
	v_or_b32_e32 v71, s37, v5
	v_mov_b32_e32 v91, v89
	v_add_lshl_u32 v90, v73, s2, 10
	v_mov_b32_e32 v95, v75
	v_add_lshl_u32 v94, v71, s3, 10
	v_lshl_add_u64 v[96:97], v[90:91], 2, v[2:3]
	v_mov_b32_e32 v98, v94
	v_mov_b32_e32 v99, v91
	v_lshl_add_u64 v[94:95], v[98:99], 2, v[2:3]
	v_mov_b32_e32 v99, v91
	global_load_dword v98, v[96:97], off
	global_load_dword v69, v[94:95], off
	v_mad_u64_u32 v[90:91], s[72:73], v73, s64, v[4:5]
	v_mad_u64_u32 v[94:95], s[72:73], v71, s64, v[4:5]
	s_add_i32 s73, s71, 16
	s_add_i32 s72, s37, 16
	v_or_b32_e32 v75, s73, v6
	v_or_b32_e32 v73, s72, v5
	v_mov_b32_e32 v96, v90
	v_mov_b32_e32 v97, v99
	s_add_i32 s35, s35, 8
	s_add_i32 s34, s34, 8
	s_add_i32 s36, s36, -8
	v_mov_b32_e32 v91, v99
	v_add_lshl_u32 v90, v75, s2, 10
	v_mov_b32_e32 v101, v97
	v_add_lshl_u32 v100, v73, s3, 10
	v_lshl_add_u64 v[102:103], v[90:91], 2, v[2:3]
	v_lshl_add_u64 v[104:105], v[100:101], 2, v[2:3]
	v_mov_b32_e32 v101, v91
	global_load_dword v100, v[102:103], off
	global_load_dword v71, v[104:105], off
	v_mad_u64_u32 v[90:91], s[72:73], v75, s64, v[4:5]
	v_mad_u64_u32 v[104:105], s[72:73], v73, s64, v[4:5]
	s_add_i32 s73, s71, 32
	s_add_i32 s72, s37, 32
	v_or_b32_e32 v77, s73, v6
	v_or_b32_e32 v75, s72, v5
	v_mov_b32_e32 v102, v90
	v_mov_b32_e32 v103, v101
	s_add_i32 s71, s71, 48
	s_add_i32 s37, s37, 48
	s_cmp_lg_u32 s36, 0
	v_mov_b32_e32 v91, v101
	v_add_lshl_u32 v90, v77, s2, 10
	v_mov_b32_e32 v107, v103
	v_add_lshl_u32 v106, v75, s3, 10
	v_lshl_add_u64 v[108:109], v[90:91], 2, v[2:3]
	v_lshl_add_u64 v[110:111], v[106:107], 2, v[2:3]
	v_mov_b32_e32 v107, v91
	global_load_dword v106, v[108:109], off
	global_load_dword v73, v[110:111], off
	v_mad_u64_u32 v[90:91], s[72:73], v77, s64, v[4:5]
	v_or_b32_e32 v79, s71, v6
	v_mad_u64_u32 v[110:111], s[72:73], v75, s64, v[4:5]
	v_or_b32_e32 v77, s37, v5
	v_mov_b32_e32 v108, v90
	v_mov_b32_e32 v109, v107
	v_mov_b32_e32 v91, v107
	v_add_lshl_u32 v90, v79, s2, 10
	v_mov_b32_e32 v113, v109
	v_add_lshl_u32 v112, v77, s3, 10
	v_lshl_add_u64 v[114:115], v[90:91], 2, v[2:3]
	v_lshl_add_u64 v[116:117], v[112:113], 2, v[2:3]
	v_mov_b32_e32 v113, v91
	global_load_dword v112, v[114:115], off
	global_load_dword v75, v[116:117], off
	v_mad_u64_u32 v[90:91], s[72:73], v79, s64, v[4:5]
	v_mad_u64_u32 v[116:117], s[72:73], v77, s64, v[4:5]
	s_waitcnt vmcnt(15)
	ds_write_b32 v70, v72
	s_waitcnt vmcnt(14)
	ds_write_b32 v68, v66
	s_waitcnt vmcnt(13)
	ds_write_b32 v78, v76
	s_waitcnt vmcnt(12)
	ds_write_b32 v80, v65
	s_waitcnt vmcnt(11)
	ds_write_b32 v84, v82
	s_waitcnt vmcnt(10)
	ds_write_b32 v86, v64
	s_waitcnt vmcnt(9)
	ds_write_b32 v74, v88
	s_waitcnt vmcnt(8)
	ds_write_b32 v92, v67
	s_waitcnt vmcnt(7)
	ds_write_b32 v96, v98
	s_waitcnt vmcnt(6)
	ds_write_b32 v94, v69
	s_waitcnt vmcnt(5)
	ds_write_b32 v102, v100
	s_waitcnt vmcnt(4)
	ds_write_b32 v104, v71
	s_waitcnt vmcnt(3)
	ds_write_b32 v108, v106
	s_waitcnt vmcnt(2)
	ds_write_b32 v110, v73
	s_waitcnt vmcnt(1)
	ds_write_b32 v90, v112
	s_waitcnt vmcnt(0)
	ds_write_b32 v116, v75
	v_mov_b32_e32 v0, v112
	v_mov_b32_e32 v1, v113
	v_mov_b32_e32 v8, v90
	v_mov_b32_e32 v9, v91
	v_mov_b32_e32 v10, v116
	v_mov_b32_e32 v11, v117
	v_mov_b32_e32 v12, v77
	v_mov_b32_e32 v13, v79
	v_mov_b32_e32 v18, v75
	v_lshlrev_b32_sdwa v0, v14, v7 dst_sel:DWORD dst_unused:UNUSED_PAD src0_sel:DWORD src1_sel:BYTE_0
	v_and_b32_e32 v0, 0x7e, v0
	v_lshrrev_b32_sdwa v8, v15, v7 dst_sel:DWORD dst_unused:UNUSED_PAD src0_sel:DWORD src1_sel:BYTE_0
	v_or_b32_e32 v6, s2, v0
	v_mul_u32_u24_e32 v0, 0x84, v0
	v_lshlrev_b32_e32 v2, 2, v8
	v_add3_u32 v12, s47, v0, v2
	s_waitcnt lgkmcnt(0)
	s_barrier
	ds_read2_b32 v[2:3], v12 offset0:33 offset1:37
	ds_read2_b32 v[4:5], v12 offset1:4
	v_lshlrev_b32_e32 v0, 1, v6
	v_lshl_add_u64 v[6:7], s[4:5], 0, v[0:1]
	v_or_b32_e32 v0, s20, v8
	v_lshlrev_b64 v[10:11], 11, v[0:1]
	s_waitcnt lgkmcnt(0)
	v_cvt_pk_bf16_f32 v2, v4, v2
	v_lshl_add_u64 v[10:11], v[6:7], 0, v[10:11]
	ds_read2_b32 v[8:9], v12 offset0:8 offset1:12
	global_store_dword v[10:11], v2, off
	v_or_b32_e32 v10, 4, v0
	v_mov_b32_e32 v11, v1
	v_cvt_pk_bf16_f32 v13, v5, v3
	ds_read2_b32 v[4:5], v12 offset0:41 offset1:45
	v_lshlrev_b64 v[2:3], 11, v[10:11]
	v_lshl_add_u64 v[2:3], v[6:7], 0, v[2:3]
	global_store_dword v[2:3], v13, off
	v_or_b32_e32 v2, 8, v0
	v_mov_b32_e32 v3, v1
	v_lshlrev_b64 v[2:3], 11, v[2:3]
	s_waitcnt lgkmcnt(0)
	v_cvt_pk_bf16_f32 v4, v8, v4
	v_lshl_add_u64 v[2:3], v[6:7], 0, v[2:3]
	global_store_dword v[2:3], v4, off
	v_or_b32_e32 v2, 12, v0
	v_mov_b32_e32 v3, v1
	v_cvt_pk_bf16_f32 v10, v9, v5
	ds_read2_b32 v[4:5], v12 offset0:16 offset1:20
	ds_read2_b32 v[8:9], v12 offset0:49 offset1:53
	v_lshlrev_b64 v[2:3], 11, v[2:3]
	v_lshl_add_u64 v[2:3], v[6:7], 0, v[2:3]
	global_store_dword v[2:3], v10, off
	v_or_b32_e32 v2, 16, v0
	v_mov_b32_e32 v3, v1
	v_lshlrev_b64 v[2:3], 11, v[2:3]
	s_waitcnt lgkmcnt(0)
	v_cvt_pk_bf16_f32 v4, v4, v8
	v_lshl_add_u64 v[2:3], v[6:7], 0, v[2:3]
	global_store_dword v[2:3], v4, off
	v_or_b32_e32 v2, 20, v0
	v_mov_b32_e32 v3, v1
	v_cvt_pk_bf16_f32 v10, v5, v9
	ds_read2_b32 v[4:5], v12 offset0:57 offset1:61
	ds_read2_b32 v[8:9], v12 offset0:24 offset1:28
	v_lshlrev_b64 v[2:3], 11, v[2:3]
	v_lshl_add_u64 v[2:3], v[6:7], 0, v[2:3]
	global_store_dword v[2:3], v10, off
	v_or_b32_e32 v2, 24, v0
	v_mov_b32_e32 v3, v1
	v_lshlrev_b64 v[2:3], 11, v[2:3]
	s_waitcnt lgkmcnt(0)
	v_cvt_pk_bf16_f32 v4, v8, v4
	v_lshl_add_u64 v[2:3], v[6:7], 0, v[2:3]
	v_or_b32_e32 v0, 28, v0
	global_store_dword v[2:3], v4, off
	v_lshlrev_b64 v[2:3], 11, v[0:1]
	v_cvt_pk_bf16_f32 v4, v9, v5
	v_lshl_add_u64 v[2:3], v[6:7], 0, v[2:3]
	global_store_dword v[2:3], v4, off
	s_barrier
	s_mov_b64 s[2:3], 0

.LBB0_809:
	s_lshl_b32 s74, s35, 3
	s_lshl_b32 s71, s34, 3
	v_or_b32_e32 v64, s74, v6
	v_or_b32_e32 v65, s71, v5
	v_mov_b32_e32 v67, v1
	v_add_lshl_u32 v66, v64, s3, 10
	v_mov_b32_e32 v69, v9
	v_add_lshl_u32 v68, v65, s36, 10
	v_lshl_add_u64 v[70:71], v[66:67], 2, v[2:3]
	v_mov_b32_e32 v72, v68
	v_mov_b32_e32 v73, v67
	v_lshl_add_u64 v[68:69], v[72:73], 2, v[2:3]
	v_mov_b32_e32 v73, v67
	global_load_dword v72, v[70:71], off
	global_load_dword v66, v[68:69], off
	v_mad_u64_u32 v[74:75], s[72:73], v64, s64, v[4:5]
	v_mad_u64_u32 v[68:69], s[72:73], v65, s64, v[4:5]
	s_add_i32 s73, s74, 16
	s_add_i32 s72, s71, 16
	v_or_b32_e32 v67, s73, v6
	v_or_b32_e32 v64, s72, v5
	v_mov_b32_e32 v70, v74
	v_mov_b32_e32 v71, v73
	s_add_i32 s35, s35, 8
	s_add_i32 s34, s34, 8
	s_add_i32 s37, s37, -8
	v_mov_b32_e32 v75, v73
	v_add_lshl_u32 v74, v67, s3, 10
	v_mov_b32_e32 v77, v71
	v_add_lshl_u32 v76, v64, s36, 10
	v_lshl_add_u64 v[78:79], v[74:75], 2, v[2:3]
	v_lshl_add_u64 v[80:81], v[76:77], 2, v[2:3]
	v_mov_b32_e32 v77, v75
	global_load_dword v76, v[78:79], off
	global_load_dword v65, v[80:81], off
	v_mad_u64_u32 v[74:75], s[72:73], v67, s64, v[4:5]
	v_mad_u64_u32 v[80:81], s[72:73], v64, s64, v[4:5]
	s_add_i32 s73, s74, 32
	s_add_i32 s72, s71, 32
	v_or_b32_e32 v69, s73, v6
	v_or_b32_e32 v67, s72, v5
	v_mov_b32_e32 v78, v74
	v_mov_b32_e32 v79, v77
	s_add_i32 s74, s74, 48
	s_add_i32 s71, s71, 48
	s_cmp_lg_u32 s37, 0
	v_mov_b32_e32 v75, v77
	v_add_lshl_u32 v74, v69, s3, 10
	v_mov_b32_e32 v83, v79
	v_add_lshl_u32 v82, v67, s36, 10
	v_lshl_add_u64 v[84:85], v[74:75], 2, v[2:3]
	v_lshl_add_u64 v[86:87], v[82:83], 2, v[2:3]
	v_mov_b32_e32 v83, v75
	global_load_dword v82, v[84:85], off
	global_load_dword v64, v[86:87], off
	v_mad_u64_u32 v[74:75], s[72:73], v69, s64, v[4:5]
	v_or_b32_e32 v71, s74, v6
	v_mad_u64_u32 v[86:87], s[72:73], v67, s64, v[4:5]
	v_or_b32_e32 v69, s71, v5
	v_mov_b32_e32 v84, v74
	v_mov_b32_e32 v85, v83
	v_mov_b32_e32 v75, v83
	v_add_lshl_u32 v74, v71, s3, 10
	v_mov_b32_e32 v89, v85
	v_add_lshl_u32 v88, v69, s36, 10
	v_lshl_add_u64 v[90:91], v[74:75], 2, v[2:3]
	v_lshl_add_u64 v[92:93], v[88:89], 2, v[2:3]
	v_mov_b32_e32 v89, v75
	global_load_dword v88, v[90:91], off
	global_load_dword v67, v[92:93], off
	v_mad_u64_u32 v[74:75], s[72:73], v71, s64, v[4:5]
	v_mad_u64_u32 v[92:93], s[72:73], v69, s64, v[4:5]
	s_lshl_b32 s74, s35, 3
	s_lshl_b32 s71, s34, 3
	v_or_b32_e32 v73, s74, v6
	v_or_b32_e32 v71, s71, v5
	v_mov_b32_e32 v91, v89
	v_add_lshl_u32 v90, v73, s3, 10
	v_mov_b32_e32 v95, v75
	v_add_lshl_u32 v94, v71, s36, 10
	v_lshl_add_u64 v[96:97], v[90:91], 2, v[2:3]
	v_mov_b32_e32 v98, v94
	v_mov_b32_e32 v99, v91
	v_lshl_add_u64 v[94:95], v[98:99], 2, v[2:3]
	v_mov_b32_e32 v99, v91
	global_load_dword v98, v[96:97], off
	global_load_dword v69, v[94:95], off
	v_mad_u64_u32 v[90:91], s[72:73], v73, s64, v[4:5]
	v_mad_u64_u32 v[94:95], s[72:73], v71, s64, v[4:5]
	s_add_i32 s73, s74, 16
	s_add_i32 s72, s71, 16
	v_or_b32_e32 v75, s73, v6
	v_or_b32_e32 v73, s72, v5
	v_mov_b32_e32 v96, v90
	v_mov_b32_e32 v97, v99
	s_add_i32 s35, s35, 8
	s_add_i32 s34, s34, 8
	s_add_i32 s37, s37, -8
	v_mov_b32_e32 v91, v99
	v_add_lshl_u32 v90, v75, s3, 10
	v_mov_b32_e32 v101, v97
	v_add_lshl_u32 v100, v73, s36, 10
	v_lshl_add_u64 v[102:103], v[90:91], 2, v[2:3]
	v_lshl_add_u64 v[104:105], v[100:101], 2, v[2:3]
	v_mov_b32_e32 v101, v91
	global_load_dword v100, v[102:103], off
	global_load_dword v71, v[104:105], off
	v_mad_u64_u32 v[90:91], s[72:73], v75, s64, v[4:5]
	v_mad_u64_u32 v[104:105], s[72:73], v73, s64, v[4:5]
	s_add_i32 s73, s74, 32
	s_add_i32 s72, s71, 32
	v_or_b32_e32 v77, s73, v6
	v_or_b32_e32 v75, s72, v5
	v_mov_b32_e32 v102, v90
	v_mov_b32_e32 v103, v101
	s_add_i32 s74, s74, 48
	s_add_i32 s71, s71, 48
	s_cmp_lg_u32 s37, 0
	v_mov_b32_e32 v91, v101
	v_add_lshl_u32 v90, v77, s3, 10
	v_mov_b32_e32 v107, v103
	v_add_lshl_u32 v106, v75, s36, 10
	v_lshl_add_u64 v[108:109], v[90:91], 2, v[2:3]
	v_lshl_add_u64 v[110:111], v[106:107], 2, v[2:3]
	v_mov_b32_e32 v107, v91
	global_load_dword v106, v[108:109], off
	global_load_dword v73, v[110:111], off
	v_mad_u64_u32 v[90:91], s[72:73], v77, s64, v[4:5]
	v_or_b32_e32 v79, s74, v6
	v_mad_u64_u32 v[110:111], s[72:73], v75, s64, v[4:5]
	v_or_b32_e32 v77, s71, v5
	v_mov_b32_e32 v108, v90
	v_mov_b32_e32 v109, v107
	v_mov_b32_e32 v91, v107
	v_add_lshl_u32 v90, v79, s3, 10
	v_mov_b32_e32 v113, v109
	v_add_lshl_u32 v112, v77, s36, 10
	v_lshl_add_u64 v[114:115], v[90:91], 2, v[2:3]
	v_lshl_add_u64 v[116:117], v[112:113], 2, v[2:3]
	v_mov_b32_e32 v113, v91
	global_load_dword v112, v[114:115], off
	global_load_dword v75, v[116:117], off
	v_mad_u64_u32 v[90:91], s[72:73], v79, s64, v[4:5]
	v_mad_u64_u32 v[116:117], s[72:73], v77, s64, v[4:5]
	s_waitcnt vmcnt(15)
	ds_write_b32 v70, v72
	s_waitcnt vmcnt(14)
	ds_write_b32 v68, v66
	s_waitcnt vmcnt(13)
	ds_write_b32 v78, v76
	s_waitcnt vmcnt(12)
	ds_write_b32 v80, v65
	s_waitcnt vmcnt(11)
	ds_write_b32 v84, v82
	s_waitcnt vmcnt(10)
	ds_write_b32 v86, v64
	s_waitcnt vmcnt(9)
	ds_write_b32 v74, v88
	s_waitcnt vmcnt(8)
	ds_write_b32 v92, v67
	s_waitcnt vmcnt(7)
	ds_write_b32 v96, v98
	s_waitcnt vmcnt(6)
	ds_write_b32 v94, v69
	s_waitcnt vmcnt(5)
	ds_write_b32 v102, v100
	s_waitcnt vmcnt(4)
	ds_write_b32 v104, v71
	s_waitcnt vmcnt(3)
	ds_write_b32 v108, v106
	s_waitcnt vmcnt(2)
	ds_write_b32 v110, v73
	s_waitcnt vmcnt(1)
	ds_write_b32 v90, v112
	s_waitcnt vmcnt(0)
	ds_write_b32 v116, v75
	v_mov_b32_e32 v0, v112
	v_mov_b32_e32 v1, v113
	v_mov_b32_e32 v8, v90
	v_mov_b32_e32 v9, v91
	v_mov_b32_e32 v10, v116
	v_mov_b32_e32 v11, v117
	v_mov_b32_e32 v12, v77
	v_mov_b32_e32 v13, v79
	v_mov_b32_e32 v18, v75
	v_lshlrev_b32_sdwa v0, v14, v7 dst_sel:DWORD dst_unused:UNUSED_PAD src0_sel:DWORD src1_sel:BYTE_0
	v_and_b32_e32 v0, 0x7e, v0
	v_lshrrev_b32_sdwa v2, v15, v7 dst_sel:DWORD dst_unused:UNUSED_PAD src0_sel:DWORD src1_sel:BYTE_0
	v_or_b32_e32 v12, s2, v2
	v_or_b32_e32 v6, s3, v0
	v_mul_u32_u24_e32 v0, 0x84, v0
	v_lshlrev_b32_e32 v2, 2, v2
	v_add3_u32 v22, s47, v0, v2
	s_waitcnt lgkmcnt(0)
	s_barrier
	ds_read2_b32 v[2:3], v22 offset0:33 offset1:37
	ds_read2_b32 v[4:5], v22 offset1:4
	s_lshl_b64 s[34:35], s[20:21], 20
	s_add_u32 s34, s41, s34
	s_addc_u32 s35, s42, s35
	v_lshlrev_b32_e32 v0, 1, v6
	v_lshl_add_u64 v[6:7], s[34:35], 0, v[0:1]
	ds_read2_b32 v[8:9], v22 offset0:8 offset1:12
	ds_read2_b32 v[10:11], v22 offset0:41 offset1:45
	v_lshlrev_b32_e32 v0, 10, v12
	s_waitcnt lgkmcnt(2)
	v_cvt_pk_bf16_f32 v2, v4, v2
	v_lshl_add_u64 v[6:7], v[6:7], 0, v[0:1]
	global_store_dword v[6:7], v2, off
	ds_read2_b32 v[12:13], v22 offset0:16 offset1:20
	ds_read2_b32 v[18:19], v22 offset0:49 offset1:53
	ds_read2_b32 v[20:21], v22 offset0:24 offset1:28
	ds_read2_b32 v[22:23], v22 offset0:57 offset1:61
	s_movk_i32 s2, 0x2000
	v_add_co_u32_e32 v24, vcc, s2, v6
	s_waitcnt lgkmcnt(4)
	v_cvt_pk_bf16_f32 v0, v8, v10
	v_addc_co_u32_e32 v25, vcc, 0, v7, vcc
	global_store_dword v[24:25], v0, off offset:-4096
	s_waitcnt lgkmcnt(2)
	v_cvt_pk_bf16_f32 v0, v12, v18
	s_movk_i32 s2, 0x4000
	global_store_dword v[24:25], v0, off
	v_add_co_u32_e32 v24, vcc, s2, v6
	s_waitcnt lgkmcnt(0)
	v_cvt_pk_bf16_f32 v0, v20, v22
	v_addc_co_u32_e32 v25, vcc, 0, v7, vcc
	s_movk_i32 s2, 0x5000
	global_store_dword v[24:25], v0, off offset:-4096
	v_cvt_pk_bf16_f32 v0, v5, v3
	v_add_co_u32_e32 v2, vcc, s2, v6
	global_store_dword v[24:25], v0, off
	v_cvt_pk_bf16_f32 v0, v9, v11
	v_addc_co_u32_e32 v3, vcc, 0, v7, vcc
	global_store_dword v[2:3], v0, off
	v_add_co_u32_e32 v2, vcc, 0x6000, v6
	v_cvt_pk_bf16_f32 v0, v13, v19
	s_nop 0
	v_addc_co_u32_e32 v3, vcc, 0, v7, vcc
	global_store_dword v[2:3], v0, off
	v_add_co_u32_e32 v2, vcc, 0x7000, v6
	v_cvt_pk_bf16_f32 v0, v21, v23
	s_nop 0
	v_addc_co_u32_e32 v3, vcc, 0, v7, vcc
	global_store_dword v[2:3], v0, off
	s_barrier

.LBB0_812:
	s_andn2_b64 vcc, exec, s[2:3]
	s_cbranch_vccnz .LBB0_824
	s_bfe_u32 s20, s51, 0x1a0005
	v_mov_b32_e32 v18, v198
	s_lshl_b64 s[2:3], s[20:21], 7
	s_bfe_u32 s20, s59, 0x10007
	v_mov_b32_e32 v5, v1
	v_bfe_u32 v10, v18, 5, 3
	v_lshlrev_b32_e32 v2, 2, v18
	v_lshl_or_b32 v8, s20, 7, v10
	v_mul_u32_u24_e32 v0, 0x84, v10
	v_and_b32_e32 v12, 0x7c, v2
	v_lshlrev_b32_e32 v6, 12, v8
	v_add3_u32 v19, v0, v12, s47
	v_or_b32_e32 v0, 0x18000, v6
	v_lshl_add_u64 v[2:3], s[2:3], 0, v[0:1]
	v_lshlrev_b32_e32 v0, 2, v10
	v_lshlrev_b32_e32 v10, 12, v10
	v_or_b32_e32 v4, 0x10000, v6
	v_or_b32_e32 v6, 0x8000, v6
	v_mov_b32_e32 v7, v1
	v_lshl_or_b32 v10, s20, 19, v10
	v_mov_b32_e32 v11, v1
	v_lshl_add_u64 v[4:5], s[2:3], 0, v[4:5]
	v_lshl_add_u64 v[6:7], s[2:3], 0, v[6:7]
	v_lshl_add_u64 v[10:11], s[2:3], 0, v[10:11]
	v_readlane_b32 s88, v240, 2
	v_or_b32_e32 v2, v2, v12
	v_or_b32_e32 v4, v4, v12
	v_or_b32_e32 v6, v6, v12
	v_or_b32_e32 v10, v10, v12
	v_readlane_b32 s92, v240, 6
	v_readlane_b32 s93, v240, 7
	v_lshl_add_u64 v[2:3], s[22:23], 0, v[2:3]
	v_lshl_or_b32 v0, s20, 9, v0
	v_lshl_add_u64 v[4:5], s[22:23], 0, v[4:5]
	v_lshl_add_u64 v[6:7], s[22:23], 0, v[6:7]
	v_lshl_or_b32 v8, v8, 2, v16
	v_mov_b32_e32 v9, v1
	v_lshl_add_u64 v[10:11], s[22:23], 0, v[10:11]
	s_mov_b64 s[34:35], 0
	s_mov_b64 s[36:37], s[92:93]
	v_readlane_b32 s89, v240, 3
	v_readlane_b32 s90, v240, 4
	v_readlane_b32 s91, v240, 5
	v_readlane_b32 s94, v240, 8
	v_readlane_b32 s95, v240, 9
	s_andn2_b64 vcc, exec, s[6:7]
	s_cbranch_vccnz .LBB0_815
	v_lshl_add_u64 v[64:65], v[10:11], 0, s[34:35]
	v_mov_b32_e32 v67, v65
	global_load_dword v66, v[64:65], off
	v_cndmask_b32_e64 v64, 0, 1, s[6:7]
	v_cmp_ne_u32_e64 s[2:3], 1, v64
	s_andn2_b64 vcc, exec, s[6:7]
	v_lshl_add_u64 v[68:69], s[36:37], 0, v[8:9]
	global_load_dword v65, v[68:69], off
	v_lshl_add_u64 v[70:71], v[6:7], 0, s[34:35]
	v_mov_b32_e32 v73, v69
	global_load_dword v72, v[70:71], off
	s_and_b64 vcc, exec, s[2:3]
	v_lshl_add_u64 v[68:69], s[36:37], 0, v[0:1]
	global_load_dword v64, v[68:69], off offset:1056
	v_lshl_add_u64 v[70:71], v[4:5], 0, s[34:35]
	v_mov_b32_e32 v75, v71
	global_load_dword v74, v[70:71], off
	s_and_b64 vcc, exec, s[2:3]
	global_load_dword v67, v[68:69], off offset:1088
	v_lshl_add_u64 v[70:71], v[2:3], 0, s[34:35]
	v_mov_b32_e32 v77, v71
	global_load_dword v76, v[70:71], off
	s_and_b64 vcc, exec, s[2:3]
	v_mov_b32_e32 v71, v69
	global_load_dword v70, v[68:69], off offset:1120
	s_add_u32 s34, s34, 0x20000
	s_addc_u32 s35, s35, 0
	s_add_u32 s36, s36, 0x80
	s_addc_u32 s37, s37, 0
	s_cmp_lg_u32 s34, 0x80000
	v_add_u32_e32 v68, 0x1080, v19
	v_lshl_add_u64 v[78:79], v[10:11], 0, s[34:35]
	v_mov_b32_e32 v81, v79
	global_load_dword v80, v[78:79], off
	v_cndmask_b32_e64 v69, 0, 1, s[6:7]
	v_cmp_ne_u32_e64 s[2:3], 1, v69
	s_andn2_b64 vcc, exec, s[6:7]
	v_lshl_add_u64 v[78:79], s[36:37], 0, v[8:9]
	global_load_dword v71, v[78:79], off
	v_lshl_add_u64 v[82:83], v[6:7], 0, s[34:35]
	v_mov_b32_e32 v85, v79
	global_load_dword v84, v[82:83], off
	s_and_b64 vcc, exec, s[2:3]
	v_lshl_add_u64 v[78:79], s[36:37], 0, v[0:1]
	global_load_dword v69, v[78:79], off offset:1056
	v_lshl_add_u64 v[82:83], v[4:5], 0, s[34:35]
	v_mov_b32_e32 v87, v83
	global_load_dword v86, v[82:83], off
	s_and_b64 vcc, exec, s[2:3]
	global_load_dword v73, v[78:79], off offset:1088
	v_lshl_add_u64 v[82:83], v[2:3], 0, s[34:35]
	v_mov_b32_e32 v89, v83
	global_load_dword v88, v[82:83], off
	s_and_b64 vcc, exec, s[2:3]
	v_mov_b32_e32 v83, v79
	global_load_dword v82, v[78:79], off offset:1120
	s_add_u32 s34, s34, 0x20000
	s_addc_u32 s35, s35, 0
	s_add_u32 s36, s36, 0x80
	s_addc_u32 s37, s37, 0
	s_cmp_lg_u32 s34, 0x80000
	v_add_u32_e32 v75, 0x1080, v68
	v_lshl_add_u64 v[78:79], v[10:11], 0, s[34:35]
	v_mov_b32_e32 v91, v79
	global_load_dword v90, v[78:79], off
	v_cndmask_b32_e64 v77, 0, 1, s[6:7]
	v_cmp_ne_u32_e64 s[2:3], 1, v77
	s_andn2_b64 vcc, exec, s[6:7]
	v_lshl_add_u64 v[78:79], s[36:37], 0, v[8:9]
	global_load_dword v81, v[78:79], off
	v_lshl_add_u64 v[92:93], v[6:7], 0, s[34:35]
	v_mov_b32_e32 v95, v79
	global_load_dword v94, v[92:93], off
	s_and_b64 vcc, exec, s[2:3]
	v_lshl_add_u64 v[78:79], s[36:37], 0, v[0:1]
	global_load_dword v77, v[78:79], off offset:1056
	v_lshl_add_u64 v[92:93], v[4:5], 0, s[34:35]
	v_mov_b32_e32 v97, v93
	global_load_dword v96, v[92:93], off
	s_and_b64 vcc, exec, s[2:3]
	global_load_dword v83, v[78:79], off offset:1088
	v_lshl_add_u64 v[92:93], v[2:3], 0, s[34:35]
	v_mov_b32_e32 v99, v93
	global_load_dword v98, v[92:93], off
	s_and_b64 vcc, exec, s[2:3]
	v_mov_b32_e32 v93, v79
	global_load_dword v92, v[78:79], off offset:1120
	s_add_u32 s34, s34, 0x20000
	s_addc_u32 s35, s35, 0
	s_add_u32 s36, s36, 0x80
	s_addc_u32 s37, s37, 0
	s_cmp_lg_u32 s34, 0x80000
	v_add_u32_e32 v78, 0x1080, v75
	v_lshl_add_u64 v[100:101], v[10:11], 0, s[34:35]
	v_mov_b32_e32 v103, v101
	global_load_dword v102, v[100:101], off
	v_cndmask_b32_e64 v79, 0, 1, s[6:7]
	v_cmp_ne_u32_e64 s[2:3], 1, v79
	s_andn2_b64 vcc, exec, s[6:7]
	v_lshl_add_u64 v[100:101], s[36:37], 0, v[8:9]
	global_load_dword v85, v[100:101], off
	v_lshl_add_u64 v[104:105], v[6:7], 0, s[34:35]
	v_mov_b32_e32 v107, v101
	global_load_dword v106, v[104:105], off
	s_and_b64 vcc, exec, s[2:3]
	v_lshl_add_u64 v[100:101], s[36:37], 0, v[0:1]
	global_load_dword v79, v[100:101], off offset:1056
	v_lshl_add_u64 v[104:105], v[4:5], 0, s[34:35]
	v_mov_b32_e32 v109, v105
	global_load_dword v108, v[104:105], off
	s_and_b64 vcc, exec, s[2:3]
	global_load_dword v87, v[100:101], off offset:1088
	v_lshl_add_u64 v[104:105], v[2:3], 0, s[34:35]
	v_mov_b32_e32 v111, v105
	global_load_dword v110, v[104:105], off
	s_and_b64 vcc, exec, s[2:3]
	v_mov_b32_e32 v105, v101
	global_load_dword v104, v[100:101], off offset:1120
	s_add_u32 s34, s34, 0x20000
	s_addc_u32 s35, s35, 0
	s_add_u32 s36, s36, 0x80
	s_addc_u32 s37, s37, 0
	s_cmp_lg_u32 s34, 0x80000
	v_add_u32_e32 v89, 0x1080, v78
	s_waitcnt vmcnt(30)
	v_mul_f32_e32 v66, v66, v65
	ds_write_b32 v19, v66
	s_waitcnt vmcnt(28)
	v_mul_f32_e32 v72, v72, v64
	ds_write_b32 v19, v72 offset:1056
	s_waitcnt vmcnt(26)
	v_mul_f32_e32 v74, v74, v67
	ds_write_b32 v19, v74 offset:2112
	s_waitcnt vmcnt(24)
	v_mul_f32_e32 v76, v76, v70
	ds_write_b32 v19, v76 offset:3168
	s_waitcnt vmcnt(22)
	v_mul_f32_e32 v80, v80, v71
	ds_write_b32 v68, v80
	s_waitcnt vmcnt(20)
	v_mul_f32_e32 v84, v84, v69
	ds_write_b32 v68, v84 offset:1056
	s_waitcnt vmcnt(18)
	v_mul_f32_e32 v86, v86, v73
	ds_write_b32 v68, v86 offset:2112
	s_waitcnt vmcnt(16)
	v_mul_f32_e32 v88, v88, v82
	ds_write_b32 v68, v88 offset:3168
	s_waitcnt vmcnt(14)
	v_mul_f32_e32 v90, v90, v81
	ds_write_b32 v75, v90
	s_waitcnt vmcnt(12)
	v_mul_f32_e32 v94, v94, v77
	ds_write_b32 v75, v94 offset:1056
	s_waitcnt vmcnt(10)
	v_mul_f32_e32 v96, v96, v83
	ds_write_b32 v75, v96 offset:2112
	s_waitcnt vmcnt(8)
	v_mul_f32_e32 v98, v98, v92
	ds_write_b32 v75, v98 offset:3168
	s_waitcnt vmcnt(6)
	v_mul_f32_e32 v102, v102, v85
	ds_write_b32 v78, v102
	s_waitcnt vmcnt(4)
	v_mul_f32_e32 v106, v106, v79
	ds_write_b32 v78, v106 offset:1056
	s_waitcnt vmcnt(2)
	v_mul_f32_e32 v108, v108, v87
	ds_write_b32 v78, v108 offset:2112
	s_waitcnt vmcnt(0)
	v_mul_f32_e32 v110, v110, v104
	ds_write_b32 v78, v110 offset:3168
	v_mov_b32_e32 v12, v104
	v_mov_b32_e32 v13, v105
	v_mov_b32_e32 v19, v89
	v_mov_b32_e32 v20, v110
	v_mov_b32_e32 v21, v111
	s_branch .LBB0_823

.LBB0_830:
	s_mul_i32 s2, s71, 6
	s_sub_i32 s2, s34, s2
	s_and_b32 s2, s2, 0xff
	s_lshl_b32 s36, s2, 7
	s_lshl_b64 s[2:3], s[20:21], 2
	s_add_u32 s34, s43, s2
	s_addc_u32 s35, s46, s3
	s_cmpk_gt_u32 s37, 0x59
	s_mov_b64 s[2:3], -1
	s_mul_i32 s20, s71, 48
	s_cbranch_scc0 .LBB0_842
	v_mov_b32_e32 v6, v198
	s_mul_hi_u32 s2, s37, 0x2aaaaaab
	v_bfe_u32 v4, v6, 5, 3
	v_lshlrev_b32_e32 v0, 2, v6
	v_and_b32_e32 v0, 0x7c, v0
	v_mul_u32_u24_e32 v5, 0x84, v4
	v_lshl_add_u64 v[2:3], s[34:35], 0, v[0:1]
	v_add3_u32 v7, v5, v0, s47
	v_lshl_or_b32 v0, s37, 7, v4
	s_mulk_i32 s2, 0x300
	v_subrev_u32_e32 v8, s2, v0
	v_add_lshl_u32 v0, v4, s36, 2
	v_lshl_add_u64 v[4:5], s[24:25], 0, v[0:1]
	s_mov_b32 s71, 0
	s_andn2_b64 vcc, exec, s[10:11]
	s_cbranch_vccnz .LBB0_833
	v_mov_b32_e32 v65, v1
	v_add_u32_e32 v64, s71, v8
	v_mad_u64_u32 v[66:67], s[2:3], v64, s66, v[2:3]
	global_load_dword v68, v[66:67], off
	v_mov_b32_e32 v71, v67
	v_cndmask_b32_e64 v70, 0, 1, s[10:11]
	v_cmp_ne_u32_e64 s[2:3], 1, v70
	s_andn2_b64 vcc, exec, s[10:11]
	v_readlane_b32 s88, v240, 2
	v_readlane_b32 s89, v240, 3
	v_readlane_b32 s90, v240, 4
	v_readlane_b32 s91, v240, 5
	v_lshl_add_u64 v[66:67], v[64:65], 2, s[88:89]
	v_mov_b32_e32 v71, v67
	global_load_dword v70, v[66:67], off offset:3072
	v_readlane_b32 s92, v240, 6
	v_readlane_b32 s93, v240, 7
	v_readlane_b32 s94, v240, 8
	v_readlane_b32 s95, v240, 9
	v_add_u32_e32 v66, 8, v64
	v_mad_u64_u32 v[72:73], s[72:73], v66, s66, v[2:3]
	global_load_dword v67, v[72:73], off
	s_and_b64 vcc, exec, s[2:3]
	v_mov_b32_e32 v75, v73
	global_load_dword v74, v[4:5], off offset:-64
	v_add_u32_e32 v66, 16, v64
	v_mad_u64_u32 v[72:73], s[72:73], v66, s66, v[2:3]
	global_load_dword v69, v[72:73], off
	s_and_b64 vcc, exec, s[2:3]
	v_mov_b32_e32 v77, v73
	global_load_dword v76, v[4:5], off offset:-32
	v_mov_b32_e32 v73, v65
	v_add_u32_e32 v72, 24, v64
	v_mad_u64_u32 v[64:65], s[72:73], v72, s66, v[2:3]
	v_mov_b32_e32 v79, v73
	global_load_dword v78, v[64:65], off
	s_and_b64 vcc, exec, s[2:3]
	global_load_dword v66, v[4:5], off
	s_add_i32 s71, s71, 32
	v_add_u32_e32 v71, 0x1080, v7
	s_cmpk_lg_i32 s71, 0x80
	v_lshl_add_u64 v[72:73], v[4:5], 0, s[26:27]
	v_mov_b32_e32 v81, v79
	v_add_u32_e32 v80, s71, v8
	v_mad_u64_u32 v[82:83], s[2:3], v80, s66, v[2:3]
	global_load_dword v64, v[82:83], off
	v_mov_b32_e32 v85, v83
	v_cndmask_b32_e64 v84, 0, 1, s[10:11]
	v_cmp_ne_u32_e64 s[2:3], 1, v84
	s_andn2_b64 vcc, exec, s[10:11]
	v_readlane_b32 s88, v240, 2
	v_readlane_b32 s89, v240, 3
	v_readlane_b32 s90, v240, 4
	v_readlane_b32 s91, v240, 5
	v_lshl_add_u64 v[82:83], v[80:81], 2, s[88:89]
	v_mov_b32_e32 v85, v83
	global_load_dword v84, v[82:83], off offset:3072
	v_readlane_b32 s92, v240, 6
	v_readlane_b32 s93, v240, 7
	v_readlane_b32 s94, v240, 8
	v_readlane_b32 s95, v240, 9
	v_add_u32_e32 v65, 8, v80
	v_mad_u64_u32 v[82:83], s[72:73], v65, s66, v[2:3]
	global_load_dword v75, v[82:83], off
	s_and_b64 vcc, exec, s[2:3]
	v_mov_b32_e32 v87, v83
	global_load_dword v86, v[72:73], off offset:-64
	v_add_u32_e32 v65, 16, v80
	v_mad_u64_u32 v[82:83], s[72:73], v65, s66, v[2:3]
	global_load_dword v77, v[82:83], off
	s_and_b64 vcc, exec, s[2:3]
	v_mov_b32_e32 v89, v83
	global_load_dword v88, v[72:73], off offset:-32
	v_mov_b32_e32 v83, v81
	v_add_u32_e32 v82, 24, v80
	v_mad_u64_u32 v[80:81], s[72:73], v82, s66, v[2:3]
	v_mov_b32_e32 v91, v83
	global_load_dword v90, v[80:81], off
	s_and_b64 vcc, exec, s[2:3]
	global_load_dword v65, v[72:73], off
	s_add_i32 s71, s71, 32
	v_add_u32_e32 v79, 0x1080, v71
	s_cmpk_lg_i32 s71, 0x80
	v_lshl_add_u64 v[82:83], v[72:73], 0, s[26:27]
	v_mov_b32_e32 v73, v91
	v_add_u32_e32 v72, s71, v8
	v_mad_u64_u32 v[92:93], s[2:3], v72, s66, v[2:3]
	global_load_dword v80, v[92:93], off
	v_mov_b32_e32 v95, v93
	v_cndmask_b32_e64 v94, 0, 1, s[10:11]
	v_cmp_ne_u32_e64 s[2:3], 1, v94
	s_andn2_b64 vcc, exec, s[10:11]
	v_readlane_b32 s88, v240, 2
	v_readlane_b32 s89, v240, 3
	v_readlane_b32 s90, v240, 4
	v_readlane_b32 s91, v240, 5
	v_lshl_add_u64 v[92:93], v[72:73], 2, s[88:89]
	v_mov_b32_e32 v95, v93
	global_load_dword v94, v[92:93], off offset:3072
	v_readlane_b32 s92, v240, 6
	v_readlane_b32 s93, v240, 7
	v_readlane_b32 s94, v240, 8
	v_readlane_b32 s95, v240, 9
	v_add_u32_e32 v81, 8, v72
	v_mad_u64_u32 v[92:93], s[72:73], v81, s66, v[2:3]
	global_load_dword v85, v[92:93], off
	s_and_b64 vcc, exec, s[2:3]
	v_mov_b32_e32 v97, v93
	global_load_dword v96, v[82:83], off offset:-64
	v_add_u32_e32 v81, 16, v72
	v_mad_u64_u32 v[92:93], s[72:73], v81, s66, v[2:3]
	global_load_dword v87, v[92:93], off
	s_and_b64 vcc, exec, s[2:3]
	v_mov_b32_e32 v99, v93
	global_load_dword v98, v[82:83], off offset:-32
	v_mov_b32_e32 v93, v73
	v_add_u32_e32 v92, 24, v72
	v_mad_u64_u32 v[72:73], s[72:73], v92, s66, v[2:3]
	v_mov_b32_e32 v101, v93
	global_load_dword v100, v[72:73], off
	s_and_b64 vcc, exec, s[2:3]
	global_load_dword v81, v[82:83], off
	s_add_i32 s71, s71, 32
	v_add_u32_e32 v89, 0x1080, v79
	s_cmpk_lg_i32 s71, 0x80
	v_lshl_add_u64 v[92:93], v[82:83], 0, s[26:27]
	v_mov_b32_e32 v83, v101
	v_add_u32_e32 v82, s71, v8
	v_mad_u64_u32 v[102:103], s[2:3], v82, s66, v[2:3]
	global_load_dword v72, v[102:103], off
	v_mov_b32_e32 v105, v103
	v_cndmask_b32_e64 v104, 0, 1, s[10:11]
	v_cmp_ne_u32_e64 s[2:3], 1, v104
	s_andn2_b64 vcc, exec, s[10:11]
	v_readlane_b32 s88, v240, 2
	v_readlane_b32 s89, v240, 3
	v_readlane_b32 s90, v240, 4
	v_readlane_b32 s91, v240, 5
	v_lshl_add_u64 v[102:103], v[82:83], 2, s[88:89]
	v_mov_b32_e32 v105, v103
	global_load_dword v104, v[102:103], off offset:3072
	v_readlane_b32 s92, v240, 6
	v_readlane_b32 s93, v240, 7
	v_readlane_b32 s94, v240, 8
	v_readlane_b32 s95, v240, 9
	v_add_u32_e32 v73, 8, v82
	v_mad_u64_u32 v[102:103], s[72:73], v73, s66, v[2:3]
	global_load_dword v91, v[102:103], off
	s_and_b64 vcc, exec, s[2:3]
	v_mov_b32_e32 v107, v103
	global_load_dword v106, v[92:93], off offset:-64
	v_add_u32_e32 v73, 16, v82
	v_mad_u64_u32 v[102:103], s[72:73], v73, s66, v[2:3]
	global_load_dword v95, v[102:103], off
	s_and_b64 vcc, exec, s[2:3]
	v_mov_b32_e32 v109, v103
	global_load_dword v108, v[92:93], off offset:-32
	v_mov_b32_e32 v103, v83
	v_add_u32_e32 v102, 24, v82
	v_mad_u64_u32 v[82:83], s[72:73], v102, s66, v[2:3]
	v_mov_b32_e32 v111, v103
	global_load_dword v110, v[82:83], off
	s_and_b64 vcc, exec, s[2:3]
	global_load_dword v73, v[92:93], off
	s_add_i32 s71, s71, 32
	v_add_u32_e32 v97, 0x1080, v89
	s_cmpk_lg_i32 s71, 0x80
	v_lshl_add_u64 v[102:103], v[92:93], 0, s[26:27]
	s_waitcnt vmcnt(30)
	v_mul_f32_e32 v68, v68, v70
	v_mul_f32_e32 v68, 0x3e16c740, v68
	ds_write_b32 v7, v68
	s_waitcnt vmcnt(28)
	v_mul_f32_e32 v67, v67, v74
	v_mul_f32_e32 v67, 0x3e16c740, v67
	ds_write_b32 v7, v67 offset:1056
	s_waitcnt vmcnt(26)
	v_mul_f32_e32 v69, v69, v76
	v_mul_f32_e32 v69, 0x3e16c740, v69
	ds_write_b32 v7, v69 offset:2112
	s_waitcnt vmcnt(24)
	v_mul_f32_e32 v78, v78, v66
	v_mul_f32_e32 v78, 0x3e16c740, v78
	ds_write_b32 v7, v78 offset:3168
	s_waitcnt vmcnt(22)
	v_mul_f32_e32 v64, v64, v84
	v_mul_f32_e32 v64, 0x3e16c740, v64
	ds_write_b32 v71, v64
	s_waitcnt vmcnt(20)
	v_mul_f32_e32 v75, v75, v86
	v_mul_f32_e32 v75, 0x3e16c740, v75
	ds_write_b32 v71, v75 offset:1056
	s_waitcnt vmcnt(18)
	v_mul_f32_e32 v77, v77, v88
	v_mul_f32_e32 v77, 0x3e16c740, v77
	ds_write_b32 v71, v77 offset:2112
	s_waitcnt vmcnt(16)
	v_mul_f32_e32 v90, v90, v65
	v_mul_f32_e32 v90, 0x3e16c740, v90
	ds_write_b32 v71, v90 offset:3168
	s_waitcnt vmcnt(14)
	v_mul_f32_e32 v80, v80, v94
	v_mul_f32_e32 v80, 0x3e16c740, v80
	ds_write_b32 v79, v80
	s_waitcnt vmcnt(12)
	v_mul_f32_e32 v85, v85, v96
	v_mul_f32_e32 v85, 0x3e16c740, v85
	ds_write_b32 v79, v85 offset:1056
	s_waitcnt vmcnt(10)
	v_mul_f32_e32 v87, v87, v98
	v_mul_f32_e32 v87, 0x3e16c740, v87
	ds_write_b32 v79, v87 offset:2112
	s_waitcnt vmcnt(8)
	v_mul_f32_e32 v100, v100, v81
	v_mul_f32_e32 v100, 0x3e16c740, v100
	ds_write_b32 v79, v100 offset:3168
	s_waitcnt vmcnt(6)
	v_mul_f32_e32 v72, v72, v104
	v_mul_f32_e32 v72, 0x3e16c740, v72
	ds_write_b32 v89, v72
	s_waitcnt vmcnt(4)
	v_mul_f32_e32 v91, v91, v106
	v_mul_f32_e32 v91, 0x3e16c740, v91
	ds_write_b32 v89, v91 offset:1056
	s_waitcnt vmcnt(2)
	v_mul_f32_e32 v95, v95, v108
	v_mul_f32_e32 v95, 0x3e16c740, v95
	ds_write_b32 v89, v95 offset:2112
	s_waitcnt vmcnt(0)
	v_mul_f32_e32 v110, v110, v73
	v_mul_f32_e32 v110, 0x3e16c740, v110
	ds_write_b32 v89, v110 offset:3168
	v_mov_b32_e32 v0, v110
	v_mov_b32_e32 v1, v111
	v_mov_b32_e32 v4, v102
	v_mov_b32_e32 v5, v103
	v_mov_b32_e32 v7, v97
	v_mov_b32_e32 v9, v73
	v_mov_b32_e32 v10, v82
	v_mov_b32_e32 v11, v83
	s_branch .LBB0_841

.LBB0_842:
	s_and_b64 vcc, exec, s[2:3]
	s_cbranch_vccz .LBB0_854
	v_mov_b32_e32 v6, v198
	s_mul_hi_u32 s2, s37, 0x2aaaaaab
	v_bfe_u32 v4, v6, 5, 3
	v_lshlrev_b32_e32 v0, 2, v6
	v_and_b32_e32 v0, 0x7c, v0
	v_mul_u32_u24_e32 v5, 0x84, v4
	v_lshl_add_u64 v[2:3], s[34:35], 0, v[0:1]
	v_add3_u32 v7, v5, v0, s47
	v_lshl_or_b32 v0, s37, 7, v4
	s_mulk_i32 s2, 0x300
	v_subrev_u32_e32 v8, s2, v0
	v_add_lshl_u32 v0, v4, s36, 2
	v_lshl_add_u64 v[4:5], s[24:25], 0, v[0:1]
	s_mov_b32 s34, 0
	s_andn2_b64 vcc, exec, s[10:11]
	s_cbranch_vccnz .LBB0_845
	v_mov_b32_e32 v65, v1
	v_add_u32_e32 v64, s34, v8
	v_mad_u64_u32 v[66:67], s[2:3], v64, s66, v[2:3]
	global_load_dword v68, v[66:67], off
	v_mov_b32_e32 v71, v67
	v_cndmask_b32_e64 v70, 0, 1, s[10:11]
	v_cmp_ne_u32_e64 s[2:3], 1, v70
	s_andn2_b64 vcc, exec, s[10:11]
	v_readlane_b32 s88, v240, 2
	v_readlane_b32 s89, v240, 3
	v_readlane_b32 s90, v240, 4
	v_readlane_b32 s91, v240, 5
	v_lshl_add_u64 v[66:67], v[64:65], 2, s[88:89]
	v_mov_b32_e32 v71, v67
	global_load_dword v70, v[66:67], off offset:3072
	v_readlane_b32 s92, v240, 6
	v_readlane_b32 s93, v240, 7
	v_readlane_b32 s94, v240, 8
	v_readlane_b32 s95, v240, 9
	v_add_u32_e32 v66, 8, v64
	v_mad_u64_u32 v[72:73], s[72:73], v66, s66, v[2:3]
	global_load_dword v67, v[72:73], off
	s_and_b64 vcc, exec, s[2:3]
	v_mov_b32_e32 v75, v73
	global_load_dword v74, v[4:5], off offset:-64
	v_add_u32_e32 v66, 16, v64
	v_mad_u64_u32 v[72:73], s[72:73], v66, s66, v[2:3]
	global_load_dword v69, v[72:73], off
	s_and_b64 vcc, exec, s[2:3]
	v_mov_b32_e32 v77, v73
	global_load_dword v76, v[4:5], off offset:-32
	v_mov_b32_e32 v73, v65
	v_add_u32_e32 v72, 24, v64
	v_mad_u64_u32 v[64:65], s[72:73], v72, s66, v[2:3]
	v_mov_b32_e32 v79, v73
	global_load_dword v78, v[64:65], off
	s_and_b64 vcc, exec, s[2:3]
	global_load_dword v66, v[4:5], off
	s_add_i32 s34, s34, 32
	v_add_u32_e32 v71, 0x1080, v7
	s_cmpk_lg_i32 s34, 0x80
	v_lshl_add_u64 v[72:73], v[4:5], 0, s[26:27]
	v_mov_b32_e32 v81, v79
	v_add_u32_e32 v80, s34, v8
	v_mad_u64_u32 v[82:83], s[2:3], v80, s66, v[2:3]
	global_load_dword v64, v[82:83], off
	v_mov_b32_e32 v85, v83
	v_cndmask_b32_e64 v84, 0, 1, s[10:11]
	v_cmp_ne_u32_e64 s[2:3], 1, v84
	s_andn2_b64 vcc, exec, s[10:11]
	v_readlane_b32 s88, v240, 2
	v_readlane_b32 s89, v240, 3
	v_readlane_b32 s90, v240, 4
	v_readlane_b32 s91, v240, 5
	v_lshl_add_u64 v[82:83], v[80:81], 2, s[88:89]
	v_mov_b32_e32 v85, v83
	global_load_dword v84, v[82:83], off offset:3072
	v_readlane_b32 s92, v240, 6
	v_readlane_b32 s93, v240, 7
	v_readlane_b32 s94, v240, 8
	v_readlane_b32 s95, v240, 9
	v_add_u32_e32 v65, 8, v80
	v_mad_u64_u32 v[82:83], s[72:73], v65, s66, v[2:3]
	global_load_dword v75, v[82:83], off
	s_and_b64 vcc, exec, s[2:3]
	v_mov_b32_e32 v87, v83
	global_load_dword v86, v[72:73], off offset:-64
	v_add_u32_e32 v65, 16, v80
	v_mad_u64_u32 v[82:83], s[72:73], v65, s66, v[2:3]
	global_load_dword v77, v[82:83], off
	s_and_b64 vcc, exec, s[2:3]
	v_mov_b32_e32 v89, v83
	global_load_dword v88, v[72:73], off offset:-32
	v_mov_b32_e32 v83, v81
	v_add_u32_e32 v82, 24, v80
	v_mad_u64_u32 v[80:81], s[72:73], v82, s66, v[2:3]
	v_mov_b32_e32 v91, v83
	global_load_dword v90, v[80:81], off
	s_and_b64 vcc, exec, s[2:3]
	global_load_dword v65, v[72:73], off
	s_add_i32 s34, s34, 32
	v_add_u32_e32 v79, 0x1080, v71
	s_cmpk_lg_i32 s34, 0x80
	v_lshl_add_u64 v[82:83], v[72:73], 0, s[26:27]
	v_mov_b32_e32 v73, v91
	v_add_u32_e32 v72, s34, v8
	v_mad_u64_u32 v[92:93], s[2:3], v72, s66, v[2:3]
	global_load_dword v80, v[92:93], off
	v_mov_b32_e32 v95, v93
	v_cndmask_b32_e64 v94, 0, 1, s[10:11]
	v_cmp_ne_u32_e64 s[2:3], 1, v94
	s_andn2_b64 vcc, exec, s[10:11]
	v_readlane_b32 s88, v240, 2
	v_readlane_b32 s89, v240, 3
	v_readlane_b32 s90, v240, 4
	v_readlane_b32 s91, v240, 5
	v_lshl_add_u64 v[92:93], v[72:73], 2, s[88:89]
	v_mov_b32_e32 v95, v93
	global_load_dword v94, v[92:93], off offset:3072
	v_readlane_b32 s92, v240, 6
	v_readlane_b32 s93, v240, 7
	v_readlane_b32 s94, v240, 8
	v_readlane_b32 s95, v240, 9
	v_add_u32_e32 v81, 8, v72
	v_mad_u64_u32 v[92:93], s[72:73], v81, s66, v[2:3]
	global_load_dword v85, v[92:93], off
	s_and_b64 vcc, exec, s[2:3]
	v_mov_b32_e32 v97, v93
	global_load_dword v96, v[82:83], off offset:-64
	v_add_u32_e32 v81, 16, v72
	v_mad_u64_u32 v[92:93], s[72:73], v81, s66, v[2:3]
	global_load_dword v87, v[92:93], off
	s_and_b64 vcc, exec, s[2:3]
	v_mov_b32_e32 v99, v93
	global_load_dword v98, v[82:83], off offset:-32
	v_mov_b32_e32 v93, v73
	v_add_u32_e32 v92, 24, v72
	v_mad_u64_u32 v[72:73], s[72:73], v92, s66, v[2:3]
	v_mov_b32_e32 v101, v93
	global_load_dword v100, v[72:73], off
	s_and_b64 vcc, exec, s[2:3]
	global_load_dword v81, v[82:83], off
	s_add_i32 s34, s34, 32
	v_add_u32_e32 v89, 0x1080, v79
	s_cmpk_lg_i32 s34, 0x80
	v_lshl_add_u64 v[92:93], v[82:83], 0, s[26:27]
	v_mov_b32_e32 v83, v101
	v_add_u32_e32 v82, s34, v8
	v_mad_u64_u32 v[102:103], s[2:3], v82, s66, v[2:3]
	global_load_dword v72, v[102:103], off
	v_mov_b32_e32 v105, v103
	v_cndmask_b32_e64 v104, 0, 1, s[10:11]
	v_cmp_ne_u32_e64 s[2:3], 1, v104
	s_andn2_b64 vcc, exec, s[10:11]
	v_readlane_b32 s88, v240, 2
	v_readlane_b32 s89, v240, 3
	v_readlane_b32 s90, v240, 4
	v_readlane_b32 s91, v240, 5
	v_lshl_add_u64 v[102:103], v[82:83], 2, s[88:89]
	v_mov_b32_e32 v105, v103
	global_load_dword v104, v[102:103], off offset:3072
	v_readlane_b32 s92, v240, 6
	v_readlane_b32 s93, v240, 7
	v_readlane_b32 s94, v240, 8
	v_readlane_b32 s95, v240, 9
	v_add_u32_e32 v73, 8, v82
	v_mad_u64_u32 v[102:103], s[72:73], v73, s66, v[2:3]
	global_load_dword v91, v[102:103], off
	s_and_b64 vcc, exec, s[2:3]
	v_mov_b32_e32 v107, v103
	global_load_dword v106, v[92:93], off offset:-64
	v_add_u32_e32 v73, 16, v82
	v_mad_u64_u32 v[102:103], s[72:73], v73, s66, v[2:3]
	global_load_dword v95, v[102:103], off
	s_and_b64 vcc, exec, s[2:3]
	v_mov_b32_e32 v109, v103
	global_load_dword v108, v[92:93], off offset:-32
	v_mov_b32_e32 v103, v83
	v_add_u32_e32 v102, 24, v82
	v_mad_u64_u32 v[82:83], s[72:73], v102, s66, v[2:3]
	v_mov_b32_e32 v111, v103
	global_load_dword v110, v[82:83], off
	s_and_b64 vcc, exec, s[2:3]
	global_load_dword v73, v[92:93], off
	s_add_i32 s34, s34, 32
	v_add_u32_e32 v97, 0x1080, v89
	s_cmpk_lg_i32 s34, 0x80
	v_lshl_add_u64 v[102:103], v[92:93], 0, s[26:27]
	s_waitcnt vmcnt(30)
	v_mul_f32_e32 v68, v68, v70
	v_mul_f32_e32 v68, 0x3e16c740, v68
	ds_write_b32 v7, v68
	s_waitcnt vmcnt(28)
	v_mul_f32_e32 v67, v67, v74
	v_mul_f32_e32 v67, 0x3e16c740, v67
	ds_write_b32 v7, v67 offset:1056
	s_waitcnt vmcnt(26)
	v_mul_f32_e32 v69, v69, v76
	v_mul_f32_e32 v69, 0x3e16c740, v69
	ds_write_b32 v7, v69 offset:2112
	s_waitcnt vmcnt(24)
	v_mul_f32_e32 v78, v78, v66
	v_mul_f32_e32 v78, 0x3e16c740, v78
	ds_write_b32 v7, v78 offset:3168
	s_waitcnt vmcnt(22)
	v_mul_f32_e32 v64, v64, v84
	v_mul_f32_e32 v64, 0x3e16c740, v64
	ds_write_b32 v71, v64
	s_waitcnt vmcnt(20)
	v_mul_f32_e32 v75, v75, v86
	v_mul_f32_e32 v75, 0x3e16c740, v75
	ds_write_b32 v71, v75 offset:1056
	s_waitcnt vmcnt(18)
	v_mul_f32_e32 v77, v77, v88
	v_mul_f32_e32 v77, 0x3e16c740, v77
	ds_write_b32 v71, v77 offset:2112
	s_waitcnt vmcnt(16)
	v_mul_f32_e32 v90, v90, v65
	v_mul_f32_e32 v90, 0x3e16c740, v90
	ds_write_b32 v71, v90 offset:3168
	s_waitcnt vmcnt(14)
	v_mul_f32_e32 v80, v80, v94
	v_mul_f32_e32 v80, 0x3e16c740, v80
	ds_write_b32 v79, v80
	s_waitcnt vmcnt(12)
	v_mul_f32_e32 v85, v85, v96
	v_mul_f32_e32 v85, 0x3e16c740, v85
	ds_write_b32 v79, v85 offset:1056
	s_waitcnt vmcnt(10)
	v_mul_f32_e32 v87, v87, v98
	v_mul_f32_e32 v87, 0x3e16c740, v87
	ds_write_b32 v79, v87 offset:2112
	s_waitcnt vmcnt(8)
	v_mul_f32_e32 v100, v100, v81
	v_mul_f32_e32 v100, 0x3e16c740, v100
	ds_write_b32 v79, v100 offset:3168
	s_waitcnt vmcnt(6)
	v_mul_f32_e32 v72, v72, v104
	v_mul_f32_e32 v72, 0x3e16c740, v72
	ds_write_b32 v89, v72
	s_waitcnt vmcnt(4)
	v_mul_f32_e32 v91, v91, v106
	v_mul_f32_e32 v91, 0x3e16c740, v91
	ds_write_b32 v89, v91 offset:1056
	s_waitcnt vmcnt(2)
	v_mul_f32_e32 v95, v95, v108
	v_mul_f32_e32 v95, 0x3e16c740, v95
	ds_write_b32 v89, v95 offset:2112
	s_waitcnt vmcnt(0)
	v_mul_f32_e32 v110, v110, v73
	v_mul_f32_e32 v110, 0x3e16c740, v110
	ds_write_b32 v89, v110 offset:3168
	v_mov_b32_e32 v0, v110
	v_mov_b32_e32 v1, v111
	v_mov_b32_e32 v4, v102
	v_mov_b32_e32 v5, v103
	v_mov_b32_e32 v7, v97
	v_mov_b32_e32 v9, v73
	v_mov_b32_e32 v10, v82
	v_mov_b32_e32 v11, v83
	s_branch .LBB0_853

.LBB0_857:
	s_lshl_b32 s71, s35, 3
	s_lshl_b32 s37, s34, 3
	v_or_b32_e32 v64, s71, v6
	v_or_b32_e32 v65, s37, v5
	v_mov_b32_e32 v67, v1
	v_add_u32_e32 v66, s2, v64
	v_mov_b32_e32 v69, v9
	v_add_u32_e32 v68, s3, v65
	v_mov_b32_e32 v71, v67
	v_mul_lo_u32 v70, v66, s67
	v_mov_b32_e32 v67, v69
	v_mul_lo_u32 v66, v68, s67
	v_lshl_add_u64 v[68:69], v[70:71], 2, v[2:3]
	v_mov_b32_e32 v72, v66
	v_mov_b32_e32 v73, v71
	v_lshl_add_u64 v[66:67], v[72:73], 2, v[2:3]
	v_mov_b32_e32 v73, v71
	global_load_dword v72, v[68:69], off
	global_load_dword v70, v[66:67], off
	v_mad_u64_u32 v[74:75], s[72:73], v64, s64, v[4:5]
	v_mad_u64_u32 v[66:67], s[72:73], v65, s64, v[4:5]
	s_add_i32 s73, s71, 16
	s_add_i32 s72, s37, 16
	v_or_b32_e32 v68, s73, v6
	v_or_b32_e32 v64, s72, v5
	v_mov_b32_e32 v76, v74
	v_mov_b32_e32 v77, v73
	s_add_i32 s35, s35, 8
	s_add_i32 s34, s34, 8
	s_add_i32 s36, s36, -8
	v_mov_b32_e32 v75, v73
	v_add_u32_e32 v74, s2, v68
	v_mov_b32_e32 v79, v77
	v_add_u32_e32 v78, s3, v64
	v_mov_b32_e32 v81, v75
	v_mul_lo_u32 v80, v74, s67
	v_mov_b32_e32 v75, v79
	v_mul_lo_u32 v74, v78, s67
	v_lshl_add_u64 v[78:79], v[80:81], 2, v[2:3]
	v_lshl_add_u64 v[82:83], v[74:75], 2, v[2:3]
	v_mov_b32_e32 v75, v81
	global_load_dword v74, v[78:79], off
	global_load_dword v65, v[82:83], off
	v_mad_u64_u32 v[80:81], s[72:73], v68, s64, v[4:5]
	v_mad_u64_u32 v[82:83], s[72:73], v64, s64, v[4:5]
	s_add_i32 s73, s71, 32
	s_add_i32 s72, s37, 32
	v_or_b32_e32 v67, s73, v6
	v_or_b32_e32 v68, s72, v5
	v_mov_b32_e32 v78, v80
	v_mov_b32_e32 v79, v75
	s_add_i32 s71, s71, 48
	s_add_i32 s37, s37, 48
	s_cmp_lg_u32 s36, 0
	v_mov_b32_e32 v81, v75
	v_add_u32_e32 v80, s2, v67
	v_mov_b32_e32 v85, v79
	v_add_u32_e32 v84, s3, v68
	v_mov_b32_e32 v87, v81
	v_mul_lo_u32 v86, v80, s67
	v_mov_b32_e32 v81, v85
	v_mul_lo_u32 v80, v84, s67
	v_lshl_add_u64 v[84:85], v[86:87], 2, v[2:3]
	v_lshl_add_u64 v[88:89], v[80:81], 2, v[2:3]
	v_mov_b32_e32 v81, v87
	global_load_dword v80, v[84:85], off
	global_load_dword v64, v[88:89], off
	v_mad_u64_u32 v[86:87], s[72:73], v67, s64, v[4:5]
	v_or_b32_e32 v69, s71, v6
	v_mad_u64_u32 v[88:89], s[72:73], v68, s64, v[4:5]
	v_or_b32_e32 v67, s37, v5
	v_mov_b32_e32 v84, v86
	v_mov_b32_e32 v85, v81
	v_mov_b32_e32 v87, v81
	v_add_u32_e32 v86, s2, v69
	v_mov_b32_e32 v91, v85
	v_add_u32_e32 v90, s3, v67
	v_mov_b32_e32 v93, v87
	v_mul_lo_u32 v92, v86, s67
	v_mov_b32_e32 v87, v91
	v_mul_lo_u32 v86, v90, s67
	v_lshl_add_u64 v[90:91], v[92:93], 2, v[2:3]
	v_lshl_add_u64 v[94:95], v[86:87], 2, v[2:3]
	v_mov_b32_e32 v87, v93
	global_load_dword v86, v[90:91], off
	global_load_dword v68, v[94:95], off
	v_mad_u64_u32 v[92:93], s[72:73], v69, s64, v[4:5]
	v_mad_u64_u32 v[94:95], s[72:73], v67, s64, v[4:5]
	s_lshl_b32 s71, s35, 3
	s_lshl_b32 s37, s34, 3
	v_or_b32_e32 v71, s71, v6
	v_or_b32_e32 v69, s37, v5
	v_mov_b32_e32 v91, v87
	v_add_u32_e32 v90, s2, v71
	v_mov_b32_e32 v97, v93
	v_add_u32_e32 v96, s3, v69
	v_mov_b32_e32 v99, v91
	v_mul_lo_u32 v98, v90, s67
	v_mov_b32_e32 v91, v97
	v_mul_lo_u32 v90, v96, s67
	v_lshl_add_u64 v[96:97], v[98:99], 2, v[2:3]
	v_mov_b32_e32 v100, v90
	v_mov_b32_e32 v101, v99
	v_lshl_add_u64 v[90:91], v[100:101], 2, v[2:3]
	v_mov_b32_e32 v101, v99
	global_load_dword v100, v[96:97], off
	global_load_dword v67, v[90:91], off
	v_mad_u64_u32 v[98:99], s[72:73], v71, s64, v[4:5]
	v_mad_u64_u32 v[90:91], s[72:73], v69, s64, v[4:5]
	s_add_i32 s73, s71, 16
	s_add_i32 s72, s37, 16
	v_or_b32_e32 v73, s73, v6
	v_or_b32_e32 v71, s72, v5
	v_mov_b32_e32 v96, v98
	v_mov_b32_e32 v97, v101
	s_add_i32 s35, s35, 8
	s_add_i32 s34, s34, 8
	s_add_i32 s36, s36, -8
	v_mov_b32_e32 v99, v101
	v_add_u32_e32 v98, s2, v73
	v_mov_b32_e32 v103, v97
	v_add_u32_e32 v102, s3, v71
	v_mov_b32_e32 v105, v99
	v_mul_lo_u32 v104, v98, s67
	v_mov_b32_e32 v99, v103
	v_mul_lo_u32 v98, v102, s67
	v_lshl_add_u64 v[102:103], v[104:105], 2, v[2:3]
	v_lshl_add_u64 v[106:107], v[98:99], 2, v[2:3]
	v_mov_b32_e32 v99, v105
	global_load_dword v98, v[102:103], off
	global_load_dword v69, v[106:107], off
	v_mad_u64_u32 v[104:105], s[72:73], v73, s64, v[4:5]
	v_mad_u64_u32 v[106:107], s[72:73], v71, s64, v[4:5]
	s_add_i32 s73, s71, 32
	s_add_i32 s72, s37, 32
	v_or_b32_e32 v75, s73, v6
	v_or_b32_e32 v73, s72, v5
	v_mov_b32_e32 v102, v104
	v_mov_b32_e32 v103, v99
	s_add_i32 s71, s71, 48
	s_add_i32 s37, s37, 48
	s_cmp_lg_u32 s36, 0
	v_mov_b32_e32 v105, v99
	v_add_u32_e32 v104, s2, v75
	v_mov_b32_e32 v109, v103
	v_add_u32_e32 v108, s3, v73
	v_mov_b32_e32 v111, v105
	v_mul_lo_u32 v110, v104, s67
	v_mov_b32_e32 v105, v109
	v_mul_lo_u32 v104, v108, s67
	v_lshl_add_u64 v[108:109], v[110:111], 2, v[2:3]
	v_lshl_add_u64 v[112:113], v[104:105], 2, v[2:3]
	v_mov_b32_e32 v105, v111
	global_load_dword v104, v[108:109], off
	global_load_dword v71, v[112:113], off
	v_mad_u64_u32 v[110:111], s[72:73], v75, s64, v[4:5]
	v_or_b32_e32 v77, s71, v6
	v_mad_u64_u32 v[112:113], s[72:73], v73, s64, v[4:5]
	v_or_b32_e32 v75, s37, v5
	v_mov_b32_e32 v108, v110
	v_mov_b32_e32 v109, v105
	v_mov_b32_e32 v111, v105
	v_add_u32_e32 v110, s2, v77
	v_mov_b32_e32 v115, v109
	v_add_u32_e32 v114, s3, v75
	v_mov_b32_e32 v117, v111
	v_mul_lo_u32 v116, v110, s67
	v_mov_b32_e32 v111, v115
	v_mul_lo_u32 v110, v114, s67
	v_lshl_add_u64 v[114:115], v[116:117], 2, v[2:3]
	v_lshl_add_u64 v[118:119], v[110:111], 2, v[2:3]
	v_mov_b32_e32 v111, v117
	global_load_dword v110, v[114:115], off
	global_load_dword v73, v[118:119], off
	v_mad_u64_u32 v[116:117], s[72:73], v77, s64, v[4:5]
	v_mad_u64_u32 v[118:119], s[72:73], v75, s64, v[4:5]
	s_waitcnt vmcnt(15)
	ds_write_b32 v76, v72
	s_waitcnt vmcnt(14)
	ds_write_b32 v66, v70
	s_waitcnt vmcnt(13)
	ds_write_b32 v78, v74
	s_waitcnt vmcnt(12)
	ds_write_b32 v82, v65
	s_waitcnt vmcnt(11)
	ds_write_b32 v84, v80
	s_waitcnt vmcnt(10)
	ds_write_b32 v88, v64
	s_waitcnt vmcnt(9)
	ds_write_b32 v92, v86
	s_waitcnt vmcnt(8)
	ds_write_b32 v94, v68
	s_waitcnt vmcnt(7)
	ds_write_b32 v96, v100
	s_waitcnt vmcnt(6)
	ds_write_b32 v90, v67
	s_waitcnt vmcnt(5)
	ds_write_b32 v102, v98
	s_waitcnt vmcnt(4)
	ds_write_b32 v106, v69
	s_waitcnt vmcnt(3)
	ds_write_b32 v108, v104
	s_waitcnt vmcnt(2)
	ds_write_b32 v112, v71
	s_waitcnt vmcnt(1)
	ds_write_b32 v116, v110
	s_waitcnt vmcnt(0)
	ds_write_b32 v118, v73
	v_mov_b32_e32 v0, v110
	v_mov_b32_e32 v1, v111
	v_mov_b32_e32 v8, v116
	v_mov_b32_e32 v9, v117
	v_mov_b32_e32 v10, v118
	v_mov_b32_e32 v11, v119
	v_mov_b32_e32 v12, v75
	v_mov_b32_e32 v13, v77
	v_mov_b32_e32 v18, v73
	v_lshlrev_b32_sdwa v0, v14, v7 dst_sel:DWORD dst_unused:UNUSED_PAD src0_sel:DWORD src1_sel:BYTE_0
	v_and_b32_e32 v0, 0x7e, v0
	v_lshrrev_b32_sdwa v3, v15, v7 dst_sel:DWORD dst_unused:UNUSED_PAD src0_sel:DWORD src1_sel:BYTE_0
	v_or_b32_e32 v2, s20, v3
	v_or_b32_e32 v8, s2, v0
	v_mul_u32_u24_e32 v0, 0x84, v0
	v_lshlrev_b32_e32 v3, 2, v3
	v_add3_u32 v24, s47, v0, v3
	s_waitcnt lgkmcnt(0)
	s_barrier
	ds_read2_b32 v[4:5], v24 offset0:33 offset1:37
	ds_read2_b32 v[6:7], v24 offset1:4
	v_lshlrev_b32_e32 v0, 1, v8
	v_mov_b32_e32 v3, v1
	ds_read2_b32 v[10:11], v24 offset0:8 offset1:12
	ds_read2_b32 v[12:13], v24 offset0:41 offset1:45
	v_lshl_add_u64 v[8:9], s[14:15], 0, v[0:1]
	v_lshlrev_b64 v[18:19], 11, v[2:3]
	s_waitcnt lgkmcnt(2)
	v_cvt_pk_bf16_f32 v0, v6, v4
	v_lshl_add_u64 v[18:19], v[8:9], 0, v[18:19]
	global_store_dword v[18:19], v0, off
	v_or_b32_e32 v0, 4, v2
	v_lshlrev_b64 v[22:23], 11, v[0:1]
	s_waitcnt lgkmcnt(0)
	v_cvt_pk_bf16_f32 v3, v10, v12
	ds_read2_b32 v[18:19], v24 offset0:16 offset1:20
	ds_read2_b32 v[20:21], v24 offset0:49 offset1:53
	v_lshl_add_u64 v[22:23], v[8:9], 0, v[22:23]
	global_store_dword v[22:23], v3, off
	ds_read2_b32 v[22:23], v24 offset0:24 offset1:28
	ds_read2_b32 v[24:25], v24 offset0:57 offset1:61
	v_or_b32_e32 v0, 8, v2
	v_lshlrev_b64 v[26:27], 11, v[0:1]
	s_waitcnt lgkmcnt(2)
	v_cvt_pk_bf16_f32 v3, v18, v20
	v_lshl_add_u64 v[26:27], v[8:9], 0, v[26:27]
	v_or_b32_e32 v0, 12, v2
	global_store_dword v[26:27], v3, off
	v_lshlrev_b64 v[26:27], 11, v[0:1]
	s_waitcnt lgkmcnt(0)
	v_cvt_pk_bf16_f32 v3, v22, v24
	v_lshl_add_u64 v[26:27], v[8:9], 0, v[26:27]
	v_or_b32_e32 v0, 16, v2
	global_store_dword v[26:27], v3, off
	v_cvt_pk_bf16_f32 v3, v7, v5
	v_lshlrev_b64 v[4:5], 11, v[0:1]
	v_lshl_add_u64 v[4:5], v[8:9], 0, v[4:5]
	v_or_b32_e32 v0, 20, v2
	global_store_dword v[4:5], v3, off
	v_lshlrev_b64 v[4:5], 11, v[0:1]
	v_cvt_pk_bf16_f32 v3, v11, v13
	v_lshl_add_u64 v[4:5], v[8:9], 0, v[4:5]
	v_or_b32_e32 v0, 24, v2
	global_store_dword v[4:5], v3, off
	v_lshlrev_b64 v[4:5], 11, v[0:1]
	v_cvt_pk_bf16_f32 v3, v19, v21
	v_lshl_add_u64 v[4:5], v[8:9], 0, v[4:5]
	v_or_b32_e32 v0, 28, v2
	global_store_dword v[4:5], v3, off
	v_lshlrev_b64 v[2:3], 11, v[0:1]
	v_cvt_pk_bf16_f32 v4, v23, v25
	v_lshl_add_u64 v[2:3], v[8:9], 0, v[2:3]
	global_store_dword v[2:3], v4, off
	s_barrier

.LBB0_863:
	s_lshl_b32 s72, s37, 3
	s_lshl_b32 s71, s36, 3
	v_or_b32_e32 v64, s72, v6
	v_or_b32_e32 v65, s71, v5
	v_mov_b32_e32 v67, v1
	v_add_u32_e32 v66, s2, v64
	v_mov_b32_e32 v69, v9
	v_add_u32_e32 v68, s3, v65
	v_mov_b32_e32 v71, v67
	v_mul_lo_u32 v70, v66, s67
	v_mov_b32_e32 v67, v69
	v_mul_lo_u32 v66, v68, s67
	v_lshl_add_u64 v[68:69], v[70:71], 2, v[2:3]
	v_mov_b32_e32 v72, v66
	v_mov_b32_e32 v73, v71
	v_lshl_add_u64 v[66:67], v[72:73], 2, v[2:3]
	v_mov_b32_e32 v73, v71
	global_load_dword v72, v[68:69], off
	global_load_dword v70, v[66:67], off
	v_mad_u64_u32 v[74:75], s[74:75], v64, s64, v[4:5]
	v_mad_u64_u32 v[66:67], s[74:75], v65, s64, v[4:5]
	s_add_i32 s74, s72, 16
	s_add_i32 s73, s71, 16
	v_or_b32_e32 v68, s74, v6
	v_or_b32_e32 v64, s73, v5
	v_mov_b32_e32 v76, v74
	v_mov_b32_e32 v77, v73
	s_add_i32 s73, s71, 32
	s_add_i32 s71, s71, 48
	s_add_i32 s37, s37, 8
	s_add_i32 s36, s36, 8
	s_add_i32 s70, s70, -8
	v_mov_b32_e32 v75, v73
	v_add_u32_e32 v74, s2, v68
	v_mov_b32_e32 v79, v77
	v_add_u32_e32 v78, s3, v64
	v_mov_b32_e32 v81, v75
	v_mul_lo_u32 v80, v74, s67
	v_mov_b32_e32 v75, v79
	v_mul_lo_u32 v74, v78, s67
	v_lshl_add_u64 v[78:79], v[80:81], 2, v[2:3]
	v_lshl_add_u64 v[82:83], v[74:75], 2, v[2:3]
	v_mov_b32_e32 v75, v81
	global_load_dword v74, v[78:79], off
	global_load_dword v65, v[82:83], off
	v_mad_u64_u32 v[80:81], s[74:75], v68, s64, v[4:5]
	v_mad_u64_u32 v[82:83], s[74:75], v64, s64, v[4:5]
	s_add_i32 s74, s72, 32
	s_nop 0
	v_or_b32_e32 v67, s74, v6
	v_or_b32_e32 v68, s73, v5
	v_mov_b32_e32 v78, v80
	v_mov_b32_e32 v79, v75
	s_add_i32 s72, s72, 48
	s_cmp_lg_u32 s70, 0
	v_mov_b32_e32 v81, v75
	v_add_u32_e32 v80, s2, v67
	v_mov_b32_e32 v85, v79
	v_add_u32_e32 v84, s3, v68
	v_mov_b32_e32 v87, v81
	v_mul_lo_u32 v86, v80, s67
	v_mov_b32_e32 v81, v85
	v_mul_lo_u32 v80, v84, s67
	v_lshl_add_u64 v[84:85], v[86:87], 2, v[2:3]
	v_lshl_add_u64 v[88:89], v[80:81], 2, v[2:3]
	v_mov_b32_e32 v81, v87
	global_load_dword v80, v[84:85], off
	global_load_dword v64, v[88:89], off
	v_mad_u64_u32 v[86:87], s[74:75], v67, s64, v[4:5]
	v_or_b32_e32 v69, s72, v6
	v_mad_u64_u32 v[88:89], s[74:75], v68, s64, v[4:5]
	v_or_b32_e32 v67, s71, v5
	v_mov_b32_e32 v84, v86
	v_mov_b32_e32 v85, v81
	v_mov_b32_e32 v87, v81
	v_add_u32_e32 v86, s2, v69
	v_mov_b32_e32 v91, v85
	v_add_u32_e32 v90, s3, v67
	v_mov_b32_e32 v93, v87
	v_mul_lo_u32 v92, v86, s67
	v_mov_b32_e32 v87, v91
	v_mul_lo_u32 v86, v90, s67
	v_lshl_add_u64 v[90:91], v[92:93], 2, v[2:3]
	v_lshl_add_u64 v[94:95], v[86:87], 2, v[2:3]
	v_mov_b32_e32 v87, v93
	global_load_dword v86, v[90:91], off
	global_load_dword v68, v[94:95], off
	v_mad_u64_u32 v[92:93], s[72:73], v69, s64, v[4:5]
	v_mad_u64_u32 v[94:95], s[72:73], v67, s64, v[4:5]
	s_lshl_b32 s72, s37, 3
	s_lshl_b32 s71, s36, 3
	v_or_b32_e32 v71, s72, v6
	v_or_b32_e32 v69, s71, v5
	v_mov_b32_e32 v91, v87
	v_add_u32_e32 v90, s2, v71
	v_mov_b32_e32 v97, v93
	v_add_u32_e32 v96, s3, v69
	v_mov_b32_e32 v99, v91
	v_mul_lo_u32 v98, v90, s67
	v_mov_b32_e32 v91, v97
	v_mul_lo_u32 v90, v96, s67
	v_lshl_add_u64 v[96:97], v[98:99], 2, v[2:3]
	v_mov_b32_e32 v100, v90
	v_mov_b32_e32 v101, v99
	v_lshl_add_u64 v[90:91], v[100:101], 2, v[2:3]
	v_mov_b32_e32 v101, v99
	global_load_dword v100, v[96:97], off
	global_load_dword v67, v[90:91], off
	v_mad_u64_u32 v[98:99], s[74:75], v71, s64, v[4:5]
	v_mad_u64_u32 v[90:91], s[74:75], v69, s64, v[4:5]
	s_add_i32 s74, s72, 16
	s_add_i32 s73, s71, 16
	v_or_b32_e32 v73, s74, v6
	v_or_b32_e32 v71, s73, v5
	v_mov_b32_e32 v96, v98
	v_mov_b32_e32 v97, v101
	s_add_i32 s73, s71, 32
	s_add_i32 s71, s71, 48
	s_add_i32 s37, s37, 8
	s_add_i32 s36, s36, 8
	s_add_i32 s70, s70, -8
	v_mov_b32_e32 v99, v101
	v_add_u32_e32 v98, s2, v73
	v_mov_b32_e32 v103, v97
	v_add_u32_e32 v102, s3, v71
	v_mov_b32_e32 v105, v99
	v_mul_lo_u32 v104, v98, s67
	v_mov_b32_e32 v99, v103
	v_mul_lo_u32 v98, v102, s67
	v_lshl_add_u64 v[102:103], v[104:105], 2, v[2:3]
	v_lshl_add_u64 v[106:107], v[98:99], 2, v[2:3]
	v_mov_b32_e32 v99, v105
	global_load_dword v98, v[102:103], off
	global_load_dword v69, v[106:107], off
	v_mad_u64_u32 v[104:105], s[74:75], v73, s64, v[4:5]
	v_mad_u64_u32 v[106:107], s[74:75], v71, s64, v[4:5]
	s_add_i32 s74, s72, 32
	s_nop 0
	v_or_b32_e32 v75, s74, v6
	v_or_b32_e32 v73, s73, v5
	v_mov_b32_e32 v102, v104
	v_mov_b32_e32 v103, v99
	s_add_i32 s72, s72, 48
	s_cmp_lg_u32 s70, 0
	v_mov_b32_e32 v105, v99
	v_add_u32_e32 v104, s2, v75
	v_mov_b32_e32 v109, v103
	v_add_u32_e32 v108, s3, v73
	v_mov_b32_e32 v111, v105
	v_mul_lo_u32 v110, v104, s67
	v_mov_b32_e32 v105, v109
	v_mul_lo_u32 v104, v108, s67
	v_lshl_add_u64 v[108:109], v[110:111], 2, v[2:3]
	v_lshl_add_u64 v[112:113], v[104:105], 2, v[2:3]
	v_mov_b32_e32 v105, v111
	global_load_dword v104, v[108:109], off
	global_load_dword v71, v[112:113], off
	v_mad_u64_u32 v[110:111], s[74:75], v75, s64, v[4:5]
	v_or_b32_e32 v77, s72, v6
	v_mad_u64_u32 v[112:113], s[74:75], v73, s64, v[4:5]
	v_or_b32_e32 v75, s71, v5
	v_mov_b32_e32 v108, v110
	v_mov_b32_e32 v109, v105
	v_mov_b32_e32 v111, v105
	v_add_u32_e32 v110, s2, v77
	v_mov_b32_e32 v115, v109
	v_add_u32_e32 v114, s3, v75
	v_mov_b32_e32 v117, v111
	v_mul_lo_u32 v116, v110, s67
	v_mov_b32_e32 v111, v115
	v_mul_lo_u32 v110, v114, s67
	v_lshl_add_u64 v[114:115], v[116:117], 2, v[2:3]
	v_lshl_add_u64 v[118:119], v[110:111], 2, v[2:3]
	v_mov_b32_e32 v111, v117
	global_load_dword v110, v[114:115], off
	global_load_dword v73, v[118:119], off
	v_mad_u64_u32 v[116:117], s[72:73], v77, s64, v[4:5]
	v_mad_u64_u32 v[118:119], s[72:73], v75, s64, v[4:5]
	s_waitcnt vmcnt(15)
	ds_write_b32 v76, v72
	s_waitcnt vmcnt(14)
	ds_write_b32 v66, v70
	s_waitcnt vmcnt(13)
	ds_write_b32 v78, v74
	s_waitcnt vmcnt(12)
	ds_write_b32 v82, v65
	s_waitcnt vmcnt(11)
	ds_write_b32 v84, v80
	s_waitcnt vmcnt(10)
	ds_write_b32 v88, v64
	s_waitcnt vmcnt(9)
	ds_write_b32 v92, v86
	s_waitcnt vmcnt(8)
	ds_write_b32 v94, v68
	s_waitcnt vmcnt(7)
	ds_write_b32 v96, v100
	s_waitcnt vmcnt(6)
	ds_write_b32 v90, v67
	s_waitcnt vmcnt(5)
	ds_write_b32 v102, v98
	s_waitcnt vmcnt(4)
	ds_write_b32 v106, v69
	s_waitcnt vmcnt(3)
	ds_write_b32 v108, v104
	s_waitcnt vmcnt(2)
	ds_write_b32 v112, v71
	s_waitcnt vmcnt(1)
	ds_write_b32 v116, v110
	s_waitcnt vmcnt(0)
	ds_write_b32 v118, v73
	v_mov_b32_e32 v0, v110
	v_mov_b32_e32 v1, v111
	v_mov_b32_e32 v8, v116
	v_mov_b32_e32 v9, v117
	v_mov_b32_e32 v10, v118
	v_mov_b32_e32 v11, v119
	v_mov_b32_e32 v12, v75
	v_mov_b32_e32 v13, v77
	v_mov_b32_e32 v18, v73
	v_lshlrev_b32_sdwa v0, v14, v7 dst_sel:DWORD dst_unused:UNUSED_PAD src0_sel:DWORD src1_sel:BYTE_0
	v_and_b32_e32 v0, 0x7e, v0
	v_lshrrev_b32_sdwa v3, v15, v7 dst_sel:DWORD dst_unused:UNUSED_PAD src0_sel:DWORD src1_sel:BYTE_0
	v_or_b32_e32 v2, s35, v3
	v_or_b32_e32 v8, s2, v0
	v_mul_u32_u24_e32 v0, 0x84, v0
	v_lshlrev_b32_e32 v3, 2, v3
	v_add3_u32 v26, s47, v0, v3
	s_waitcnt lgkmcnt(0)
	s_barrier
	ds_read2_b32 v[4:5], v26 offset0:33 offset1:37
	ds_read2_b32 v[6:7], v26 offset1:4
	v_lshlrev_b32_e32 v0, 1, v8
	v_ashrrev_i32_e32 v3, 31, v2
	v_lshl_add_u64 v[8:9], s[16:17], 0, v[0:1]
	ds_read2_b32 v[10:11], v26 offset0:8 offset1:12
	v_lshlrev_b64 v[12:13], 11, v[2:3]
	ds_read2_b32 v[18:19], v26 offset0:41 offset1:45
	s_waitcnt lgkmcnt(2)
	v_cvt_pk_bf16_f32 v0, v6, v4
	v_lshl_add_u64 v[12:13], v[8:9], 0, v[12:13]
	global_store_dword v[12:13], v0, off
	v_or_b32_e32 v12, 4, v2
	v_ashrrev_i32_e32 v13, 31, v12
	v_lshlrev_b64 v[12:13], 11, v[12:13]
	ds_read2_b32 v[20:21], v26 offset0:16 offset1:20
	ds_read2_b32 v[22:23], v26 offset0:49 offset1:53
	s_waitcnt lgkmcnt(2)
	v_cvt_pk_bf16_f32 v0, v10, v18
	v_lshl_add_u64 v[12:13], v[8:9], 0, v[12:13]
	global_store_dword v[12:13], v0, off
	v_or_b32_e32 v12, 8, v2
	v_ashrrev_i32_e32 v13, 31, v12
	v_lshlrev_b64 v[12:13], 11, v[12:13]
	ds_read2_b32 v[24:25], v26 offset0:24 offset1:28
	ds_read2_b32 v[26:27], v26 offset0:57 offset1:61
	s_waitcnt lgkmcnt(2)
	v_cvt_pk_bf16_f32 v0, v20, v22
	v_lshl_add_u64 v[12:13], v[8:9], 0, v[12:13]
	global_store_dword v[12:13], v0, off
	v_or_b32_e32 v12, 12, v2
	v_ashrrev_i32_e32 v13, 31, v12
	v_lshlrev_b64 v[12:13], 11, v[12:13]
	s_waitcnt lgkmcnt(0)
	v_cvt_pk_bf16_f32 v0, v24, v26
	v_lshl_add_u64 v[12:13], v[8:9], 0, v[12:13]
	global_store_dword v[12:13], v0, off
	v_or_b32_e32 v12, 16, v2
	v_ashrrev_i32_e32 v13, 31, v12
	v_cvt_pk_bf16_f32 v0, v7, v5
	v_lshlrev_b64 v[4:5], 11, v[12:13]
	v_lshl_add_u64 v[4:5], v[8:9], 0, v[4:5]
	global_store_dword v[4:5], v0, off
	v_or_b32_e32 v4, 20, v2
	v_ashrrev_i32_e32 v5, 31, v4
	v_lshlrev_b64 v[4:5], 11, v[4:5]
	v_cvt_pk_bf16_f32 v0, v11, v19
	v_lshl_add_u64 v[4:5], v[8:9], 0, v[4:5]
	global_store_dword v[4:5], v0, off
	v_or_b32_e32 v4, 24, v2
	v_ashrrev_i32_e32 v5, 31, v4
	v_or_b32_e32 v2, 28, v2
	v_lshlrev_b64 v[4:5], 11, v[4:5]
	v_ashrrev_i32_e32 v3, 31, v2
	v_cvt_pk_bf16_f32 v0, v21, v23
	v_lshl_add_u64 v[4:5], v[8:9], 0, v[4:5]
	v_lshlrev_b64 v[2:3], 11, v[2:3]
	global_store_dword v[4:5], v0, off
	v_cvt_pk_bf16_f32 v0, v25, v27
	v_lshl_add_u64 v[2:3], v[8:9], 0, v[2:3]
	s_mov_b64 s[2:3], 0
	global_store_dword v[2:3], v0, off
	s_barrier

.LBB0_867:
	s_lshl_b32 s37, s34, 3
	s_lshl_b32 s36, s20, 3
	v_or_b32_e32 v64, s37, v6
	v_or_b32_e32 v65, s36, v5
	v_mov_b32_e32 v67, v1
	v_add_u32_e32 v66, s2, v64
	v_mov_b32_e32 v69, v9
	v_add_u32_e32 v68, s3, v65
	v_mov_b32_e32 v71, v67
	v_mul_lo_u32 v70, v66, s67
	v_mov_b32_e32 v67, v69
	v_mul_lo_u32 v66, v68, s67
	v_lshl_add_u64 v[68:69], v[70:71], 2, v[2:3]
	v_mov_b32_e32 v72, v66
	v_mov_b32_e32 v73, v71
	v_lshl_add_u64 v[66:67], v[72:73], 2, v[2:3]
	v_mov_b32_e32 v73, v71
	global_load_dword v72, v[68:69], off
	global_load_dword v70, v[66:67], off
	v_mad_u64_u32 v[74:75], s[70:71], v64, s64, v[4:5]
	v_mad_u64_u32 v[66:67], s[70:71], v65, s64, v[4:5]
	s_add_i32 s71, s37, 16
	s_add_i32 s70, s36, 16
	v_or_b32_e32 v68, s71, v6
	v_or_b32_e32 v64, s70, v5
	v_mov_b32_e32 v76, v74
	v_mov_b32_e32 v77, v73
	s_add_i32 s34, s34, 8
	s_add_i32 s20, s20, 8
	s_add_i32 s35, s35, -8
	v_mov_b32_e32 v75, v73
	v_add_u32_e32 v74, s2, v68
	v_mov_b32_e32 v79, v77
	v_add_u32_e32 v78, s3, v64
	v_mov_b32_e32 v81, v75
	v_mul_lo_u32 v80, v74, s67
	v_mov_b32_e32 v75, v79
	v_mul_lo_u32 v74, v78, s67
	v_lshl_add_u64 v[78:79], v[80:81], 2, v[2:3]
	v_lshl_add_u64 v[82:83], v[74:75], 2, v[2:3]
	v_mov_b32_e32 v75, v81
	global_load_dword v74, v[78:79], off
	global_load_dword v65, v[82:83], off
	v_mad_u64_u32 v[80:81], s[70:71], v68, s64, v[4:5]
	v_mad_u64_u32 v[82:83], s[70:71], v64, s64, v[4:5]
	s_add_i32 s71, s37, 32
	s_add_i32 s70, s36, 32
	v_or_b32_e32 v67, s71, v6
	v_or_b32_e32 v68, s70, v5
	v_mov_b32_e32 v78, v80
	v_mov_b32_e32 v79, v75
	s_add_i32 s37, s37, 48
	s_add_i32 s36, s36, 48
	s_cmp_lg_u32 s35, 0
	v_mov_b32_e32 v81, v75
	v_add_u32_e32 v80, s2, v67
	v_mov_b32_e32 v85, v79
	v_add_u32_e32 v84, s3, v68
	v_mov_b32_e32 v87, v81
	v_mul_lo_u32 v86, v80, s67
	v_mov_b32_e32 v81, v85
	v_mul_lo_u32 v80, v84, s67
	v_lshl_add_u64 v[84:85], v[86:87], 2, v[2:3]
	v_lshl_add_u64 v[88:89], v[80:81], 2, v[2:3]
	v_mov_b32_e32 v81, v87
	global_load_dword v80, v[84:85], off
	global_load_dword v64, v[88:89], off
	v_mad_u64_u32 v[86:87], s[70:71], v67, s64, v[4:5]
	v_or_b32_e32 v69, s37, v6
	v_mad_u64_u32 v[88:89], s[70:71], v68, s64, v[4:5]
	v_or_b32_e32 v67, s36, v5
	v_mov_b32_e32 v84, v86
	v_mov_b32_e32 v85, v81
	v_mov_b32_e32 v87, v81
	v_add_u32_e32 v86, s2, v69
	v_mov_b32_e32 v91, v85
	v_add_u32_e32 v90, s3, v67
	v_mov_b32_e32 v93, v87
	v_mul_lo_u32 v92, v86, s67
	v_mov_b32_e32 v87, v91
	v_mul_lo_u32 v86, v90, s67
	v_lshl_add_u64 v[90:91], v[92:93], 2, v[2:3]
	v_lshl_add_u64 v[94:95], v[86:87], 2, v[2:3]
	v_mov_b32_e32 v87, v93
	global_load_dword v86, v[90:91], off
	global_load_dword v68, v[94:95], off
	v_mad_u64_u32 v[92:93], s[36:37], v69, s64, v[4:5]
	v_mad_u64_u32 v[94:95], s[36:37], v67, s64, v[4:5]
	s_lshl_b32 s37, s34, 3
	s_lshl_b32 s36, s20, 3
	v_or_b32_e32 v71, s37, v6
	v_or_b32_e32 v69, s36, v5
	v_mov_b32_e32 v91, v87
	v_add_u32_e32 v90, s2, v71
	v_mov_b32_e32 v97, v93
	v_add_u32_e32 v96, s3, v69
	v_mov_b32_e32 v99, v91
	v_mul_lo_u32 v98, v90, s67
	v_mov_b32_e32 v91, v97
	v_mul_lo_u32 v90, v96, s67
	v_lshl_add_u64 v[96:97], v[98:99], 2, v[2:3]
	v_mov_b32_e32 v100, v90
	v_mov_b32_e32 v101, v99
	v_lshl_add_u64 v[90:91], v[100:101], 2, v[2:3]
	v_mov_b32_e32 v101, v99
	global_load_dword v100, v[96:97], off
	global_load_dword v67, v[90:91], off
	v_mad_u64_u32 v[98:99], s[70:71], v71, s64, v[4:5]
	v_mad_u64_u32 v[90:91], s[70:71], v69, s64, v[4:5]
	s_add_i32 s71, s37, 16
	s_add_i32 s70, s36, 16
	v_or_b32_e32 v73, s71, v6
	v_or_b32_e32 v71, s70, v5
	v_mov_b32_e32 v96, v98
	v_mov_b32_e32 v97, v101
	s_add_i32 s34, s34, 8
	s_add_i32 s20, s20, 8
	s_add_i32 s35, s35, -8
	v_mov_b32_e32 v99, v101
	v_add_u32_e32 v98, s2, v73
	v_mov_b32_e32 v103, v97
	v_add_u32_e32 v102, s3, v71
	v_mov_b32_e32 v105, v99
	v_mul_lo_u32 v104, v98, s67
	v_mov_b32_e32 v99, v103
	v_mul_lo_u32 v98, v102, s67
	v_lshl_add_u64 v[102:103], v[104:105], 2, v[2:3]
	v_lshl_add_u64 v[106:107], v[98:99], 2, v[2:3]
	v_mov_b32_e32 v99, v105
	global_load_dword v98, v[102:103], off
	global_load_dword v69, v[106:107], off
	v_mad_u64_u32 v[104:105], s[70:71], v73, s64, v[4:5]
	v_mad_u64_u32 v[106:107], s[70:71], v71, s64, v[4:5]
	s_add_i32 s71, s37, 32
	s_add_i32 s70, s36, 32
	v_or_b32_e32 v75, s71, v6
	v_or_b32_e32 v73, s70, v5
	v_mov_b32_e32 v102, v104
	v_mov_b32_e32 v103, v99
	s_add_i32 s37, s37, 48
	s_add_i32 s36, s36, 48
	s_cmp_lg_u32 s35, 0
	v_mov_b32_e32 v105, v99
	v_add_u32_e32 v104, s2, v75
	v_mov_b32_e32 v109, v103
	v_add_u32_e32 v108, s3, v73
	v_mov_b32_e32 v111, v105
	v_mul_lo_u32 v110, v104, s67
	v_mov_b32_e32 v105, v109
	v_mul_lo_u32 v104, v108, s67
	v_lshl_add_u64 v[108:109], v[110:111], 2, v[2:3]
	v_lshl_add_u64 v[112:113], v[104:105], 2, v[2:3]
	v_mov_b32_e32 v105, v111
	global_load_dword v104, v[108:109], off
	global_load_dword v71, v[112:113], off
	v_mad_u64_u32 v[110:111], s[70:71], v75, s64, v[4:5]
	v_or_b32_e32 v77, s37, v6
	v_mad_u64_u32 v[112:113], s[70:71], v73, s64, v[4:5]
	v_or_b32_e32 v75, s36, v5
	v_mov_b32_e32 v108, v110
	v_mov_b32_e32 v109, v105
	v_mov_b32_e32 v111, v105
	v_add_u32_e32 v110, s2, v77
	v_mov_b32_e32 v115, v109
	v_add_u32_e32 v114, s3, v75
	v_mov_b32_e32 v117, v111
	v_mul_lo_u32 v116, v110, s67
	v_mov_b32_e32 v111, v115
	v_mul_lo_u32 v110, v114, s67
	v_lshl_add_u64 v[114:115], v[116:117], 2, v[2:3]
	v_lshl_add_u64 v[118:119], v[110:111], 2, v[2:3]
	v_mov_b32_e32 v111, v117
	global_load_dword v110, v[114:115], off
	global_load_dword v73, v[118:119], off
	v_mad_u64_u32 v[116:117], s[36:37], v77, s64, v[4:5]
	v_mad_u64_u32 v[118:119], s[36:37], v75, s64, v[4:5]
	s_waitcnt vmcnt(15)
	ds_write_b32 v76, v72
	s_waitcnt vmcnt(14)
	ds_write_b32 v66, v70
	s_waitcnt vmcnt(13)
	ds_write_b32 v78, v74
	s_waitcnt vmcnt(12)
	ds_write_b32 v82, v65
	s_waitcnt vmcnt(11)
	ds_write_b32 v84, v80
	s_waitcnt vmcnt(10)
	ds_write_b32 v88, v64
	s_waitcnt vmcnt(9)
	ds_write_b32 v92, v86
	s_waitcnt vmcnt(8)
	ds_write_b32 v94, v68
	s_waitcnt vmcnt(7)
	ds_write_b32 v96, v100
	s_waitcnt vmcnt(6)
	ds_write_b32 v90, v67
	s_waitcnt vmcnt(5)
	ds_write_b32 v102, v98
	s_waitcnt vmcnt(4)
	ds_write_b32 v106, v69
	s_waitcnt vmcnt(3)
	ds_write_b32 v108, v104
	s_waitcnt vmcnt(2)
	ds_write_b32 v112, v71
	s_waitcnt vmcnt(1)
	ds_write_b32 v116, v110
	s_waitcnt vmcnt(0)
	ds_write_b32 v118, v73
	v_mov_b32_e32 v0, v110
	v_mov_b32_e32 v1, v111
	v_mov_b32_e32 v8, v116
	v_mov_b32_e32 v9, v117
	v_mov_b32_e32 v10, v118
	v_mov_b32_e32 v11, v119
	v_mov_b32_e32 v12, v75
	v_mov_b32_e32 v13, v77
	v_mov_b32_e32 v18, v73
	v_lshlrev_b32_sdwa v0, v14, v7 dst_sel:DWORD dst_unused:UNUSED_PAD src0_sel:DWORD src1_sel:BYTE_0
	v_and_b32_e32 v0, 0x7e, v0
	v_lshrrev_b32_sdwa v10, v15, v7 dst_sel:DWORD dst_unused:UNUSED_PAD src0_sel:DWORD src1_sel:BYTE_0
	v_mul_u32_u24_e32 v2, 0x84, v0
	v_lshlrev_b32_e32 v3, 2, v10
	v_add3_u32 v12, s47, v2, v3
	s_waitcnt lgkmcnt(0)
	s_barrier
	ds_read2_b32 v[2:3], v12 offset0:33 offset1:37
	ds_read2_b32 v[4:5], v12 offset1:4
	v_or_b32_e32 v0, s2, v0
	v_lshlrev_b32_e32 v0, 1, v0
	v_lshl_add_u64 v[6:7], s[18:19], 0, v[0:1]
	v_lshlrev_b32_e32 v0, 11, v10
	s_waitcnt lgkmcnt(0)
	v_cvt_pk_bf16_f32 v2, v4, v2
	v_lshl_add_u64 v[10:11], v[6:7], 0, v[0:1]
	ds_read2_b32 v[8:9], v12 offset0:8 offset1:12
	global_store_dword v[10:11], v2, off
	v_cvt_pk_bf16_f32 v10, v5, v3
	ds_read2_b32 v[2:3], v12 offset0:41 offset1:45
	v_or_b32_e32 v4, 0x2000, v0
	v_mov_b32_e32 v5, v1
	v_lshl_add_u64 v[4:5], v[6:7], 0, v[4:5]
	global_store_dword v[4:5], v10, off
	v_or_b32_e32 v4, 0x4000, v0
	v_mov_b32_e32 v5, v1
	s_waitcnt lgkmcnt(0)
	v_cvt_pk_bf16_f32 v2, v8, v2
	v_lshl_add_u64 v[4:5], v[6:7], 0, v[4:5]
	global_store_dword v[4:5], v2, off
	v_cvt_pk_bf16_f32 v10, v9, v3
	ds_read2_b32 v[2:3], v12 offset0:16 offset1:20
	ds_read2_b32 v[4:5], v12 offset0:49 offset1:53
	v_or_b32_e32 v8, 0x6000, v0
	v_mov_b32_e32 v9, v1
	v_lshl_add_u64 v[8:9], v[6:7], 0, v[8:9]
	global_store_dword v[8:9], v10, off
	v_or_b32_e32 v8, 0x8000, v0
	v_mov_b32_e32 v9, v1
	s_waitcnt lgkmcnt(0)
	v_cvt_pk_bf16_f32 v2, v2, v4
	v_lshl_add_u64 v[8:9], v[6:7], 0, v[8:9]
	global_store_dword v[8:9], v2, off
	v_cvt_pk_bf16_f32 v10, v3, v5
	ds_read2_b32 v[2:3], v12 offset0:57 offset1:61
	ds_read2_b32 v[4:5], v12 offset0:24 offset1:28
	v_or_b32_e32 v8, 0xa000, v0
	v_mov_b32_e32 v9, v1
	v_lshl_add_u64 v[8:9], v[6:7], 0, v[8:9]
	global_store_dword v[8:9], v10, off
	v_or_b32_e32 v8, 0xc000, v0
	v_mov_b32_e32 v9, v1
	s_waitcnt lgkmcnt(0)
	v_cvt_pk_bf16_f32 v2, v4, v2
	v_lshl_add_u64 v[8:9], v[6:7], 0, v[8:9]
	v_or_b32_e32 v0, 0xe000, v0
	global_store_dword v[8:9], v2, off
	v_cvt_pk_bf16_f32 v4, v5, v3
	v_lshl_add_u64 v[2:3], v[6:7], 0, v[0:1]
	global_store_dword v[2:3], v4, off
	s_barrier
	s_branch .LBB0_798

.LBB0_1399:
.LBB0_1400:
	s_and_b32 s12, s18, 1
	s_mul_i32 s19, s12, 0x6000
	s_lshl_b32 s17, s12, 14
	s_add_i32 s17, s17, 0xc000
	s_add_i32 s16, s18, 1
	s_waitcnt vmcnt(0)
	s_barrier
	s_add_i32 s13, s18, 2
	s_cmp_ge_u32 s13, s10
	s_cbranch_scc1 .Lattn_slow_1
	s_xor_b32 s13, s12, 1
	s_mul_i32 s14, s13, 0x6000
	s_add_i32 s14, s14, s11
	s_lshl_b32 s15, s13, 14
	s_add_i32 s15, s15, s11
	s_add_i32 s15, s15, 0xc000
	s_movk_i32 s12, 0x100
	s_mov_b32 s13, 0
	v_add_u32_e32 v10, s19, v152
	v_xor_b32_e32 v154, 32, v10
	ds_read_b128 v[6:9], v10
	ds_read_b128 v[222:225], v154
	ds_read_b128 v[226:229], v10 offset:64
	ds_read_b128 v[230:233], v154 offset:64
	ds_read_b128 v[234:237], v10 offset:128
	ds_read_b128 v[242:245], v154 offset:128
	ds_read_b128 v[246:249], v10 offset:6144
	ds_read_b128 v[250:253], v154 offset:6144
	s_waitcnt lgkmcnt(7)
	v_mfma_f32_32x32x16_bf16 v[80:95], v[6:9], v[120:123], v[174:189]
	ds_read_b128 v[6:9], v10 offset:6208
	s_add_i32 m0, s14, 0x0
	v_lshl_add_u64 v[136:137], v[136:137], 0, v[146:147]
	global_load_lds_dwordx4 v[136:137], off
	s_waitcnt lgkmcnt(7)
	v_mfma_f32_32x32x16_bf16 v[80:95], v[222:225], v[112:115], v[80:95]
	ds_read_b128 v[222:225], v154 offset:6208
	s_waitcnt lgkmcnt(7)
	v_mfma_f32_32x32x16_bf16 v[80:95], v[226:229], v[116:119], v[80:95]
	ds_read_b128 v[226:229], v10 offset:6272
	s_add_i32 m0, s14, 0x2000
	v_lshl_add_u64 v[138:139], v[138:139], 0, v[148:149]
	global_load_lds_dwordx4 v[138:139], off
	s_waitcnt lgkmcnt(7)
	v_mfma_f32_32x32x16_bf16 v[80:95], v[230:233], v[124:127], v[80:95]
	ds_read_b128 v[230:233], v154 offset:6272
	s_waitcnt lgkmcnt(7)
	v_mfma_f32_32x32x16_bf16 v[80:95], v[234:237], v[128:131], v[80:95]
	ds_read_b128 v[234:237], v10 offset:12288
	s_add_i32 m0, s14, 0x4000
	v_lshl_add_u64 v[140:141], v[140:141], 0, v[150:151]
	global_load_lds_dwordx4 v[140:141], off
	s_waitcnt lgkmcnt(7)
	v_mfma_f32_32x32x16_bf16 v[80:95], v[242:245], v[132:135], v[80:95]
	ds_read_b128 v[242:245], v154 offset:12288
	s_waitcnt lgkmcnt(7)
	v_mfma_f32_32x32x16_bf16 v[64:79], v[246:249], v[120:123], v[174:189]
	ds_read_b128 v[246:249], v10 offset:12352
	s_add_i32 m0, s15, 0x0
	v_lshl_add_u64 v[142:143], v[142:143], 0, s[12:13]
	global_load_lds_dwordx4 v[142:143], off
	s_waitcnt lgkmcnt(7)
	v_mfma_f32_32x32x16_bf16 v[64:79], v[250:253], v[112:115], v[64:79]
	ds_read_b128 v[250:253], v154 offset:12352
	s_waitcnt lgkmcnt(7)
	v_mfma_f32_32x32x16_bf16 v[64:79], v[6:9], v[116:119], v[64:79]
	ds_read_b128 v[6:9], v10 offset:12416
	s_add_i32 m0, s15, 0x2000
	v_lshl_add_u64 v[144:145], v[144:145], 0, s[12:13]
	global_load_lds_dwordx4 v[144:145], off
	s_waitcnt lgkmcnt(7)
	v_mfma_f32_32x32x16_bf16 v[64:79], v[222:225], v[124:127], v[64:79]
	ds_read_b128 v[222:225], v154 offset:12416
	s_waitcnt lgkmcnt(7)
	v_mfma_f32_32x32x16_bf16 v[64:79], v[226:229], v[128:131], v[64:79]
	ds_read_b128 v[226:229], v10 offset:18432
	v_max3_f32 v3, v80, v81, v82
	v_max3_f32 v3, v3, v83, v84
	v_max3_f32 v3, v3, v85, v86
	v_max3_f32 v3, v3, v87, v88
	v_max3_f32 v3, v3, v89, v90
	s_waitcnt lgkmcnt(7)
	v_mfma_f32_32x32x16_bf16 v[64:79], v[230:233], v[132:135], v[64:79]
	ds_read_b128 v[230:233], v154 offset:18432
	v_max3_f32 v3, v3, v91, v92
	v_max3_f32 v3, v3, v93, v94
	v_max_f32_e32 v3, v3, v95
	v_exp_f32_e32 v80, v80
	v_exp_f32_e32 v81, v81
	s_waitcnt lgkmcnt(7)
	v_mfma_f32_32x32x16_bf16 v[96:111], v[234:237], v[120:123], v[174:189]
	ds_read_b128 v[234:237], v10 offset:18496
	v_exp_f32_e32 v82, v82
	v_exp_f32_e32 v83, v83
	v_mov_b64_e32 v[12:13], v[80:81]
	v_mov_b64_e32 v[14:15], v[82:83]
	v_exp_f32_e32 v84, v84
	s_waitcnt lgkmcnt(7)
	v_mfma_f32_32x32x16_bf16 v[96:111], v[242:245], v[112:115], v[96:111]
	ds_read_b128 v[242:245], v154 offset:18496
	v_exp_f32_e32 v85, v85
	v_exp_f32_e32 v86, v86
	v_exp_f32_e32 v87, v87
	v_pk_add_f32 v[12:13], v[12:13], v[84:85]
	v_pk_add_f32 v[14:15], v[14:15], v[86:87]
	s_waitcnt lgkmcnt(7)
	v_mfma_f32_32x32x16_bf16 v[96:111], v[246:249], v[116:119], v[96:111]
	ds_read_b128 v[246:249], v10 offset:18560
	v_cvt_pk_bf16_f32 v80, v80, v81
	v_cvt_pk_bf16_f32 v81, v82, v83
	v_cvt_pk_bf16_f32 v82, v84, v85
	v_cvt_pk_bf16_f32 v83, v86, v87
	v_exp_f32_e32 v88, v88
	s_waitcnt lgkmcnt(7)
	v_mfma_f32_32x32x16_bf16 v[96:111], v[250:253], v[124:127], v[96:111]
	ds_read_b128 v[250:253], v154 offset:18560
	v_exp_f32_e32 v89, v89
	v_exp_f32_e32 v90, v90
	v_exp_f32_e32 v91, v91
	v_pk_add_f32 v[12:13], v[12:13], v[88:89]
	v_pk_add_f32 v[14:15], v[14:15], v[90:91]
	s_waitcnt lgkmcnt(7)
	v_mfma_f32_32x32x16_bf16 v[96:111], v[6:9], v[128:131], v[96:111]
	v_add_u32_e32 v155, s17, v153
	v_exp_f32_e32 v92, v92
	v_exp_f32_e32 v93, v93
	v_exp_f32_e32 v94, v94
	v_exp_f32_e32 v95, v95
	v_pk_add_f32 v[12:13], v[12:13], v[92:93]
	s_waitcnt lgkmcnt(6)
	v_mfma_f32_32x32x16_bf16 v[96:111], v[222:225], v[132:135], v[96:111]
	ds_read_b128 v[222:225], v155
	v_pk_add_f32 v[14:15], v[14:15], v[94:95]
	v_cvt_pk_bf16_f32 v84, v88, v89
	v_cvt_pk_bf16_f32 v85, v90, v91
	v_cvt_pk_bf16_f32 v86, v92, v93
	v_cvt_pk_bf16_f32 v87, v94, v95
	s_waitcnt lgkmcnt(6)
	v_mfma_f32_32x32x16_bf16 v[48:63], v[226:229], v[120:123], v[174:189]
	ds_read_b128 v[226:229], v155 offset:8192
	v_max3_f32 v4, v64, v65, v66
	v_max3_f32 v4, v4, v67, v68
	v_max3_f32 v4, v4, v69, v70
	v_max3_f32 v4, v4, v71, v72
	v_max3_f32 v4, v4, v73, v74
	s_waitcnt lgkmcnt(6)
	v_mfma_f32_32x32x16_bf16 v[48:63], v[230:233], v[112:115], v[48:63]
	v_xor_b32_e32 v238, 32, v155
	ds_read_b128 v[230:233], v238
	v_max3_f32 v4, v4, v75, v76
	v_max3_f32 v4, v4, v77, v78
	v_max_f32_e32 v4, v4, v79
	v_exp_f32_e32 v64, v64
	v_exp_f32_e32 v65, v65
	s_waitcnt lgkmcnt(6)
	v_mfma_f32_32x32x16_bf16 v[48:63], v[234:237], v[116:119], v[48:63]
	ds_read_b128 v[234:237], v238 offset:8192
	v_exp_f32_e32 v66, v66
	v_exp_f32_e32 v67, v67
	v_pk_add_f32 v[12:13], v[12:13], v[64:65]
	v_pk_add_f32 v[14:15], v[14:15], v[66:67]
	v_exp_f32_e32 v68, v68
	s_waitcnt lgkmcnt(6)
	v_mfma_f32_32x32x16_bf16 v[48:63], v[242:245], v[124:127], v[48:63]
	v_xor_b32_e32 v239, 64, v155
	ds_read_b128 v[242:245], v239
	v_exp_f32_e32 v69, v69
	v_exp_f32_e32 v70, v70
	v_exp_f32_e32 v71, v71
	v_pk_add_f32 v[12:13], v[12:13], v[68:69]
	v_pk_add_f32 v[14:15], v[14:15], v[70:71]
	s_waitcnt lgkmcnt(6)
	v_mfma_f32_32x32x16_bf16 v[48:63], v[246:249], v[128:131], v[48:63]
	ds_read_b128 v[246:249], v239 offset:8192
	v_cvt_pk_bf16_f32 v64, v64, v65
	v_cvt_pk_bf16_f32 v65, v66, v67
	v_cvt_pk_bf16_f32 v66, v68, v69
	v_cvt_pk_bf16_f32 v67, v70, v71
	v_exp_f32_e32 v72, v72
	s_waitcnt lgkmcnt(6)
	v_mfma_f32_32x32x16_bf16 v[48:63], v[250:253], v[132:135], v[48:63]
	v_xor_b32_e32 v238, 96, v155
	ds_read_b128 v[250:253], v238
	v_exp_f32_e32 v73, v73
	v_exp_f32_e32 v74, v74
	v_exp_f32_e32 v75, v75
	v_pk_add_f32 v[12:13], v[12:13], v[72:73]
	v_pk_add_f32 v[14:15], v[14:15], v[74:75]
	s_waitcnt lgkmcnt(6)
	v_mfma_f32_32x32x16_bf16 v[32:47], v[222:225], v[80:83], v[32:47]
	v_exp_f32_e32 v76, v76
	v_exp_f32_e32 v77, v77
	v_exp_f32_e32 v78, v78
	s_waitcnt lgkmcnt(5)
	v_mfma_f32_32x32x16_bf16 v[16:31], v[226:229], v[80:83], v[16:31]
	ds_read_b128 v[222:225], v238 offset:8192
	v_xor_b32_e32 v239, 128, v155
	ds_read_b128 v[226:229], v239
	v_exp_f32_e32 v79, v79
	v_pk_add_f32 v[12:13], v[12:13], v[76:77]
	v_pk_add_f32 v[14:15], v[14:15], v[78:79]
	s_waitcnt lgkmcnt(6)
	v_mfma_f32_32x32x16_bf16 v[32:47], v[230:233], v[84:87], v[32:47]
	v_cvt_pk_bf16_f32 v68, v72, v73
	v_cvt_pk_bf16_f32 v69, v74, v75
	v_cvt_pk_bf16_f32 v70, v76, v77
	s_waitcnt lgkmcnt(5)
	v_mfma_f32_32x32x16_bf16 v[16:31], v[234:237], v[84:87], v[16:31]
	ds_read_b128 v[230:233], v239 offset:8192
	v_xor_b32_e32 v238, 160, v155
	ds_read_b128 v[234:237], v238
	v_cvt_pk_bf16_f32 v71, v78, v79
	s_waitcnt lgkmcnt(6)
	v_mfma_f32_32x32x16_bf16 v[32:47], v[242:245], v[64:67], v[32:47]
	v_max3_f32 v5, v96, v97, v98
	v_max3_f32 v5, v5, v99, v100
	v_max3_f32 v5, v5, v101, v102
	v_max3_f32 v5, v5, v103, v104
	v_max3_f32 v5, v5, v105, v106
	v_max3_f32 v5, v5, v107, v108
	v_max3_f32 v5, v5, v109, v110
	v_max_f32_e32 v5, v5, v111
	v_exp_f32_e32 v96, v96
	v_exp_f32_e32 v97, v97
	s_waitcnt lgkmcnt(5)
	v_mfma_f32_32x32x16_bf16 v[16:31], v[246:249], v[64:67], v[16:31]
	ds_read_b128 v[242:245], v238 offset:8192
	v_xor_b32_e32 v239, 192, v155
	ds_read_b128 v[246:249], v239
	v_exp_f32_e32 v98, v98
	v_exp_f32_e32 v99, v99
	v_pk_add_f32 v[12:13], v[12:13], v[96:97]
	v_pk_add_f32 v[14:15], v[14:15], v[98:99]
	v_exp_f32_e32 v100, v100
	v_exp_f32_e32 v101, v101
	v_exp_f32_e32 v102, v102
	v_exp_f32_e32 v103, v103
	v_pk_add_f32 v[12:13], v[12:13], v[100:101]
	v_pk_add_f32 v[14:15], v[14:15], v[102:103]
	s_waitcnt lgkmcnt(6)
	v_mfma_f32_32x32x16_bf16 v[32:47], v[250:253], v[68:71], v[32:47]
	v_cvt_pk_bf16_f32 v96, v96, v97
	v_cvt_pk_bf16_f32 v97, v98, v99
	v_cvt_pk_bf16_f32 v98, v100, v101
	v_cvt_pk_bf16_f32 v99, v102, v103
	v_exp_f32_e32 v104, v104
	v_exp_f32_e32 v105, v105
	v_exp_f32_e32 v106, v106
	v_exp_f32_e32 v107, v107
	v_pk_add_f32 v[12:13], v[12:13], v[104:105]
	v_pk_add_f32 v[14:15], v[14:15], v[106:107]
	s_waitcnt lgkmcnt(5)
	v_mfma_f32_32x32x16_bf16 v[16:31], v[222:225], v[68:71], v[16:31]
	ds_read_b128 v[250:253], v239 offset:8192
	v_xor_b32_e32 v238, 224, v155
	ds_read_b128 v[222:225], v238
	v_exp_f32_e32 v108, v108
	v_exp_f32_e32 v109, v109
	v_exp_f32_e32 v110, v110
	v_exp_f32_e32 v111, v111
	v_pk_add_f32 v[12:13], v[12:13], v[108:109]
	v_pk_add_f32 v[14:15], v[14:15], v[110:111]
	v_cvt_pk_bf16_f32 v100, v104, v105
	v_cvt_pk_bf16_f32 v101, v106, v107
	v_cvt_pk_bf16_f32 v102, v108, v109
	v_cvt_pk_bf16_f32 v103, v110, v111
	s_waitcnt lgkmcnt(6)
	v_mfma_f32_32x32x16_bf16 v[32:47], v[226:229], v[96:99], v[32:47]
	v_max3_f32 v2, v48, v49, v50
	v_max3_f32 v2, v2, v51, v52
	v_max3_f32 v2, v2, v53, v54
	v_max3_f32 v2, v2, v55, v56
	v_max3_f32 v2, v2, v57, v58
	v_max3_f32 v2, v2, v59, v60
	v_max3_f32 v2, v2, v61, v62
	v_max_f32_e32 v2, v2, v63
	v_exp_f32_e32 v48, v48
	v_exp_f32_e32 v49, v49
	s_waitcnt lgkmcnt(5)
	v_mfma_f32_32x32x16_bf16 v[16:31], v[230:233], v[96:99], v[16:31]
	ds_read_b128 v[226:229], v238 offset:8192
	v_exp_f32_e32 v50, v50
	v_exp_f32_e32 v51, v51
	v_pk_add_f32 v[12:13], v[12:13], v[48:49]
	v_pk_add_f32 v[14:15], v[14:15], v[50:51]
	v_exp_f32_e32 v52, v52
	v_exp_f32_e32 v53, v53
	v_exp_f32_e32 v54, v54
	v_exp_f32_e32 v55, v55
	v_pk_add_f32 v[12:13], v[12:13], v[52:53]
	v_pk_add_f32 v[14:15], v[14:15], v[54:55]
	s_waitcnt lgkmcnt(5)
	v_mfma_f32_32x32x16_bf16 v[32:47], v[234:237], v[100:103], v[32:47]
	v_cvt_pk_bf16_f32 v48, v48, v49
	v_cvt_pk_bf16_f32 v49, v50, v51
	v_cvt_pk_bf16_f32 v50, v52, v53
	v_cvt_pk_bf16_f32 v51, v54, v55
	v_exp_f32_e32 v56, v56
	v_exp_f32_e32 v57, v57
	v_exp_f32_e32 v58, v58
	v_exp_f32_e32 v59, v59
	v_pk_add_f32 v[12:13], v[12:13], v[56:57]
	v_pk_add_f32 v[14:15], v[14:15], v[58:59]
	s_waitcnt lgkmcnt(4)
	v_mfma_f32_32x32x16_bf16 v[16:31], v[242:245], v[100:103], v[16:31]
	v_exp_f32_e32 v60, v60
	v_exp_f32_e32 v61, v61
	v_exp_f32_e32 v62, v62
	v_exp_f32_e32 v63, v63
	v_pk_add_f32 v[12:13], v[12:13], v[60:61]
	v_pk_add_f32 v[14:15], v[14:15], v[62:63]
	v_cvt_pk_bf16_f32 v52, v56, v57
	v_cvt_pk_bf16_f32 v53, v58, v59
	v_cvt_pk_bf16_f32 v54, v60, v61
	v_cvt_pk_bf16_f32 v55, v62, v63
	s_waitcnt lgkmcnt(3)
	v_mfma_f32_32x32x16_bf16 v[32:47], v[246:249], v[48:51], v[32:47]
	s_waitcnt lgkmcnt(2)
	v_mfma_f32_32x32x16_bf16 v[16:31], v[250:253], v[48:51], v[16:31]
	s_waitcnt lgkmcnt(1)
	v_mfma_f32_32x32x16_bf16 v[32:47], v[222:225], v[52:55], v[32:47]
	s_waitcnt lgkmcnt(0)
	v_mfma_f32_32x32x16_bf16 v[16:31], v[226:229], v[52:55], v[16:31]
	v_add_f32_e32 v12, v12, v13
	v_add_f32_e32 v14, v14, v15
	v_max3_f32 v2, v2, v3, v4
	v_add_f32_e32 v12, v12, v14
	v_max_f32_e32 v2, v2, v5
	v_add_f32_e32 v159, v159, v12
	v_mov_b32_e32 v3, v2
	s_nop 1
	v_permlane32_swap_b32_e32 v2, v3
	v_max_f32_e32 v2, v2, v3
	v_cmp_lt_f32_e32 vcc, 0, v2
	s_cbranch_vccz .Lattn_fnr_1
	s_nop 7
	s_nop 3
	v_max_f32_e32 v2, 0, v2
	v_exp_f32_e64 v4, -v2
	v_add_f32_e32 v0, v0, v2
	s_nop 0
	v_mul_f32_e32 v159, v159, v4
	v_mul_f32_e32 v16, v16, v4
	v_mul_f32_e32 v17, v17, v4
	v_mul_f32_e32 v18, v18, v4
	v_mul_f32_e32 v19, v19, v4
	v_mul_f32_e32 v20, v20, v4
	v_mul_f32_e32 v21, v21, v4
	v_mul_f32_e32 v22, v22, v4
	v_mul_f32_e32 v23, v23, v4
	v_mul_f32_e32 v24, v24, v4
	v_mul_f32_e32 v25, v25, v4
	v_mul_f32_e32 v26, v26, v4
	v_mul_f32_e32 v27, v27, v4
	v_mul_f32_e32 v28, v28, v4
	v_mul_f32_e32 v29, v29, v4
	v_mul_f32_e32 v30, v30, v4
	v_mul_f32_e32 v31, v31, v4
	v_mul_f32_e32 v32, v32, v4
	v_mul_f32_e32 v33, v33, v4
	v_mul_f32_e32 v34, v34, v4
	v_mul_f32_e32 v35, v35, v4
	v_mul_f32_e32 v36, v36, v4
	v_mul_f32_e32 v37, v37, v4
	v_mul_f32_e32 v38, v38, v4
	v_mul_f32_e32 v39, v39, v4
	v_mul_f32_e32 v40, v40, v4
	v_mul_f32_e32 v41, v41, v4
	v_mul_f32_e32 v42, v42, v4
	v_mul_f32_e32 v43, v43, v4
	v_mul_f32_e32 v44, v44, v4
	v_mul_f32_e32 v45, v45, v4
	v_mul_f32_e32 v46, v46, v4
	v_mul_f32_e32 v47, v47, v4
	v_xor_b32_e32 v174, 0x80000000, v0
	v_mov_b32_e32 v175, v174
	v_mov_b32_e32 v176, v174
	v_mov_b32_e32 v177, v174
	v_mov_b32_e32 v178, v174
	v_mov_b32_e32 v179, v174
	v_mov_b32_e32 v180, v174
	v_mov_b32_e32 v181, v174
	v_mov_b32_e32 v182, v174
	v_mov_b32_e32 v183, v174
	v_mov_b32_e32 v184, v174
	v_mov_b32_e32 v185, v174
	v_mov_b32_e32 v186, v174
	v_mov_b32_e32 v187, v174
	v_mov_b32_e32 v188, v174
	v_mov_b32_e32 v189, v174
